# EpiPG: bias vectors loaded once per tile into free regs, vmcnt waits re-placed at first consumers (restores next-row prefetch); plus F12 weight prefetch, G1 rot/plain epilogue rewrite, mix2 branch-fre
# speedup vs baseline: 1.0258x; 1.0258x over previous
; #define LAS __attribute__((address_space(3)))
; __device__ __forceinline__ unsigned cvt_pk_bf16(float lo, float hi) { unsigned r; asm volatile("v_cvt_pk_bf16_f32 %0, %1, %2" : "=v"(r) : "v"(lo), "v"(hi)); return r; }
; #define MFMA16(a, b, c) __builtin_amdgcn_mfma_f32_16x16x32_bf16((a), (b), (c), 0, 0, 0)
; __device__ void mix_sweep(const Params& P, LAS unsigned char* lds, int tok0, int pos0, int seqlen, int hd, int dir, bool state_only, bool final_pass,
;                           f32x4 (&Cacc)[9], float& m_state, float& aseg_sum, float lgam) {
;     ...
;             const float wi = vwi[irow], rt = vrow[irow];
; #pragma unroll
;             for (int nt = 0; nt < 9; ++nt) O[nt] = O[nt] * wi;
; #pragma unroll
;             for (int nt = 0; nt < 8; ++nt) { f32x4 a = (f32x4){0.f, 0.f, 0.f, 0.f}; bf16x8 kr[4];
; #pragma unroll
;                 for (int s = 0; s < 4; ++s) kr[s] = ROWFRAG(IMG_K, 16 * nt, s);
;                 __builtin_amdgcn_sched_barrier(0);
; #pragma unroll
;                 for (int s = 0; s < 4; ++s) a = MFMA16(kr[s], qf[s], a);
;                 const f32x4 ct = *(const LAS f32x4*)(vcol + 16 * nt + 4 * fg); float p[4];
; #pragma unroll
;                 for (int e = 0; e < 4; ++e) { const int j = 16 * nt + 4 * fg + e;
;                     const bool keep = dir ? (is_m ? (j >= irow) : (j > irow)) : (j <= irow);
;                     const float ex = __builtin_amdgcn_exp2f(rt + ct[e]); p[e] = keep ? a[e] * ex : 0.f; }
;                 u32x2 pv; pv.x = cvt_pk_bf16(p[0], p[1]); pv.y = cvt_pk_bf16(p[2], p[3]);
;                 { LAUNDER_X16 *(LAS u32x2*)(lds + IMG_Q + CWA(nt)) = pv; } __builtin_amdgcn_sched_barrier(0); }
.LBB0_107:
	s_setprio 0
	v_lshl_add_u32 v220, v188, 2, 0
	v_add_u32_e32 v124, 0x22400, v220
	v_add_u32_e32 v125, 0x22000, v220
	v_add_u32_e32 v132, 0, v174
	ds_read_b32 v158, v124
	ds_read_b32 v171, v125
	ds_read_b128 v[124:127], v132 offset:32768
	v_add_u32_e32 v133, 0, v175
	v_add_u32_e32 v134, 0, v176
	ds_read_b128 v[128:131], v133 offset:32768
	ds_read_b128 v[136:139], v134 offset:32768
	v_add_u32_e32 v135, 0, v177
	ds_read_b128 v[140:143], v135 offset:32768
	s_waitcnt lgkmcnt(3)
	v_mfma_f32_16x16x32_bf16 v[124:127], v[124:127], v[92:95], 0
	s_mov_b64 s[18:19], -1
	s_andn2_b64 vcc, exec, s[12:13]
	s_waitcnt lgkmcnt(2)
	v_mfma_f32_16x16x32_bf16 v[128:131], v[128:131], v[96:99], v[124:127]
	s_waitcnt lgkmcnt(1)
	v_mfma_f32_16x16x32_bf16 v[128:131], v[136:139], v[100:103], v[128:131]
	s_nop 1
	ds_read_b128 v[124:127], v190
	v_cndmask_b32_e64 v136, 0, 1, s[12:13]
	v_cmp_ne_u32_e64 s[48:49], 1, v136
	s_waitcnt lgkmcnt(1)
	v_mfma_f32_16x16x32_bf16 v[128:131], v[140:143], v[88:91], v[128:131]
	v_or_b32_e32 v141, 1, v189
	v_cmp_le_i32_e64 s[16:17], v189, v188
	v_cmp_le_i32_e64 s[18:19], v141, v188
	v_cmp_le_i32_e64 s[50:51], v201, v188
	v_cmp_le_i32_e64 s[54:55], v202, v188
	s_cbranch_vccnz .Lmk_done_0
	v_cndmask_b32_e64 v140, 1, 0, s[42:43]
	v_add_u32_e32 v140, v140, v188
	v_cmp_ge_i32_e64 s[16:17], v189, v140
	v_cmp_ge_i32_e64 s[18:19], v141, v140
	v_cmp_ge_i32_e64 s[50:51], v201, v140
	v_cmp_ge_i32_e64 s[54:55], v202, v140
.Lmk_done_0:
.LBB0_139:
	s_waitcnt lgkmcnt(0)
	v_add_f32_e32 v126, v171, v126
	v_add_f32_e32 v125, v171, v125
	v_add_f32_e32 v124, v171, v124
	v_exp_f32_e32 v126, v126
	v_exp_f32_e32 v125, v125
	v_exp_f32_e32 v124, v124
	v_add_f32_e32 v127, v171, v127
	v_exp_f32_e32 v127, v127
	v_mul_f32_e32 v126, v130, v126
	v_mul_f32_e32 v125, v129, v125
	v_mul_f32_e32 v124, v128, v124
	v_cndmask_b32_e64 v126, 0, v126, s[50:51]
	v_cndmask_b32_e64 v125, 0, v125, s[18:19]
	v_cndmask_b32_e64 v124, 0, v124, s[16:17]
	v_mul_f32_e32 v127, v131, v127
	v_cndmask_b32_e64 v127, 0, v127, s[54:55]
	v_cvt_pk_bf16_f32 v124, v124, v125
	v_cvt_pk_bf16_f32 v125, v126, v127
	v_mov_b32_e32 v126, v179
	s_nop 0
	v_add_u32_e32 v126, v191, v126
	ds_write_b64 v126, v[124:125]
	ds_read_b128 v[124:127], v132 offset:36864
	ds_read_b128 v[128:131], v133 offset:36864
	ds_read_b128 v[136:139], v134 offset:36864
	ds_read_b128 v[140:143], v135 offset:36864
	s_waitcnt lgkmcnt(3)
	v_mfma_f32_16x16x32_bf16 v[124:127], v[124:127], v[92:95], 0
	s_mov_b64 s[18:19], -1
	s_and_b64 vcc, exec, s[48:49]
	s_waitcnt lgkmcnt(2)
	v_mfma_f32_16x16x32_bf16 v[124:127], v[128:131], v[96:99], v[124:127]
	ds_read_b128 v[128:131], v190 offset:64
	s_waitcnt lgkmcnt(2)
	v_mfma_f32_16x16x32_bf16 v[124:127], v[136:139], v[100:103], v[124:127]
	s_waitcnt lgkmcnt(1)
	v_mfma_f32_16x16x32_bf16 v[124:127], v[140:143], v[88:91], v[124:127]
	v_cmp_le_i32_e64 s[16:17], v204, v188
	v_cmp_le_i32_e64 s[18:19], v205, v188
	v_cmp_le_i32_e64 s[50:51], v206, v188
	v_cmp_le_i32_e64 s[54:55], v207, v188
	s_cbranch_vccnz .Lmk_done_1
	v_cndmask_b32_e64 v140, 1, 0, s[42:43]
	v_add_u32_e32 v140, v140, v188
	v_cmp_ge_i32_e64 s[16:17], v204, v140
	v_cmp_ge_i32_e64 s[18:19], v205, v140
	v_cmp_ge_i32_e64 s[50:51], v206, v140
	v_cmp_ge_i32_e64 s[54:55], v207, v140
.Lmk_done_1:
.LBB0_171:
	s_waitcnt lgkmcnt(0)
	v_add_f32_e32 v129, v171, v129
	v_exp_f32_e32 v129, v129
	v_add_f32_e32 v130, v171, v130
	v_add_f32_e32 v128, v171, v128
	v_exp_f32_e32 v130, v130
	v_mul_f32_e32 v125, v125, v129
	v_exp_f32_e32 v128, v128
	v_add_f32_e32 v129, v171, v131
	v_exp_f32_e32 v129, v129
	v_mul_f32_e32 v126, v126, v130
	v_mul_f32_e32 v124, v124, v128
	v_cndmask_b32_e64 v126, 0, v126, s[50:51]
	v_cndmask_b32_e64 v125, 0, v125, s[18:19]
	v_cndmask_b32_e64 v124, 0, v124, s[16:17]
	v_mul_f32_e32 v127, v127, v129
	v_cndmask_b32_e64 v127, 0, v127, s[54:55]
	v_cvt_pk_bf16_f32 v124, v124, v125
	v_cvt_pk_bf16_f32 v125, v126, v127
	v_mov_b32_e32 v126, v179
	s_nop 0
	v_xad_u32 v126, v126, 32, v191
	ds_write_b64 v126, v[124:125]
	ds_read_b128 v[124:127], v132 offset:40960
	ds_read_b128 v[128:131], v133 offset:40960
	ds_read_b128 v[136:139], v134 offset:40960
	ds_read_b128 v[140:143], v135 offset:40960
	s_waitcnt lgkmcnt(3)
	v_mfma_f32_16x16x32_bf16 v[124:127], v[124:127], v[92:95], 0
	s_mov_b64 s[18:19], -1
	s_and_b64 vcc, exec, s[48:49]
	s_waitcnt lgkmcnt(2)
	v_mfma_f32_16x16x32_bf16 v[124:127], v[128:131], v[96:99], v[124:127]
	ds_read_b128 v[128:131], v190 offset:128
	s_waitcnt lgkmcnt(2)
	v_mfma_f32_16x16x32_bf16 v[124:127], v[136:139], v[100:103], v[124:127]
	s_waitcnt lgkmcnt(1)
	v_mfma_f32_16x16x32_bf16 v[124:127], v[140:143], v[88:91], v[124:127]
	v_cmp_le_i32_e64 s[16:17], v222, v188
	v_cmp_le_i32_e64 s[18:19], v223, v188
	v_cmp_le_i32_e64 s[50:51], v224, v188
	v_cmp_le_i32_e64 s[54:55], v225, v188
	s_cbranch_vccnz .Lmk_done_2
	v_cndmask_b32_e64 v140, 1, 0, s[42:43]
	v_add_u32_e32 v140, v140, v188
	v_cmp_ge_i32_e64 s[16:17], v222, v140
	v_cmp_ge_i32_e64 s[18:19], v223, v140
	v_cmp_ge_i32_e64 s[50:51], v224, v140
	v_cmp_ge_i32_e64 s[54:55], v225, v140
; #define LAS __attribute__((address_space(3)))
; __device__ __forceinline__ unsigned cvt_pk_bf16(float lo, float hi) { unsigned r; asm volatile("v_cvt_pk_bf16_f32 %0, %1, %2" : "=v"(r) : "v"(lo), "v"(hi)); return r; }
; #define MFMA16(a, b, c) __builtin_amdgcn_mfma_f32_16x16x32_bf16((a), (b), (c), 0, 0, 0)
; __device__ void mix_sweep(const Params& P, LAS unsigned char* lds, int tok0, int pos0, int seqlen, int hd, int dir, bool state_only, bool final_pass,
;                           f32x4 (&Cacc)[9], float& m_state, float& aseg_sum, float lgam) {
;     ...
;             for (int nt = 0; nt < 8; ++nt) { f32x4 a = (f32x4){0.f, 0.f, 0.f, 0.f}; bf16x8 kr[4];
; #pragma unroll
;                 for (int s = 0; s < 4; ++s) kr[s] = ROWFRAG(IMG_K, 16 * nt, s);
;                 __builtin_amdgcn_sched_barrier(0);
; #pragma unroll
;                 for (int s = 0; s < 4; ++s) a = MFMA16(kr[s], qf[s], a);
;                 const f32x4 ct = *(const LAS f32x4*)(vcol + 16 * nt + 4 * fg); float p[4];
; #pragma unroll
;                 for (int e = 0; e < 4; ++e) { const int j = 16 * nt + 4 * fg + e;
;                     const bool keep = dir ? (is_m ? (j >= irow) : (j > irow)) : (j <= irow);
;                     const float ex = __builtin_amdgcn_exp2f(rt + ct[e]); p[e] = keep ? a[e] * ex : 0.f; }
;                 u32x2 pv; pv.x = cvt_pk_bf16(p[0], p[1]); pv.y = cvt_pk_bf16(p[2], p[3]);
;                 { LAUNDER_X16 *(LAS u32x2*)(lds + IMG_Q + CWA(nt)) = pv; } __builtin_amdgcn_sched_barrier(0); }
.Lmk_done_2:
.LBB0_203:
	s_waitcnt lgkmcnt(0)
	v_add_f32_e32 v129, v171, v129
	v_exp_f32_e32 v129, v129
	v_add_f32_e32 v130, v171, v130
	v_add_f32_e32 v128, v171, v128
	v_exp_f32_e32 v130, v130
	v_mul_f32_e32 v125, v125, v129
	v_exp_f32_e32 v128, v128
	v_add_f32_e32 v129, v171, v131
	v_exp_f32_e32 v129, v129
	v_mul_f32_e32 v126, v126, v130
	v_mul_f32_e32 v124, v124, v128
	v_cndmask_b32_e64 v126, 0, v126, s[50:51]
	v_cndmask_b32_e64 v125, 0, v125, s[18:19]
	v_cndmask_b32_e64 v124, 0, v124, s[16:17]
	v_mul_f32_e32 v127, v127, v129
	v_cndmask_b32_e64 v127, 0, v127, s[54:55]
	v_cvt_pk_bf16_f32 v124, v124, v125
	v_cvt_pk_bf16_f32 v125, v126, v127
	v_mov_b32_e32 v126, v179
	s_nop 0
	v_xad_u32 v126, v126, 64, v191
	ds_write_b64 v126, v[124:125]
	ds_read_b128 v[124:127], v132 offset:45056
	ds_read_b128 v[128:131], v133 offset:45056
	ds_read_b128 v[136:139], v134 offset:45056
	ds_read_b128 v[140:143], v135 offset:45056
	s_waitcnt lgkmcnt(3)
	v_mfma_f32_16x16x32_bf16 v[124:127], v[124:127], v[92:95], 0
	s_mov_b64 s[18:19], -1
	s_and_b64 vcc, exec, s[48:49]
	s_waitcnt lgkmcnt(2)
	v_mfma_f32_16x16x32_bf16 v[124:127], v[128:131], v[96:99], v[124:127]
	ds_read_b128 v[128:131], v190 offset:192
	s_waitcnt lgkmcnt(2)
	v_mfma_f32_16x16x32_bf16 v[124:127], v[136:139], v[100:103], v[124:127]
	s_waitcnt lgkmcnt(1)
	v_mfma_f32_16x16x32_bf16 v[124:127], v[140:143], v[88:91], v[124:127]
	v_cmp_le_i32_e64 s[16:17], v226, v188
	v_cmp_le_i32_e64 s[18:19], v227, v188
	v_cmp_le_i32_e64 s[50:51], v228, v188
	v_cmp_le_i32_e64 s[54:55], v229, v188
	s_cbranch_vccnz .Lmk_done_3
	v_cndmask_b32_e64 v140, 1, 0, s[42:43]
	v_add_u32_e32 v140, v140, v188
	v_cmp_ge_i32_e64 s[16:17], v226, v140
	v_cmp_ge_i32_e64 s[18:19], v227, v140
	v_cmp_ge_i32_e64 s[50:51], v228, v140
	v_cmp_ge_i32_e64 s[54:55], v229, v140
.Lmk_done_3:
.LBB0_235:
	s_waitcnt lgkmcnt(0)
	v_add_f32_e32 v129, v171, v129
	v_exp_f32_e32 v129, v129
	v_add_f32_e32 v130, v171, v130
	v_add_f32_e32 v128, v171, v128
	v_exp_f32_e32 v130, v130
	v_mul_f32_e32 v125, v125, v129
	v_exp_f32_e32 v128, v128
	v_add_f32_e32 v129, v171, v131
	v_exp_f32_e32 v129, v129
	v_mul_f32_e32 v126, v126, v130
	v_mul_f32_e32 v124, v124, v128
	v_cndmask_b32_e64 v126, 0, v126, s[50:51]
	v_cndmask_b32_e64 v125, 0, v125, s[18:19]
	v_cndmask_b32_e64 v124, 0, v124, s[16:17]
	v_mul_f32_e32 v127, v127, v129
	v_cndmask_b32_e64 v127, 0, v127, s[54:55]
	v_cvt_pk_bf16_f32 v124, v124, v125
	v_cvt_pk_bf16_f32 v125, v126, v127
	v_mov_b32_e32 v126, v179
	s_nop 0
	v_xad_u32 v126, v126, s33, v191
	ds_write_b64 v126, v[124:125]
	ds_read_b128 v[124:127], v132 offset:49152
	ds_read_b128 v[128:131], v133 offset:49152
	ds_read_b128 v[136:139], v134 offset:49152
	ds_read_b128 v[140:143], v135 offset:49152
	s_waitcnt lgkmcnt(3)
	v_mfma_f32_16x16x32_bf16 v[124:127], v[124:127], v[92:95], 0
	s_mov_b64 s[18:19], -1
	s_and_b64 vcc, exec, s[48:49]
	s_waitcnt lgkmcnt(2)
	v_mfma_f32_16x16x32_bf16 v[124:127], v[128:131], v[96:99], v[124:127]
	ds_read_b128 v[128:131], v190 offset:256
	s_waitcnt lgkmcnt(2)
	v_mfma_f32_16x16x32_bf16 v[124:127], v[136:139], v[100:103], v[124:127]
	s_waitcnt lgkmcnt(1)
	v_mfma_f32_16x16x32_bf16 v[124:127], v[140:143], v[88:91], v[124:127]
	v_cmp_le_i32_e64 s[16:17], v230, v188
	v_cmp_le_i32_e64 s[18:19], v231, v188
	v_cmp_le_i32_e64 s[50:51], v232, v188
	v_cmp_le_i32_e64 s[54:55], v233, v188
	s_cbranch_vccnz .Lmk_done_4
	v_cndmask_b32_e64 v140, 1, 0, s[42:43]
	v_add_u32_e32 v140, v140, v188
	v_cmp_ge_i32_e64 s[16:17], v230, v140
	v_cmp_ge_i32_e64 s[18:19], v231, v140
	v_cmp_ge_i32_e64 s[50:51], v232, v140
	v_cmp_ge_i32_e64 s[54:55], v233, v140
.Lmk_done_4:
.LBB0_267:
	s_waitcnt lgkmcnt(0)
	v_add_f32_e32 v129, v171, v129
	v_exp_f32_e32 v129, v129
	v_add_f32_e32 v130, v171, v130
	v_add_f32_e32 v128, v171, v128
	v_exp_f32_e32 v130, v130
	v_mul_f32_e32 v125, v125, v129
	v_exp_f32_e32 v128, v128
	v_add_f32_e32 v129, v171, v131
	v_exp_f32_e32 v129, v129
	v_mul_f32_e32 v126, v126, v130
	v_mul_f32_e32 v124, v124, v128
	v_cndmask_b32_e64 v126, 0, v126, s[50:51]
	v_cndmask_b32_e64 v125, 0, v125, s[18:19]
	v_cndmask_b32_e64 v124, 0, v124, s[16:17]
	v_mul_f32_e32 v127, v127, v129
	v_cndmask_b32_e64 v127, 0, v127, s[54:55]
	v_cvt_pk_bf16_f32 v124, v124, v125
	v_cvt_pk_bf16_f32 v125, v126, v127
	v_mov_b32_e32 v126, v179
	s_nop 0
	v_xad_u32 v126, v126, s25, v191
	ds_write_b64 v126, v[124:125]
	ds_read_b128 v[124:127], v132 offset:53248
	ds_read_b128 v[128:131], v133 offset:53248
	ds_read_b128 v[136:139], v134 offset:53248
	ds_read_b128 v[140:143], v135 offset:53248
	s_waitcnt lgkmcnt(3)
	v_mfma_f32_16x16x32_bf16 v[124:127], v[124:127], v[92:95], 0
	s_mov_b64 s[18:19], -1
	s_and_b64 vcc, exec, s[48:49]
	s_waitcnt lgkmcnt(2)
	v_mfma_f32_16x16x32_bf16 v[124:127], v[128:131], v[96:99], v[124:127]
	ds_read_b128 v[128:131], v190 offset:320
	s_waitcnt lgkmcnt(2)
	v_mfma_f32_16x16x32_bf16 v[124:127], v[136:139], v[100:103], v[124:127]
	s_waitcnt lgkmcnt(1)
	v_mfma_f32_16x16x32_bf16 v[124:127], v[140:143], v[88:91], v[124:127]
	v_cmp_le_i32_e64 s[16:17], v234, v188
	v_cmp_le_i32_e64 s[18:19], v235, v188
	v_cmp_le_i32_e64 s[50:51], v236, v188
	v_cmp_le_i32_e64 s[54:55], v237, v188
	s_cbranch_vccnz .Lmk_done_5
	v_cndmask_b32_e64 v140, 1, 0, s[42:43]
	v_add_u32_e32 v140, v140, v188
	v_cmp_ge_i32_e64 s[16:17], v234, v140
	v_cmp_ge_i32_e64 s[18:19], v235, v140
	v_cmp_ge_i32_e64 s[50:51], v236, v140
	v_cmp_ge_i32_e64 s[54:55], v237, v140
; #define LAS __attribute__((address_space(3)))
; __device__ __forceinline__ unsigned cvt_pk_bf16(float lo, float hi) { unsigned r; asm volatile("v_cvt_pk_bf16_f32 %0, %1, %2" : "=v"(r) : "v"(lo), "v"(hi)); return r; }
; #define MFMA16(a, b, c) __builtin_amdgcn_mfma_f32_16x16x32_bf16((a), (b), (c), 0, 0, 0)
; __device__ void mix_sweep(const Params& P, LAS unsigned char* lds, int tok0, int pos0, int seqlen, int hd, int dir, bool state_only, bool final_pass,
;                           f32x4 (&Cacc)[9], float& m_state, float& aseg_sum, float lgam) {
;     ...
;             for (int nt = 0; nt < 9; ++nt) O[nt] = O[nt] * wi;
; #pragma unroll
;             for (int nt = 0; nt < 8; ++nt) { f32x4 a = (f32x4){0.f, 0.f, 0.f, 0.f}; bf16x8 kr[4];
; #pragma unroll
;                 for (int s = 0; s < 4; ++s) kr[s] = ROWFRAG(IMG_K, 16 * nt, s);
;                 __builtin_amdgcn_sched_barrier(0);
; #pragma unroll
;                 for (int s = 0; s < 4; ++s) a = MFMA16(kr[s], qf[s], a);
;                 const f32x4 ct = *(const LAS f32x4*)(vcol + 16 * nt + 4 * fg); float p[4];
; #pragma unroll
;                 for (int e = 0; e < 4; ++e) { const int j = 16 * nt + 4 * fg + e;
;                     const bool keep = dir ? (is_m ? (j >= irow) : (j > irow)) : (j <= irow);
;                     const float ex = __builtin_amdgcn_exp2f(rt + ct[e]); p[e] = keep ? a[e] * ex : 0.f; }
;                 u32x2 pv; pv.x = cvt_pk_bf16(p[0], p[1]); pv.y = cvt_pk_bf16(p[2], p[3]);
;                 { LAUNDER_X16 *(LAS u32x2*)(lds + IMG_Q + CWA(nt)) = pv; } __builtin_amdgcn_sched_barrier(0); }
;             bf16x8 pf[4];
; #pragma unroll
;             for (int s = 0; s < 4; ++s) pf[s] = ROWFRAG(IMG_Q, 16 * w, s);
;             bf16x8 kf[4], kraw[4];
; #pragma unroll
;             for (int ks = 0; ks < 4; ++ks) kraw[ks] = trfrag_(lds, IMG_K + 256u * (32u * ks) + ktb0, IMG_K + 256u * (32u * ks + 4u) + ktb1);
.Lmk_done_5:
.LBB0_299:
	s_waitcnt lgkmcnt(0)
	v_add_f32_e32 v129, v171, v129
	v_exp_f32_e32 v129, v129
	v_add_f32_e32 v130, v171, v130
	v_add_f32_e32 v128, v171, v128
	v_exp_f32_e32 v130, v130
	v_mul_f32_e32 v125, v125, v129
	v_exp_f32_e32 v128, v128
	v_add_f32_e32 v129, v171, v131
	v_exp_f32_e32 v129, v129
	v_mul_f32_e32 v126, v126, v130
	v_mul_f32_e32 v124, v124, v128
	v_cndmask_b32_e64 v126, 0, v126, s[50:51]
	v_cndmask_b32_e64 v125, 0, v125, s[18:19]
	v_cndmask_b32_e64 v124, 0, v124, s[16:17]
	v_mul_f32_e32 v127, v127, v129
	v_cndmask_b32_e64 v127, 0, v127, s[54:55]
	v_cvt_pk_bf16_f32 v124, v124, v125
	v_cvt_pk_bf16_f32 v125, v126, v127
	v_mov_b32_e32 v126, v179
	s_nop 0
	v_xad_u32 v126, v126, s31, v191
	ds_write_b64 v126, v[124:125]
	ds_read_b128 v[124:127], v132 offset:57344
	ds_read_b128 v[128:131], v133 offset:57344
	ds_read_b128 v[136:139], v134 offset:57344
	ds_read_b128 v[140:143], v135 offset:57344
	s_waitcnt lgkmcnt(3)
	v_mfma_f32_16x16x32_bf16 v[124:127], v[124:127], v[92:95], 0
	s_mov_b64 s[18:19], -1
	s_and_b64 vcc, exec, s[48:49]
	s_waitcnt lgkmcnt(2)
	v_mfma_f32_16x16x32_bf16 v[124:127], v[128:131], v[96:99], v[124:127]
	ds_read_b128 v[128:131], v190 offset:384
	s_waitcnt lgkmcnt(2)
	v_mfma_f32_16x16x32_bf16 v[124:127], v[136:139], v[100:103], v[124:127]
	s_waitcnt lgkmcnt(1)
	v_mfma_f32_16x16x32_bf16 v[124:127], v[140:143], v[88:91], v[124:127]
	v_cmp_le_i32_e64 s[16:17], v238, v188
	v_cmp_le_i32_e64 s[18:19], v239, v188
	v_cmp_le_i32_e64 s[50:51], v240, v188
	v_cmp_le_i32_e64 s[54:55], v241, v188
	s_cbranch_vccnz .Lmk_done_6
	v_cndmask_b32_e64 v140, 1, 0, s[42:43]
	v_add_u32_e32 v140, v140, v188
	v_cmp_ge_i32_e64 s[16:17], v238, v140
	v_cmp_ge_i32_e64 s[18:19], v239, v140
	v_cmp_ge_i32_e64 s[50:51], v240, v140
	v_cmp_ge_i32_e64 s[54:55], v241, v140
.Lmk_done_6:
.LBB0_331:
	s_waitcnt lgkmcnt(0)
	v_add_f32_e32 v129, v171, v129
	v_exp_f32_e32 v129, v129
	v_add_f32_e32 v130, v171, v130
	v_add_f32_e32 v128, v171, v128
	v_exp_f32_e32 v130, v130
	v_mul_f32_e32 v125, v125, v129
	v_exp_f32_e32 v128, v128
	v_add_f32_e32 v129, v171, v131
	v_exp_f32_e32 v129, v129
	v_mul_f32_e32 v126, v126, v130
	v_mul_f32_e32 v124, v124, v128
	v_cndmask_b32_e64 v126, 0, v126, s[50:51]
	v_cndmask_b32_e64 v125, 0, v125, s[18:19]
	v_cndmask_b32_e64 v124, 0, v124, s[16:17]
	v_mul_f32_e32 v127, v127, v129
	v_cndmask_b32_e64 v127, 0, v127, s[54:55]
	v_cvt_pk_bf16_f32 v124, v124, v125
	v_cvt_pk_bf16_f32 v125, v126, v127
	v_mov_b32_e32 v126, v179
	s_nop 0
	v_xad_u32 v126, v126, s27, v191
	ds_write_b64 v126, v[124:125]
	ds_read_b128 v[124:127], v132 offset:61440
	ds_read_b128 v[128:131], v133 offset:61440
	ds_read_b128 v[136:139], v134 offset:61440
	ds_read_b128 v[132:135], v135 offset:61440
	s_waitcnt lgkmcnt(3)
	v_mfma_f32_16x16x32_bf16 v[92:95], v[124:127], v[92:95], 0
	s_mov_b64 s[18:19], -1
	s_and_b64 vcc, exec, s[48:49]
	s_waitcnt lgkmcnt(2)
	v_mfma_f32_16x16x32_bf16 v[92:95], v[128:131], v[96:99], v[92:95]
	s_waitcnt lgkmcnt(1)
	v_mfma_f32_16x16x32_bf16 v[96:99], v[136:139], v[100:103], v[92:95]
	s_waitcnt lgkmcnt(0)
	v_mfma_f32_16x16x32_bf16 v[88:91], v[132:135], v[88:91], v[96:99]
	s_nop 3
	ds_read_b128 v[92:95], v190 offset:448
	v_cmp_le_i32_e64 s[16:17], v242, v188
	v_cmp_le_i32_e64 s[18:19], v243, v188
	v_cmp_le_i32_e64 s[54:55], v244, v188
	v_cmp_le_i32_e64 s[50:51], v245, v188
	s_cbranch_vccnz .Lmk_done_7
	v_cndmask_b32_e64 v140, 1, 0, s[42:43]
	v_add_u32_e32 v140, v140, v188
	v_cmp_ge_i32_e64 s[16:17], v242, v140
	v_cmp_ge_i32_e64 s[18:19], v243, v140
	v_cmp_ge_i32_e64 s[54:55], v244, v140
	v_cmp_ge_i32_e64 s[50:51], v245, v140
.Lmk_done_7:
.LBB0_363:
	v_pk_mul_f32 v[148:149], v[76:77], v[158:159] op_sel_hi:[1,0]
	s_waitcnt lgkmcnt(0)
	v_add_f32_e32 v76, v171, v95
	v_add_f32_e32 v94, v171, v94
	v_add_f32_e32 v93, v171, v93
	v_add_f32_e32 v92, v171, v92
	v_exp_f32_e32 v76, v76
	v_exp_f32_e32 v94, v94
	v_exp_f32_e32 v93, v93
	v_exp_f32_e32 v92, v92
	v_mul_f32_e32 v76, v91, v76
	v_mul_f32_e32 v90, v90, v94
	v_mul_f32_e32 v89, v89, v93
	v_mul_f32_e32 v88, v88, v92
	v_pk_mul_f32 v[150:151], v[78:79], v[158:159] op_sel_hi:[1,0]
	v_cndmask_b32_e64 v77, 0, v76, s[50:51]
	v_mov_b32_e32 v78, v179
	v_cndmask_b32_e64 v90, 0, v90, s[54:55]
	v_cndmask_b32_e64 v89, 0, v89, s[18:19]
	v_cndmask_b32_e64 v88, 0, v88, s[16:17]
	v_cvt_pk_bf16_f32 v76, v88, v89
	v_cvt_pk_bf16_f32 v77, v90, v77
	v_pk_mul_f32 v[130:131], v[106:107], v[158:159] op_sel_hi:[1,0]
	v_pk_mul_f32 v[128:129], v[104:105], v[158:159] op_sel_hi:[1,0]
	v_pk_mul_f32 v[138:139], v[110:111], v[158:159] op_sel_hi:[1,0]
	v_pk_mul_f32 v[136:137], v[108:109], v[158:159] op_sel_hi:[1,0]
	v_pk_mul_f32 v[134:135], v[114:115], v[158:159] op_sel_hi:[1,0]
	v_pk_mul_f32 v[132:133], v[112:113], v[158:159] op_sel_hi:[1,0]
	v_pk_mul_f32 v[126:127], v[118:119], v[158:159] op_sel_hi:[1,0]
	v_pk_mul_f32 v[124:125], v[116:117], v[158:159] op_sel_hi:[1,0]
	v_pk_mul_f32 v[118:119], v[122:123], v[158:159] op_sel_hi:[1,0]
	v_pk_mul_f32 v[116:117], v[120:121], v[158:159] op_sel_hi:[1,0]
	v_xad_u32 v78, v78, s97, v191
	v_pk_mul_f32 v[146:147], v[82:83], v[158:159] op_sel_hi:[1,0]
	v_pk_mul_f32 v[144:145], v[80:81], v[158:159] op_sel_hi:[1,0]
	v_pk_mul_f32 v[142:143], v[86:87], v[158:159] op_sel_hi:[1,0]
	v_pk_mul_f32 v[140:141], v[84:85], v[158:159] op_sel_hi:[1,0]
	ds_write_b64 v78, v[76:77]
	ds_read_b128 v[100:103], v0
	ds_read_b128 v[88:91], v157
	ds_read_b128 v[84:87], v159
	ds_read_b128 v[76:79], v170
	ds_read_b64_tr_b16 v[96:97], v165 offset:32768
	ds_read_b64_tr_b16 v[98:99], v165 offset:40960
	ds_read_b64_tr_b16 v[104:105], v165 offset:49152
	ds_read_b64_tr_b16 v[112:113], v165 offset:57344
	ds_read_b64_tr_b16 v[106:107], v166 offset:33792
	ds_read_b64_tr_b16 v[114:115], v166 offset:41984
	ds_read_b64_tr_b16 v[120:121], v166 offset:50176
	ds_read_b64_tr_b16 v[122:123], v166 offset:58368
	ds_read_b128 v[80:83], v192
	ds_read_b128 v[92:95], v192 offset:16
	s_waitcnt lgkmcnt(9)
; #define LAS __attribute__((address_space(3)))
; __device__ __forceinline__ unsigned cvt_pk_bf16(float lo, float hi) { unsigned r; asm volatile("v_cvt_pk_bf16_f32 %0, %1, %2" : "=v"(r) : "v"(lo), "v"(hi)); return r; }
; #define TRFRAG(img, c, ks) trfrag_(lds, (img) + 256u * (32u * (ks)) + TRA(c, 0), (img) + 256u * (32u * (ks) + 4u) + TRA(c, 1))
; #define MFMA16(a, b, c) __builtin_amdgcn_mfma_f32_16x16x32_bf16((a), (b), (c), 0, 0, 0)
; __device__ void mix_sweep(const Params& P, LAS unsigned char* lds, int tok0, int pos0, int seqlen, int hd, int dir, bool state_only, bool final_pass,
;                           f32x4 (&Cacc)[9], float& m_state, float& aseg_sum, float lgam) {
;     ...
;             for (int ks = 0; ks < 4; ++ks) { const bf16x8 raw = kraw[ks];
;                 const f32x4 k0 = *(const LAS f32x4*)(vkw + 32 * ks + 8 * fg), k1 = *(const LAS f32x4*)(vkw + 32 * ks + 8 * fg + 4);
;                 float f[8];
; #pragma unroll
;                 for (int e = 0; e < 8; ++e) f[e] = __uint_as_float(((unsigned)(unsigned short)raw[e]) << 16) * (e < 4 ? k0[e] : k1[e - 4]);
;                 u32x4 pk; pk.x = cvt_pk_bf16(f[0], f[1]); pk.y = cvt_pk_bf16(f[2], f[3]); pk.z = cvt_pk_bf16(f[4], f[5]); pk.w = cvt_pk_bf16(f[6], f[7]);
;                 kf[ks] = __builtin_bit_cast(bf16x8, pk); }
;             __builtin_amdgcn_s_setprio(1);
; #pragma unroll
;             for (int nt = 0; nt < 8; ++nt) { LAUNDER_L16
;                 bf16x8 vf[4];
; #pragma unroll
;                 for (int ks = 0; ks < 4; ++ks) vf[ks] = TRFRAG(IMG_V, nt, ks);
;                 __builtin_amdgcn_sched_barrier(0);
;                 f32x4 a = Cacc[nt] * decay;
; #pragma unroll
;                 for (int ks = 0; ks < 4; ++ks) { O[nt] = MFMA16(vf[ks], pf[ks], O[nt]); a = MFMA16(vf[ks], kf[ks], a); }
;                 Cacc[nt] = a; }
	v_lshlrev_b32_e32 v0, 16, v96
	v_and_b32_e32 v96, 0xffff0000, v96
	s_waitcnt lgkmcnt(1)
	v_mul_f32_e32 v0, v80, v0
	v_mul_f32_e32 v80, v81, v96
	v_lshlrev_b32_e32 v81, 16, v97
	v_mul_f32_e32 v81, v82, v81
	v_and_b32_e32 v82, 0xffff0000, v97
	v_mul_f32_e32 v82, v83, v82
	v_lshlrev_b32_e32 v83, 16, v106
	s_waitcnt lgkmcnt(0)
	v_mul_f32_e32 v83, v92, v83
	v_and_b32_e32 v92, 0xffff0000, v106
	v_mul_f32_e32 v92, v93, v92
	v_lshlrev_b32_e32 v93, 16, v107
	v_mul_f32_e32 v93, v94, v93
	v_and_b32_e32 v94, 0xffff0000, v107
	v_mul_f32_e32 v94, v95, v94
	v_cvt_pk_bf16_f32 v108, v0, v80
	v_cvt_pk_bf16_f32 v109, v81, v82
	v_cvt_pk_bf16_f32 v110, v83, v92
	v_cvt_pk_bf16_f32 v111, v93, v94
	ds_read_b128 v[80:83], v192 offset:128
	ds_read_b128 v[92:95], v192 offset:144
	v_lshlrev_b32_e32 v0, 16, v98
	s_waitcnt lgkmcnt(1)
	v_mul_f32_e32 v0, v80, v0
	v_and_b32_e32 v80, 0xffff0000, v98
	v_mul_f32_e32 v80, v81, v80
	v_lshlrev_b32_e32 v81, 16, v99
	v_mul_f32_e32 v81, v82, v81
	v_and_b32_e32 v82, 0xffff0000, v99
	v_mul_f32_e32 v82, v83, v82
	v_lshlrev_b32_e32 v83, 16, v114
	s_waitcnt lgkmcnt(0)
	v_mul_f32_e32 v83, v92, v83
	v_and_b32_e32 v92, 0xffff0000, v114
	v_mul_f32_e32 v96, v93, v92
	v_lshlrev_b32_e32 v92, 16, v115
	v_mul_f32_e32 v97, v94, v92
	v_and_b32_e32 v92, 0xffff0000, v115
	v_mul_f32_e32 v95, v95, v92
	v_cvt_pk_bf16_f32 v92, v0, v80
	v_cvt_pk_bf16_f32 v93, v81, v82
	v_cvt_pk_bf16_f32 v94, v83, v96
	v_cvt_pk_bf16_f32 v95, v97, v95
	ds_read_b128 v[80:83], v192 offset:256
	ds_read_b128 v[96:99], v192 offset:272
	v_lshlrev_b32_e32 v0, 16, v104
	s_waitcnt lgkmcnt(1)
	v_mul_f32_e32 v0, v80, v0
	v_and_b32_e32 v80, 0xffff0000, v104
	v_mul_f32_e32 v80, v81, v80
	v_lshlrev_b32_e32 v81, 16, v105
	v_mul_f32_e32 v81, v82, v81
	v_and_b32_e32 v82, 0xffff0000, v105
	v_mul_f32_e32 v82, v83, v82
	v_lshlrev_b32_e32 v83, 16, v120
	s_waitcnt lgkmcnt(0)
	v_mul_f32_e32 v83, v96, v83
	v_and_b32_e32 v96, 0xffff0000, v120
	v_mul_f32_e32 v96, v97, v96
	v_lshlrev_b32_e32 v97, 16, v121
	v_mul_f32_e32 v97, v98, v97
	v_and_b32_e32 v98, 0xffff0000, v121
	v_mul_f32_e32 v98, v99, v98
	v_cvt_pk_bf16_f32 v104, v0, v80
	v_cvt_pk_bf16_f32 v105, v81, v82
	v_cvt_pk_bf16_f32 v106, v83, v96
	v_cvt_pk_bf16_f32 v107, v97, v98
	ds_read_b128 v[80:83], v192 offset:384
	ds_read_b128 v[96:99], v192 offset:400
	v_lshlrev_b32_e32 v0, 16, v112
	s_waitcnt lgkmcnt(1)
	v_mul_f32_e32 v0, v80, v0
	v_and_b32_e32 v80, 0xffff0000, v112
	v_mul_f32_e32 v80, v81, v80
	v_lshlrev_b32_e32 v81, 16, v113
	v_mul_f32_e32 v81, v82, v81
	v_and_b32_e32 v82, 0xffff0000, v113
	v_mul_f32_e32 v82, v83, v82
	v_lshlrev_b32_e32 v83, 16, v122
	s_waitcnt lgkmcnt(0)
	v_mul_f32_e32 v83, v96, v83
	v_and_b32_e32 v96, 0xffff0000, v122
	v_mul_f32_e32 v112, v97, v96
	v_lshlrev_b32_e32 v96, 16, v123
	v_mul_f32_e32 v113, v98, v96
	v_and_b32_e32 v96, 0xffff0000, v123
	v_mul_f32_e32 v99, v99, v96
	v_cvt_pk_bf16_f32 v96, v0, v80
	v_cvt_pk_bf16_f32 v97, v81, v82
	v_cvt_pk_bf16_f32 v98, v83, v112
	v_cvt_pk_bf16_f32 v99, v113, v99
	s_setprio 1
	v_mov_b32_e32 v0, v178
	s_nop 0
	v_xor_b32_e32 v120, 16, v0
	v_add_u32_e32 v80, v246, v0
	v_add_u32_e32 v82, v247, v120
	v_add_u32_e32 v112, v248, v0
	v_add_u32_e32 v114, v249, v120
	v_add_u32_e32 v121, v250, v0
	v_add_u32_e32 v122, v251, v120
	ds_read_b64_tr_b16 v[80:81], v80
	ds_read_b64_tr_b16 v[82:83], v82
	ds_read_b64_tr_b16 v[112:113], v112
	ds_read_b64_tr_b16 v[114:115], v114
	v_add_u32_e32 v0, v252, v0
	v_add_u32_e32 v157, v211, v120
	ds_read_b64_tr_b16 v[120:121], v121
	ds_read_b64_tr_b16 v[122:123], v122
	ds_read_b64_tr_b16 v[170:171], v0
	ds_read_b64_tr_b16 v[172:173], v157
	v_pk_mul_f32 v[34:35], v[34:35], v[156:157] op_sel_hi:[1,0]
	v_pk_mul_f32 v[32:33], v[32:33], v[156:157] op_sel_hi:[1,0]
	s_waitcnt lgkmcnt(6)
	v_mfma_f32_16x16x32_bf16 v[148:151], v[80:83], v[100:103], v[148:151]
	v_mov_b32_e32 v0, v178
	v_mfma_f32_16x16x32_bf16 v[32:35], v[80:83], v[108:111], v[32:35]
	v_xor_b32_e32 v157, 32, v0
	v_xor_b32_e32 v0, 48, v0
	s_waitcnt lgkmcnt(4)
	v_mfma_f32_16x16x32_bf16 v[80:83], v[112:115], v[88:91], v[148:151]
	v_mfma_f32_16x16x32_bf16 v[32:35], v[112:115], v[92:95], v[32:35]
	v_add_u32_e32 v112, v246, v157
	v_add_u32_e32 v114, v247, v0
	ds_read_b64_tr_b16 v[112:113], v112
	ds_read_b64_tr_b16 v[114:115], v114
	s_waitcnt lgkmcnt(4)
	v_mfma_f32_16x16x32_bf16 v[80:83], v[120:123], v[84:87], v[80:83]
	v_add_u32_e32 v148, v250, v157
	v_add_u32_e32 v150, v251, v0
	ds_read_b64_tr_b16 v[148:149], v148
	ds_read_b64_tr_b16 v[150:151], v150
	v_mfma_f32_16x16x32_bf16 v[32:35], v[120:123], v[104:107], v[32:35]
	v_add_u32_e32 v120, v248, v157
	v_add_u32_e32 v122, v249, v0
	ds_read_b64_tr_b16 v[120:121], v120
	ds_read_b64_tr_b16 v[122:123], v122
	v_add_u32_e32 v157, v252, v157
	v_add_u32_e32 v0, v211, v0
	s_waitcnt lgkmcnt(6)
	v_mfma_f32_16x16x32_bf16 v[80:83], v[170:173], v[76:79], v[80:83]
	v_mfma_f32_16x16x32_bf16 v[32:35], v[170:173], v[96:99], v[32:35]
	ds_read_b64_tr_b16 v[170:171], v157
	ds_read_b64_tr_b16 v[172:173], v0
	v_pk_mul_f32 v[30:31], v[30:31], v[156:157] op_sel_hi:[1,0]
	v_pk_mul_f32 v[28:29], v[28:29], v[156:157] op_sel_hi:[1,0]
	s_waitcnt lgkmcnt(6)
	v_mfma_f32_16x16x32_bf16 v[144:147], v[112:115], v[100:103], v[144:147]
	v_mov_b32_e32 v0, v178
	v_mfma_f32_16x16x32_bf16 v[28:31], v[112:115], v[108:111], v[28:31]
	v_xor_b32_e32 v157, 64, v0
	v_xor_b32_e32 v0, 0x50, v0
	s_waitcnt lgkmcnt(2)
; #define TRFRAG(img, c, ks) trfrag_(lds, (img) + 256u * (32u * (ks)) + TRA(c, 0), (img) + 256u * (32u * (ks) + 4u) + TRA(c, 1))
; #define MFMA16(a, b, c) __builtin_amdgcn_mfma_f32_16x16x32_bf16((a), (b), (c), 0, 0, 0)
; __device__ void mix_sweep(const Params& P, LAS unsigned char* lds, int tok0, int pos0, int seqlen, int hd, int dir, bool state_only, bool final_pass,
;                           f32x4 (&Cacc)[9], float& m_state, float& aseg_sum, float lgam) {
;     ...
;             for (int nt = 0; nt < 8; ++nt) { LAUNDER_L16
;                 bf16x8 vf[4];
; #pragma unroll
;                 for (int ks = 0; ks < 4; ++ks) vf[ks] = TRFRAG(IMG_V, nt, ks);
;                 __builtin_amdgcn_sched_barrier(0);
;                 f32x4 a = Cacc[nt] * decay;
; #pragma unroll
;                 for (int ks = 0; ks < 4; ++ks) { O[nt] = MFMA16(vf[ks], pf[ks], O[nt]); a = MFMA16(vf[ks], kf[ks], a); }
;                 Cacc[nt] = a; }
	v_mfma_f32_16x16x32_bf16 v[112:115], v[120:123], v[88:91], v[144:147]
	v_mfma_f32_16x16x32_bf16 v[28:31], v[120:123], v[92:95], v[28:31]
	v_add_u32_e32 v120, v246, v157
	v_add_u32_e32 v122, v247, v0
	ds_read_b64_tr_b16 v[120:121], v120
	ds_read_b64_tr_b16 v[122:123], v122
	v_mfma_f32_16x16x32_bf16 v[112:115], v[148:151], v[84:87], v[112:115]
	v_add_u32_e32 v144, v248, v157
	v_add_u32_e32 v146, v249, v0
	ds_read_b64_tr_b16 v[144:145], v144
	v_mfma_f32_16x16x32_bf16 v[28:31], v[148:151], v[104:107], v[28:31]
	v_add_u32_e32 v148, v250, v157
	v_add_u32_e32 v150, v251, v0
	v_add_u32_e32 v157, v252, v157
	v_add_u32_e32 v0, v211, v0
	s_waitcnt lgkmcnt(3)
	v_mfma_f32_16x16x32_bf16 v[112:115], v[170:173], v[76:79], v[112:115]
	ds_read_b64_tr_b16 v[146:147], v146
	ds_read_b64_tr_b16 v[148:149], v148
	ds_read_b64_tr_b16 v[150:151], v150
	v_mfma_f32_16x16x32_bf16 v[28:31], v[170:173], v[96:99], v[28:31]
	ds_read_b64_tr_b16 v[170:171], v157
	ds_read_b64_tr_b16 v[172:173], v0
	v_pk_mul_f32 v[26:27], v[26:27], v[156:157] op_sel_hi:[1,0]
	v_pk_mul_f32 v[24:25], v[24:25], v[156:157] op_sel_hi:[1,0]
	s_waitcnt lgkmcnt(6)
	v_mfma_f32_16x16x32_bf16 v[140:143], v[120:123], v[100:103], v[140:143]
	v_mov_b32_e32 v0, v178
	v_mfma_f32_16x16x32_bf16 v[24:27], v[120:123], v[108:111], v[24:27]
	v_xor_b32_e32 v157, 0x60, v0
	v_xor_b32_e32 v0, 0x70, v0
	s_waitcnt lgkmcnt(4)
	v_mfma_f32_16x16x32_bf16 v[120:123], v[144:147], v[88:91], v[140:143]
	v_mfma_f32_16x16x32_bf16 v[24:27], v[144:147], v[92:95], v[24:27]
	s_nop 1
	v_add_u32_e32 v140, v246, v157
	v_add_u32_e32 v142, v247, v0
	v_add_u32_e32 v144, v248, v157
	s_waitcnt lgkmcnt(2)
	v_mfma_f32_16x16x32_bf16 v[120:123], v[148:151], v[84:87], v[120:123]
	v_add_u32_e32 v146, v249, v0
	ds_read_b64_tr_b16 v[140:141], v140
	ds_read_b64_tr_b16 v[142:143], v142
	ds_read_b64_tr_b16 v[144:145], v144
	v_mfma_f32_16x16x32_bf16 v[24:27], v[148:151], v[104:107], v[24:27]
	v_add_u32_e32 v148, v250, v157
	v_add_u32_e32 v150, v251, v0
	v_add_u32_e32 v157, v252, v157
	v_add_u32_e32 v0, v211, v0
	s_waitcnt lgkmcnt(3)
	v_mfma_f32_16x16x32_bf16 v[120:123], v[170:173], v[76:79], v[120:123]
	ds_read_b64_tr_b16 v[146:147], v146
	ds_read_b64_tr_b16 v[148:149], v148
	ds_read_b64_tr_b16 v[150:151], v150
	v_mfma_f32_16x16x32_bf16 v[24:27], v[170:173], v[96:99], v[24:27]
	ds_read_b64_tr_b16 v[170:171], v157
	ds_read_b64_tr_b16 v[172:173], v0
	v_pk_mul_f32 v[22:23], v[22:23], v[156:157] op_sel_hi:[1,0]
	v_pk_mul_f32 v[20:21], v[20:21], v[156:157] op_sel_hi:[1,0]
	s_waitcnt lgkmcnt(6)
	v_mfma_f32_16x16x32_bf16 v[128:131], v[140:143], v[100:103], v[128:131]
	v_mov_b32_e32 v0, v178
	v_mfma_f32_16x16x32_bf16 v[20:23], v[140:143], v[108:111], v[20:23]
	v_xor_b32_e32 v157, 0x80, v0
	v_xor_b32_e32 v0, 0x90, v0
	v_add_u32_e32 v140, v246, v157
	s_waitcnt lgkmcnt(4)
	v_mfma_f32_16x16x32_bf16 v[128:131], v[144:147], v[88:91], v[128:131]
	v_add_u32_e32 v142, v247, v0
	ds_read_b64_tr_b16 v[140:141], v140
	ds_read_b64_tr_b16 v[142:143], v142
	v_mfma_f32_16x16x32_bf16 v[20:23], v[144:147], v[92:95], v[20:23]
	v_add_u32_e32 v144, v248, v157
	v_add_u32_e32 v146, v249, v0
	ds_read_b64_tr_b16 v[144:145], v144
	s_waitcnt lgkmcnt(5)
	v_mfma_f32_16x16x32_bf16 v[128:131], v[148:151], v[84:87], v[128:131]
	ds_read_b64_tr_b16 v[146:147], v146
	v_mfma_f32_16x16x32_bf16 v[20:23], v[148:151], v[104:107], v[20:23]
	v_add_u32_e32 v148, v250, v157
	v_add_u32_e32 v150, v251, v0
	v_add_u32_e32 v157, v252, v157
	v_add_u32_e32 v0, v211, v0
	s_waitcnt lgkmcnt(4)
	v_mfma_f32_16x16x32_bf16 v[128:131], v[170:173], v[76:79], v[128:131]
	ds_read_b64_tr_b16 v[148:149], v148
	ds_read_b64_tr_b16 v[150:151], v150
	v_mfma_f32_16x16x32_bf16 v[20:23], v[170:173], v[96:99], v[20:23]
	ds_read_b64_tr_b16 v[170:171], v157
	ds_read_b64_tr_b16 v[172:173], v0
	v_pk_mul_f32 v[18:19], v[18:19], v[156:157] op_sel_hi:[1,0]
	v_pk_mul_f32 v[16:17], v[16:17], v[156:157] op_sel_hi:[1,0]
	s_waitcnt lgkmcnt(6)
	v_mfma_f32_16x16x32_bf16 v[136:139], v[140:143], v[100:103], v[136:139]
	v_mov_b32_e32 v0, v178
	v_mfma_f32_16x16x32_bf16 v[16:19], v[140:143], v[108:111], v[16:19]
	v_xor_b32_e32 v157, 0xa0, v0
	v_xor_b32_e32 v0, 0xb0, v0
	v_add_u32_e32 v140, v246, v157
	s_waitcnt lgkmcnt(4)
	v_mfma_f32_16x16x32_bf16 v[136:139], v[144:147], v[88:91], v[136:139]
	v_add_u32_e32 v142, v247, v0
	ds_read_b64_tr_b16 v[140:141], v140
	ds_read_b64_tr_b16 v[142:143], v142
	v_mfma_f32_16x16x32_bf16 v[16:19], v[144:147], v[92:95], v[16:19]
	v_add_u32_e32 v144, v248, v157
	v_add_u32_e32 v146, v249, v0
	ds_read_b64_tr_b16 v[144:145], v144
	s_waitcnt lgkmcnt(5)
; #define TRFRAG(img, c, ks) trfrag_(lds, (img) + 256u * (32u * (ks)) + TRA(c, 0), (img) + 256u * (32u * (ks) + 4u) + TRA(c, 1))
; #define MFMA16(a, b, c) __builtin_amdgcn_mfma_f32_16x16x32_bf16((a), (b), (c), 0, 0, 0)
; __device__ void mix_sweep(const Params& P, LAS unsigned char* lds, int tok0, int pos0, int seqlen, int hd, int dir, bool state_only, bool final_pass,
;                           f32x4 (&Cacc)[9], float& m_state, float& aseg_sum, float lgam) {
;     ...
;             for (int nt = 0; nt < 8; ++nt) { LAUNDER_L16
;                 bf16x8 vf[4];
; #pragma unroll
;                 for (int ks = 0; ks < 4; ++ks) vf[ks] = TRFRAG(IMG_V, nt, ks);
;                 __builtin_amdgcn_sched_barrier(0);
;                 f32x4 a = Cacc[nt] * decay;
; #pragma unroll
;                 for (int ks = 0; ks < 4; ++ks) { O[nt] = MFMA16(vf[ks], pf[ks], O[nt]); a = MFMA16(vf[ks], kf[ks], a); }
;                 Cacc[nt] = a; }
;             if (is_m) { f32x4 a = Cacc[8] * decay;
	v_mfma_f32_16x16x32_bf16 v[136:139], v[148:151], v[84:87], v[136:139]
	ds_read_b64_tr_b16 v[146:147], v146
	v_mfma_f32_16x16x32_bf16 v[16:19], v[148:151], v[104:107], v[16:19]
	v_add_u32_e32 v148, v250, v157
	v_add_u32_e32 v150, v251, v0
	v_add_u32_e32 v157, v252, v157
	v_add_u32_e32 v0, v211, v0
	s_waitcnt lgkmcnt(4)
	v_mfma_f32_16x16x32_bf16 v[136:139], v[170:173], v[76:79], v[136:139]
	ds_read_b64_tr_b16 v[148:149], v148
	ds_read_b64_tr_b16 v[150:151], v150
	v_mfma_f32_16x16x32_bf16 v[16:19], v[170:173], v[96:99], v[16:19]
	ds_read_b64_tr_b16 v[170:171], v157
	ds_read_b64_tr_b16 v[172:173], v0
	v_pk_mul_f32 v[14:15], v[14:15], v[156:157] op_sel_hi:[1,0]
	v_pk_mul_f32 v[12:13], v[12:13], v[156:157] op_sel_hi:[1,0]
	s_waitcnt lgkmcnt(6)
	v_mfma_f32_16x16x32_bf16 v[132:135], v[140:143], v[100:103], v[132:135]
	v_mov_b32_e32 v0, v178
	v_mfma_f32_16x16x32_bf16 v[12:15], v[140:143], v[108:111], v[12:15]
	v_xor_b32_e32 v157, 0xc0, v0
	v_xor_b32_e32 v0, 0xd0, v0
	v_add_u32_e32 v140, v246, v157
	s_waitcnt lgkmcnt(4)
	v_mfma_f32_16x16x32_bf16 v[132:135], v[144:147], v[88:91], v[132:135]
	v_add_u32_e32 v142, v247, v0
	ds_read_b64_tr_b16 v[140:141], v140
	ds_read_b64_tr_b16 v[142:143], v142
	v_mfma_f32_16x16x32_bf16 v[12:15], v[144:147], v[92:95], v[12:15]
	v_add_u32_e32 v144, v248, v157
	v_add_u32_e32 v146, v249, v0
	ds_read_b64_tr_b16 v[144:145], v144
	s_waitcnt lgkmcnt(5)
	v_mfma_f32_16x16x32_bf16 v[132:135], v[148:151], v[84:87], v[132:135]
	ds_read_b64_tr_b16 v[146:147], v146
	v_mfma_f32_16x16x32_bf16 v[12:15], v[148:151], v[104:107], v[12:15]
	v_add_u32_e32 v148, v250, v157
	v_add_u32_e32 v150, v251, v0
	v_add_u32_e32 v157, v252, v157
	v_add_u32_e32 v0, v211, v0
	s_waitcnt lgkmcnt(4)
	v_mfma_f32_16x16x32_bf16 v[132:135], v[170:173], v[76:79], v[132:135]
	ds_read_b64_tr_b16 v[148:149], v148
	ds_read_b64_tr_b16 v[150:151], v150
	v_mfma_f32_16x16x32_bf16 v[12:15], v[170:173], v[96:99], v[12:15]
	ds_read_b64_tr_b16 v[170:171], v157
	ds_read_b64_tr_b16 v[172:173], v0
	v_pk_mul_f32 v[10:11], v[10:11], v[156:157] op_sel_hi:[1,0]
	v_pk_mul_f32 v[8:9], v[8:9], v[156:157] op_sel_hi:[1,0]
	s_waitcnt lgkmcnt(6)
	v_mfma_f32_16x16x32_bf16 v[124:127], v[140:143], v[100:103], v[124:127]
	v_mov_b32_e32 v0, v178
	v_mfma_f32_16x16x32_bf16 v[8:11], v[140:143], v[108:111], v[8:11]
	v_xor_b32_e32 v157, 0xe0, v0
	v_xor_b32_e32 v0, 0xf0, v0
	v_add_u32_e32 v140, v246, v157
	s_waitcnt lgkmcnt(4)
	v_mfma_f32_16x16x32_bf16 v[124:127], v[144:147], v[88:91], v[124:127]
	v_add_u32_e32 v142, v247, v0
	ds_read_b64_tr_b16 v[140:141], v140
	ds_read_b64_tr_b16 v[142:143], v142
	v_mfma_f32_16x16x32_bf16 v[8:11], v[144:147], v[92:95], v[8:11]
	v_add_u32_e32 v144, v248, v157
	v_add_u32_e32 v146, v249, v0
	ds_read_b64_tr_b16 v[144:145], v144
	s_waitcnt lgkmcnt(5)
	v_mfma_f32_16x16x32_bf16 v[124:127], v[148:151], v[84:87], v[124:127]
	ds_read_b64_tr_b16 v[146:147], v146
	v_mfma_f32_16x16x32_bf16 v[8:11], v[148:151], v[104:107], v[8:11]
	v_add_u32_e32 v148, v250, v157
	v_add_u32_e32 v150, v251, v0
	v_add_u32_e32 v157, v252, v157
	v_add_u32_e32 v0, v211, v0
	s_waitcnt lgkmcnt(4)
	v_mfma_f32_16x16x32_bf16 v[124:127], v[170:173], v[76:79], v[124:127]
	ds_read_b64_tr_b16 v[148:149], v148
	ds_read_b64_tr_b16 v[150:151], v150
	v_mfma_f32_16x16x32_bf16 v[8:11], v[170:173], v[96:99], v[8:11]
	ds_read_b64_tr_b16 v[170:171], v157
	ds_read_b64_tr_b16 v[172:173], v0
	v_pk_mul_f32 v[6:7], v[6:7], v[156:157] op_sel_hi:[1,0]
	v_pk_mul_f32 v[4:5], v[4:5], v[156:157] op_sel_hi:[1,0]
	s_waitcnt lgkmcnt(6)
	v_mfma_f32_16x16x32_bf16 v[116:119], v[140:143], v[100:103], v[116:119]
	s_mov_b64 s[16:17], -1
	s_and_b64 vcc, exec, s[92:93]
	v_mfma_f32_16x16x32_bf16 v[4:7], v[140:143], v[108:111], v[4:7]
	s_waitcnt lgkmcnt(4)
	v_mfma_f32_16x16x32_bf16 v[116:119], v[144:147], v[88:91], v[116:119]
	v_mfma_f32_16x16x32_bf16 v[4:7], v[144:147], v[92:95], v[4:7]
	s_waitcnt lgkmcnt(2)
	v_mfma_f32_16x16x32_bf16 v[116:119], v[148:151], v[84:87], v[116:119]
	v_mfma_f32_16x16x32_bf16 v[4:7], v[148:151], v[104:107], v[4:7]
	s_waitcnt lgkmcnt(0)
	v_mfma_f32_16x16x32_bf16 v[116:119], v[170:173], v[76:79], v[116:119]
	v_mfma_f32_16x16x32_bf16 v[4:7], v[170:173], v[96:99], v[4:7]
	s_cbranch_vccz .LBB0_365
	s_setprio 0
	s_mov_b64 s[16:17], 0

; #define NTL(p) __builtin_nontemporal_load((const f32x4*)(p))
; #define NTS(v, p) __builtin_nontemporal_store((v), (f32x4*)(p))
;     __device__ __forceinline__ void operator()(AccT& acc, const Unit& u, int wr, int wc, int fr, int fq) const {
;     ...
;         const int row0 = u.pm * 256 + wr * 64 + fr, col0 = u.pn * 256 + wc * 32 + 8 * fq;
;         f32x4 hv[2][4]; u32x4 pv[2][2]; float rs[2];
;         const bf16_t* ppbase = (u.L < 256 ? T0 : T1) + (size_t)(u.L & 255) * 65536 + (wr * 64 + fr) * 256 + wc * 32 + 8 * fq;
;         { const float* hr = H + (size_t)row0 * DM + col0; const bf16_t* pp = ppbase;
;           hv[0][0] = NTL(hr); hv[0][1] = NTL(hr + 4); hv[0][2] = NTL(hr + 128); hv[0][3] = NTL(hr + 132);
;           pv[0][0] = *(const u32x4*)pp; pv[0][1] = *(const u32x4*)(pp + 128); rs[0] = rss2[row0]; }
; #pragma unroll
;         for (int r = 0; r < 8; ++r) { const int ai = r >> 2, m = r & 3; const int row = row0 + ai * 128 + m * 16;
;             if (r < 7) { const int rn = row0 + ((r + 1) >> 2) * 128 + ((r + 1) & 3) * 16; const float* hn = H + (size_t)rn * DM + col0; const bf16_t* pn = ppbase + (((r + 1) >> 2) * 128 + ((r + 1) & 3) * 16) * 256;
;                 hv[(r + 1) & 1][0] = NTL(hn); hv[(r + 1) & 1][1] = NTL(hn + 4); hv[(r + 1) & 1][2] = NTL(hn + 128); hv[(r + 1) & 1][3] = NTL(hn + 132);
;                 pv[(r + 1) & 1][0] = *(const u32x4*)pn; pv[(r + 1) & 1][1] = *(const u32x4*)(pn + 128); rs[(r + 1) & 1] = rss2[rn]; }
;             float* hp = H + (size_t)row * DM + col0; float ss = 0.f; const float rstd = rsqrtf(rs[r & 1] * (1.0f / DM) + 1e-6f);
; #pragma unroll
;             for (int bj = 0; bj < 2; ++bj) { const u32x4 pw = pv[r & 1][bj];
;                 const f32x4 b0 = *(const f32x4*)(bias + col0 + bj * 128), b1 = *(const f32x4*)(bias + col0 + bj * 128 + 4);
;                 const f32x4 p0 = (f32x4){bf_lo(pw.x), bf_hi(pw.x), bf_lo(pw.y), bf_hi(pw.y)}, p1 = (f32x4){bf_lo(pw.z), bf_hi(pw.z), bf_lo(pw.w), bf_hi(pw.w)};
;                 f32x4 g0 = acc[ai][bj][m][0] * rstd + b0, g1 = acc[ai][bj][m][1] * rstd + b1;
; #pragma unroll
;                 for (int j = 0; j < 4; ++j) { g0[j] = sigmoidf_(g0[j]); g1[j] = sigmoidf_(g1[j]); }
;                 const f32x4 v0 = hv[r & 1][2 * bj] + p0 * g0, v1 = hv[r & 1][2 * bj + 1] + p1 * g1;
;                 NTS(v0, hp + bj * 128); NTS(v1, hp + bj * 128 + 4);
.LBB0_781:
	v_mov_b32_e32 v130, v169
	v_mov_b32_e32 v145, v222
	v_add_u32_e32 v131, s79, v130
	v_lshl_add_u32 v186, s0, 8, v131
	s_lshl_b32 s0, s24, 8
	v_ashrrev_i32_e32 v187, 31, v186
	s_or_b32 s0, s0, s80
	v_lshl_add_u64 v[188:189], v[186:187], 2, s[34:35]
	s_cmpk_lt_i32 s26, 0x100
	global_load_dword v144, v[188:189], off
	s_cselect_b32 s3, s50, s53
	s_cselect_b32 s2, s51, s52
	s_lshl_b32 s4, s26, 17
	s_and_b32 s4, s4, 0x1fe0000
	s_add_u32 s2, s2, s4
	v_lshlrev_b32_e32 v132, 8, v131
	v_lshlrev_b32_e32 v130, 3, v145
	s_addc_u32 s3, s3, 0
	v_ashrrev_i32_e32 v133, 31, v132
	v_lshl_add_u64 v[132:133], v[132:133], 1, s[2:3]
	v_add_u32_e32 v192, s0, v130
	v_lshl_add_u64 v[132:133], v[132:133], 0, s[38:39]
	v_ashrrev_i32_e32 v131, 31, v130
	v_ashrrev_i32_e32 v193, 31, v192
	v_readlane_b32 s60, v255, 2
	v_lshl_add_u64 v[190:191], v[130:131], 1, v[132:133]
	v_lshlrev_b64 v[130:131], 2, v[192:193]
	v_readlane_b32 s72, v255, 14
	v_readlane_b32 s73, v255, 15
	global_load_dwordx4 v[138:141], v[190:191], off
	v_lshlrev_b64 v[132:133], 12, v[186:187]
	v_lshl_add_u64 v[184:185], s[72:73], 0, v[130:131]
	global_load_dwordx4 v[240:243], v[184:185], off
	global_load_dwordx4 v[244:247], v[184:185], off offset:16
	global_load_dwordx4 v[248:251], v[184:185], off offset:512
	global_load_dwordx4 v[232:235], v[184:185], off offset:528
	v_add_u32_e32 v198, 16, v186
	v_lshl_add_u64 v[132:133], s[22:23], 0, v[132:133]
	v_ashrrev_i32_e32 v199, 31, v198
	v_lshl_add_u64 v[142:143], v[132:133], 0, v[130:131]
	v_add_co_u32_e32 v132, vcc, s85, v190
	v_lshl_add_u64 v[134:135], v[198:199], 2, s[34:35]
	s_nop 0
	v_addc_co_u32_e32 v133, vcc, 0, v191, vcc
	global_load_dword v165, v[134:135], off
	global_load_dwordx4 v[170:173], v[142:143], off offset:16 nt
	global_load_dwordx4 v[194:197], v[142:143], off nt
	s_nop 0
	global_load_dwordx4 v[134:137], v[190:191], off offset:256
	global_load_dwordx4 v[158:161], v[132:133], off
	global_load_dwordx4 v[146:149], v[132:133], off offset:256
	v_readlane_b32 s61, v255, 3
	v_readlane_b32 s62, v255, 4
	v_readlane_b32 s63, v255, 5
	v_readlane_b32 s64, v255, 6
	v_readlane_b32 s65, v255, 7
	v_readlane_b32 s66, v255, 8
	v_readlane_b32 s67, v255, 9
	v_readlane_b32 s68, v255, 10
	v_readlane_b32 s69, v255, 11
	v_readlane_b32 s70, v255, 12
	v_readlane_b32 s71, v255, 13
	v_readlane_b32 s74, v255, 16
	v_readlane_b32 s75, v255, 17
	s_waitcnt vmcnt(11)
	v_fmamk_f32 v132, v144, 0x3a800000, v210
	v_mul_f32_e32 v133, 0x4b800000, v132
	v_cmp_gt_f32_e32 vcc, s30, v132
	s_waitcnt vmcnt(10)
	v_lshlrev_b32_e32 v166, 16, v140
	s_nop 0
	v_cndmask_b32_e32 v132, v132, v133, vcc
	v_rsq_f32_e32 v144, v132
	v_lshlrev_b32_e32 v132, 16, v138
	v_and_b32_e32 v133, 0xffff0000, v138
	v_lshlrev_b32_e32 v138, 16, v139
	v_mul_f32_e32 v164, 0x45800000, v144
	v_cndmask_b32_e32 v144, v144, v164, vcc
	s_waitcnt vmcnt(9)
	v_pk_fma_f32 v[124:125], v[124:125], v[144:145], v[242:243] op_sel_hi:[1,0,1]
	v_pk_fma_f32 v[122:123], v[122:123], v[144:145], v[240:241] op_sel_hi:[1,0,1]
	s_waitcnt vmcnt(8)
	v_pk_fma_f32 v[114:115], v[114:115], v[144:145], v[244:245] op_sel_hi:[1,0,1]
	v_mul_f32_e32 v122, 0xbfb8aa3b, v122
	v_mul_f32_e32 v123, 0xbfb8aa3b, v123
	v_mul_f32_e32 v151, 0xbfb8aa3b, v115
	v_mul_f32_e32 v115, 0xbfb8aa3b, v124
	v_mul_f32_e32 v150, 0xbfb8aa3b, v114
	v_exp_f32_e32 v114, v122
	v_exp_f32_e32 v124, v115
	v_exp_f32_e32 v115, v123
	v_mul_f32_e32 v125, 0xbfb8aa3b, v125
	v_exp_f32_e32 v125, v125
	v_exp_f32_e32 v122, v150
	v_pk_add_f32 v[114:115], v[114:115], 1.0 op_sel_hi:[1,0]
	v_pk_fma_f32 v[116:117], v[116:117], v[144:145], v[246:247] op_sel_hi:[1,0,1]
	v_div_scale_f32 v150, s[2:3], v115, v115, 1.0
	v_pk_add_f32 v[124:125], v[124:125], 1.0 op_sel_hi:[1,0]
	v_div_scale_f32 v152, s[2:3], v114, v114, 1.0
	v_rcp_f32_e32 v154, v150
	v_div_scale_f32 v153, s[2:3], v125, v125, 1.0
	v_rcp_f32_e32 v155, v152
	v_rcp_f32_e32 v156, v153
	v_fma_f32 v164, -v150, v154, 1.0
	v_exp_f32_e32 v123, v151
	v_div_scale_f32 v151, vcc, 1.0, v115, 1.0
	v_fma_f32 v200, -v152, v155, 1.0
	v_fmac_f32_e32 v154, v164, v154
	v_div_scale_f32 v157, s[42:43], 1.0, v114, 1.0
	v_fma_f32 v201, -v153, v156, 1.0
	v_fmac_f32_e32 v155, v200, v155
	v_mul_f32_e32 v164, v151, v154
	v_fmac_f32_e32 v156, v201, v156
	v_mul_f32_e32 v200, v157, v155
	v_fma_f32 v201, -v150, v164, v151
	v_fma_f32 v202, -v152, v200, v157
	v_fmac_f32_e32 v164, v201, v154
	v_fmac_f32_e32 v200, v202, v155
	v_fma_f32 v150, -v150, v164, v151
	v_fma_f32 v151, -v152, v200, v157
	v_div_fmas_f32 v150, v150, v154, v164
	s_mov_b64 vcc, s[42:43]
	v_div_fixup_f32 v115, v150, v115, 1.0
	v_div_fmas_f32 v150, v151, v155, v200
	v_div_fixup_f32 v114, v150, v114, 1.0
	v_div_scale_f32 v150, vcc, 1.0, v125, 1.0
	v_mul_f32_e32 v151, v150, v156
	v_fma_f32 v152, -v153, v151, v150
	v_fmac_f32_e32 v151, v152, v156
	v_div_scale_f32 v152, s[2:3], v124, v124, 1.0
	v_fma_f32 v150, -v153, v151, v150
	v_rcp_f32_e32 v153, v152
	v_div_fmas_f32 v150, v150, v156, v151
	v_div_fixup_f32 v125, v150, v125, 1.0
	v_pk_add_f32 v[122:123], v[122:123], 1.0 op_sel_hi:[1,0]
	v_fma_f32 v150, -v152, v153, 1.0
	v_fmac_f32_e32 v153, v150, v153
	v_div_scale_f32 v150, vcc, 1.0, v124, 1.0
	v_mul_f32_e32 v151, v150, v153
	v_fma_f32 v154, -v152, v151, v150
	v_fmac_f32_e32 v151, v154, v153
	v_fma_f32 v150, -v152, v151, v150
	v_div_scale_f32 v152, s[2:3], v123, v123, 1.0
	v_rcp_f32_e32 v154, v152
	v_div_fmas_f32 v150, v150, v153, v151
	v_div_fixup_f32 v124, v150, v124, 1.0
	v_mul_f32_e32 v116, 0xbfb8aa3b, v116
	v_fma_f32 v150, -v152, v154, 1.0
	v_fmac_f32_e32 v154, v150, v154
	v_div_scale_f32 v150, vcc, 1.0, v123, 1.0
	v_mul_f32_e32 v151, v150, v154
	v_fma_f32 v153, -v152, v151, v150
; #define NTL(p) __builtin_nontemporal_load((const f32x4*)(p))
; #define NTS(v, p) __builtin_nontemporal_store((v), (f32x4*)(p))
; __device__ __forceinline__ float bf_lo(unsigned w) { return __uint_as_float(w << 16); }
; __device__ __forceinline__ float bf_hi(unsigned w) { return __uint_as_float(w & 0xffff0000u); }
; __device__ __forceinline__ float sigmoidf_(float x) { return 1.0f / (1.0f + __expf(-x)); }
;     __device__ __forceinline__ void operator()(AccT& acc, const Unit& u, int wr, int wc, int fr, int fq) const {
;     ...
;             if (r < 7) { const int rn = row0 + ((r + 1) >> 2) * 128 + ((r + 1) & 3) * 16; const float* hn = H + (size_t)rn * DM + col0; const bf16_t* pn = ppbase + (((r + 1) >> 2) * 128 + ((r + 1) & 3) * 16) * 256;
;                 hv[(r + 1) & 1][0] = NTL(hn); hv[(r + 1) & 1][1] = NTL(hn + 4); hv[(r + 1) & 1][2] = NTL(hn + 128); hv[(r + 1) & 1][3] = NTL(hn + 132);
;                 pv[(r + 1) & 1][0] = *(const u32x4*)pn; pv[(r + 1) & 1][1] = *(const u32x4*)(pn + 128); rs[(r + 1) & 1] = rss2[rn]; }
;             float* hp = H + (size_t)row * DM + col0; float ss = 0.f; const float rstd = rsqrtf(rs[r & 1] * (1.0f / DM) + 1e-6f);
; #pragma unroll
;             for (int bj = 0; bj < 2; ++bj) { const u32x4 pw = pv[r & 1][bj];
;                 const f32x4 b0 = *(const f32x4*)(bias + col0 + bj * 128), b1 = *(const f32x4*)(bias + col0 + bj * 128 + 4);
;                 const f32x4 p0 = (f32x4){bf_lo(pw.x), bf_hi(pw.x), bf_lo(pw.y), bf_hi(pw.y)}, p1 = (f32x4){bf_lo(pw.z), bf_hi(pw.z), bf_lo(pw.w), bf_hi(pw.w)};
;                 f32x4 g0 = acc[ai][bj][m][0] * rstd + b0, g1 = acc[ai][bj][m][1] * rstd + b1;
; #pragma unroll
;                 for (int j = 0; j < 4; ++j) { g0[j] = sigmoidf_(g0[j]); g1[j] = sigmoidf_(g1[j]); }
;                 const f32x4 v0 = hv[r & 1][2 * bj] + p0 * g0, v1 = hv[r & 1][2 * bj + 1] + p1 * g1;
;                 NTS(v0, hp + bj * 128); NTS(v1, hp + bj * 128 + 4);
; #pragma unroll
;                 for (int j = 0; j < 4; ++j) ss += v0[j] * v0[j] + v1[j] * v1[j]; }
	v_fmac_f32_e32 v151, v153, v154
	v_fma_f32 v150, -v152, v151, v150
	v_div_scale_f32 v152, s[2:3], v122, v122, 1.0
	v_rcp_f32_e32 v153, v152
	v_mul_f32_e32 v117, 0xbfb8aa3b, v117
	v_div_fmas_f32 v150, v150, v154, v151
	v_exp_f32_e32 v116, v116
	v_exp_f32_e32 v117, v117
	v_div_fixup_f32 v123, v150, v123, 1.0
	v_fma_f32 v150, -v152, v153, 1.0
	v_fmac_f32_e32 v153, v150, v153
	v_div_scale_f32 v150, vcc, 1.0, v122, 1.0
	v_mul_f32_e32 v151, v150, v153
	v_fma_f32 v154, -v152, v151, v150
	v_pk_add_f32 v[116:117], v[116:117], 1.0 op_sel_hi:[1,0]
	v_fmac_f32_e32 v151, v154, v153
	v_fma_f32 v150, -v152, v151, v150
	v_div_scale_f32 v152, s[2:3], v117, v117, 1.0
	v_rcp_f32_e32 v154, v152
	v_div_fmas_f32 v150, v150, v153, v151
	v_div_fixup_f32 v122, v150, v122, 1.0
	v_and_b32_e32 v139, 0xffff0000, v139
	v_fma_f32 v150, -v152, v154, 1.0
	v_fmac_f32_e32 v154, v150, v154
	v_div_scale_f32 v150, vcc, 1.0, v117, 1.0
	v_mul_f32_e32 v151, v150, v154
	v_fma_f32 v153, -v152, v151, v150
	v_fmac_f32_e32 v151, v153, v154
	v_fma_f32 v150, -v152, v151, v150
	v_div_scale_f32 v152, s[2:3], v116, v116, 1.0
	v_rcp_f32_e32 v153, v152
	v_div_fmas_f32 v150, v150, v154, v151
	v_div_fixup_f32 v151, v150, v117, 1.0
	v_and_b32_e32 v167, 0xffff0000, v140
	v_fma_f32 v117, -v152, v153, 1.0
	v_fmac_f32_e32 v153, v117, v153
	v_div_scale_f32 v117, vcc, 1.0, v116, 1.0
	v_mul_f32_e32 v150, v117, v153
	v_fma_f32 v154, -v152, v150, v117
	v_fmac_f32_e32 v150, v154, v153
	v_fma_f32 v117, -v152, v150, v117
	v_div_fmas_f32 v117, v117, v153, v150
	v_lshlrev_b32_e32 v140, 16, v141
	v_and_b32_e32 v141, 0xffff0000, v141
	v_div_fixup_f32 v150, v117, v116, 1.0
	s_waitcnt vmcnt(3)
	v_pk_fma_f32 v[116:117], v[124:125], v[138:139], v[196:197]
	v_pk_fma_f32 v[114:115], v[114:115], v[132:133], v[194:195]
	v_pk_fma_f32 v[124:125], v[150:151], v[140:141], v[172:173]
	v_pk_fma_f32 v[122:123], v[122:123], v[166:167], v[170:171]
	global_store_dwordx4 v[142:143], v[114:117], off nt
	global_store_dwordx4 v[142:143], v[122:125], off offset:16 nt
	s_nop 0
	s_nop 0
	global_load_dwordx4 v[204:207], v[142:143], off offset:528 nt
	global_load_dwordx4 v[226:229], v[142:143], off offset:512 nt
	v_mul_f32_e32 v122, v122, v122
	v_fmac_f32_e32 v122, v114, v114
	v_mul_f32_e32 v114, v123, v123
	v_fmac_f32_e32 v114, v115, v115
	v_mul_f32_e32 v115, v124, v124
	v_add_f32_e32 v114, v122, v114
	v_fmac_f32_e32 v115, v116, v116
	v_add_f32_e32 v114, v115, v114
	v_mul_f32_e32 v115, v125, v125
	v_fmac_f32_e32 v115, v117, v117
	v_add_f32_e32 v166, v115, v114
	s_waitcnt vmcnt(6)
	v_lshlrev_b32_e32 v114, 16, v134
	v_and_b32_e32 v115, 0xffff0000, v134
	v_lshlrev_b32_e32 v116, 16, v135
	v_and_b32_e32 v117, 0xffff0000, v135
	v_and_b32_e32 v133, 64, v203
	v_xor_b32_e32 v132, 16, v203
	v_add_u32_e32 v164, 64, v133
	v_cmp_lt_i32_e32 vcc, v132, v164
	v_lshlrev_b32_e32 v122, 16, v136
	v_and_b32_e32 v123, 0xffff0000, v136
	v_cndmask_b32_e32 v132, v203, v132, vcc
	v_lshlrev_b32_e32 v124, 16, v137
	v_and_b32_e32 v125, 0xffff0000, v137
	v_lshlrev_b32_e32 v225, 2, v132
	v_lshlrev_b64 v[132:133], 12, v[198:199]
	v_lshl_add_u64 v[132:133], s[22:23], 0, v[132:133]
	v_lshl_add_u64 v[200:201], v[132:133], 0, v[130:131]
	global_load_dwordx4 v[150:153], v[200:201], off offset:16 nt
	global_load_dwordx4 v[154:157], v[200:201], off nt
	global_load_dwordx4 v[130:133], v[200:201], off offset:528 nt
	global_load_dwordx4 v[138:141], v[200:201], off offset:512 nt
	v_cmp_eq_u32_e64 s[42:43], 0, v145
	v_pk_fma_f32 v[110:111], v[110:111], v[144:145], v[248:249] op_sel_hi:[1,0,1]
	s_nop 0
	v_mul_f32_e32 v110, 0xbfb8aa3b, v110
	v_mul_f32_e32 v111, 0xbfb8aa3b, v111
	v_exp_f32_e32 v110, v110
	v_exp_f32_e32 v111, v111
	v_pk_fma_f32 v[112:113], v[112:113], v[144:145], v[250:251] op_sel_hi:[1,0,1]
	v_pk_fma_f32 v[108:109], v[108:109], v[144:145], v[234:235] op_sel_hi:[1,0,1]
	v_pk_fma_f32 v[106:107], v[106:107], v[144:145], v[232:233] op_sel_hi:[1,0,1]
	v_pk_add_f32 v[110:111], v[110:111], 1.0 op_sel_hi:[1,0]
	v_mul_f32_e32 v112, 0xbfb8aa3b, v112
	v_div_scale_f32 v134, s[2:3], v111, v111, 1.0
	v_rcp_f32_e32 v135, v134
	v_mul_f32_e32 v113, 0xbfb8aa3b, v113
	v_exp_f32_e32 v112, v112
	v_exp_f32_e32 v113, v113
	v_fma_f32 v136, -v134, v135, 1.0
	v_fmac_f32_e32 v135, v136, v135
	v_div_scale_f32 v136, vcc, 1.0, v111, 1.0
	v_mul_f32_e32 v137, v136, v135
	v_fma_f32 v144, -v134, v137, v136
	v_fmac_f32_e32 v137, v144, v135
	v_fma_f32 v134, -v134, v137, v136
	v_div_scale_f32 v136, s[2:3], v110, v110, 1.0
	v_rcp_f32_e32 v144, v136
	v_div_fmas_f32 v134, v134, v135, v137
	v_div_fixup_f32 v135, v134, v111, 1.0
	v_pk_add_f32 v[112:113], v[112:113], 1.0 op_sel_hi:[1,0]
	v_fma_f32 v111, -v136, v144, 1.0
	v_fmac_f32_e32 v144, v111, v144
	v_div_scale_f32 v111, vcc, 1.0, v110, 1.0
	v_mul_f32_e32 v134, v111, v144
	v_fma_f32 v137, -v136, v134, v111
	v_fmac_f32_e32 v134, v137, v144
	v_fma_f32 v111, -v136, v134, v111
	v_div_scale_f32 v136, s[2:3], v113, v113, 1.0
	v_rcp_f32_e32 v137, v136
	v_div_fmas_f32 v111, v111, v144, v134
	v_div_fixup_f32 v134, v111, v110, 1.0
	v_mul_f32_e32 v106, 0xbfb8aa3b, v106
	v_fma_f32 v110, -v136, v137, 1.0
	v_fmac_f32_e32 v137, v110, v137
	v_div_scale_f32 v110, vcc, 1.0, v113, 1.0
	v_mul_f32_e32 v111, v110, v137
	v_fma_f32 v144, -v136, v111, v110
	v_fmac_f32_e32 v111, v144, v137
	v_fma_f32 v110, -v136, v111, v110
	v_div_scale_f32 v136, s[2:3], v112, v112, 1.0
	v_rcp_f32_e32 v144, v136
	v_mul_f32_e32 v107, 0xbfb8aa3b, v107
	v_div_fmas_f32 v110, v110, v137, v111
	v_exp_f32_e32 v106, v106
	v_exp_f32_e32 v107, v107
	v_div_fixup_f32 v111, v110, v113, 1.0
	v_fma_f32 v110, -v136, v144, 1.0
	v_fmac_f32_e32 v144, v110, v144
	v_div_scale_f32 v110, vcc, 1.0, v112, 1.0
	v_mul_f32_e32 v113, v110, v144
	v_fma_f32 v137, -v136, v113, v110
	v_fmac_f32_e32 v113, v137, v144
	v_pk_add_f32 v[106:107], v[106:107], 1.0 op_sel_hi:[1,0]
	v_fma_f32 v110, -v136, v113, v110
	v_div_scale_f32 v136, s[2:3], v107, v107, 1.0
	v_rcp_f32_e32 v137, v136
	v_div_fmas_f32 v110, v110, v144, v113
	v_div_fixup_f32 v110, v110, v112, 1.0
	v_mul_f32_e32 v108, 0xbfb8aa3b, v108
	v_fma_f32 v112, -v136, v137, 1.0
	v_fmac_f32_e32 v137, v112, v137
	v_div_scale_f32 v112, vcc, 1.0, v107, 1.0
	v_mul_f32_e32 v113, v112, v137
	v_fma_f32 v144, -v136, v113, v112
	v_fmac_f32_e32 v113, v144, v137
	v_fma_f32 v112, -v136, v113, v112
	v_div_scale_f32 v136, s[2:3], v106, v106, 1.0
	v_rcp_f32_e32 v144, v136
	v_mul_f32_e32 v109, 0xbfb8aa3b, v109
	v_div_fmas_f32 v112, v112, v137, v113
	v_exp_f32_e32 v108, v108
	v_exp_f32_e32 v109, v109
	v_div_fixup_f32 v107, v112, v107, 1.0
	v_fma_f32 v112, -v136, v144, 1.0
	v_fmac_f32_e32 v144, v112, v144
	v_div_scale_f32 v112, vcc, 1.0, v106, 1.0
	v_mul_f32_e32 v113, v112, v144
	v_fma_f32 v137, -v136, v113, v112
	v_pk_add_f32 v[108:109], v[108:109], 1.0 op_sel_hi:[1,0]
	v_fmac_f32_e32 v113, v137, v144
	v_fma_f32 v112, -v136, v113, v112
	v_div_scale_f32 v136, s[2:3], v109, v109, 1.0
	v_rcp_f32_e32 v137, v136
	v_div_fmas_f32 v112, v112, v144, v113
	v_div_fixup_f32 v106, v112, v106, 1.0
	s_waitcnt vmcnt(4)
; #define NTL(p) __builtin_nontemporal_load((const f32x4*)(p))
; #define NTS(v, p) __builtin_nontemporal_store((v), (f32x4*)(p))
; __device__ __forceinline__ float bf_lo(unsigned w) { return __uint_as_float(w << 16); }
; __device__ __forceinline__ float bf_hi(unsigned w) { return __uint_as_float(w & 0xffff0000u); }
; __device__ __forceinline__ float sigmoidf_(float x) { return 1.0f / (1.0f + __expf(-x)); }
;     __device__ __forceinline__ void operator()(AccT& acc, const Unit& u, int wr, int wc, int fr, int fq) const {
;     ...
;             if (r < 7) { const int rn = row0 + ((r + 1) >> 2) * 128 + ((r + 1) & 3) * 16; const float* hn = H + (size_t)rn * DM + col0; const bf16_t* pn = ppbase + (((r + 1) >> 2) * 128 + ((r + 1) & 3) * 16) * 256;
;                 hv[(r + 1) & 1][0] = NTL(hn); hv[(r + 1) & 1][1] = NTL(hn + 4); hv[(r + 1) & 1][2] = NTL(hn + 128); hv[(r + 1) & 1][3] = NTL(hn + 132);
;                 pv[(r + 1) & 1][0] = *(const u32x4*)pn; pv[(r + 1) & 1][1] = *(const u32x4*)(pn + 128); rs[(r + 1) & 1] = rss2[rn]; }
;             float* hp = H + (size_t)row * DM + col0; float ss = 0.f; const float rstd = rsqrtf(rs[r & 1] * (1.0f / DM) + 1e-6f);
; #pragma unroll
;             for (int bj = 0; bj < 2; ++bj) { const u32x4 pw = pv[r & 1][bj];
;                 const f32x4 b0 = *(const f32x4*)(bias + col0 + bj * 128), b1 = *(const f32x4*)(bias + col0 + bj * 128 + 4);
;                 const f32x4 p0 = (f32x4){bf_lo(pw.x), bf_hi(pw.x), bf_lo(pw.y), bf_hi(pw.y)}, p1 = (f32x4){bf_lo(pw.z), bf_hi(pw.z), bf_lo(pw.w), bf_hi(pw.w)};
;                 f32x4 g0 = acc[ai][bj][m][0] * rstd + b0, g1 = acc[ai][bj][m][1] * rstd + b1;
; #pragma unroll
;                 for (int j = 0; j < 4; ++j) { g0[j] = sigmoidf_(g0[j]); g1[j] = sigmoidf_(g1[j]); }
;                 const f32x4 v0 = hv[r & 1][2 * bj] + p0 * g0, v1 = hv[r & 1][2 * bj + 1] + p1 * g1;
;                 NTS(v0, hp + bj * 128); NTS(v1, hp + bj * 128 + 4);
; #pragma unroll
;                 for (int j = 0; j < 4; ++j) ss += v0[j] * v0[j] + v1[j] * v1[j]; }
;             ss += __shfl_xor(ss, 16); ss += __shfl_xor(ss, 32);
;             if (fq == 0) unsafeAtomicAdd(rss3 + row, ss); __builtin_amdgcn_sched_barrier(0); }
	v_pk_fma_f32 v[110:111], v[110:111], v[116:117], v[228:229]
	v_fma_f32 v112, -v136, v137, 1.0
	v_fmac_f32_e32 v137, v112, v137
	v_div_scale_f32 v112, vcc, 1.0, v109, 1.0
	v_mul_f32_e32 v113, v112, v137
	v_fma_f32 v144, -v136, v113, v112
	v_fmac_f32_e32 v113, v144, v137
	v_fma_f32 v112, -v136, v113, v112
	v_div_scale_f32 v136, s[2:3], v108, v108, 1.0
	v_rcp_f32_e32 v144, v136
	v_div_fmas_f32 v112, v112, v137, v113
	v_div_fixup_f32 v113, v112, v109, 1.0
	v_xor_b32_e32 v116, 32, v203
	v_fma_f32 v109, -v136, v144, 1.0
	v_fmac_f32_e32 v144, v109, v144
	v_div_scale_f32 v109, vcc, 1.0, v108, 1.0
	v_mul_f32_e32 v112, v109, v144
	v_fma_f32 v137, -v136, v112, v109
	v_fmac_f32_e32 v112, v137, v144
	v_fma_f32 v109, -v136, v112, v109
	v_div_fmas_f32 v109, v109, v144, v112
	v_div_fixup_f32 v112, v109, v108, 1.0
	v_pk_fma_f32 v[108:109], v[134:135], v[114:115], v[226:227]
	v_pk_fma_f32 v[114:115], v[112:113], v[124:125], v[206:207]
	v_pk_fma_f32 v[112:113], v[106:107], v[122:123], v[204:205]
	v_cmp_lt_i32_e32 vcc, v116, v164
	v_mul_f32_e32 v106, v112, v112
	v_fmac_f32_e32 v106, v108, v108
	v_mul_f32_e32 v107, v113, v113
	v_add_f32_e32 v106, v106, v166
	v_fmac_f32_e32 v107, v109, v109
	v_add_f32_e32 v106, v107, v106
	v_mul_f32_e32 v107, v114, v114
	v_fmac_f32_e32 v107, v110, v110
	v_add_f32_e32 v106, v107, v106
	v_mul_f32_e32 v107, v115, v115
	v_fmac_f32_e32 v107, v111, v111
	v_add_f32_e32 v106, v107, v106
	ds_bpermute_b32 v107, v225, v106
	v_cndmask_b32_e32 v116, v203, v116, vcc
	v_lshlrev_b32_e32 v226, 2, v116
	global_store_dwordx4 v[142:143], v[108:111], off offset:512 nt
	global_store_dwordx4 v[142:143], v[112:115], off offset:528 nt
	s_waitcnt lgkmcnt(0)
	v_add_f32_e32 v106, v106, v107
	ds_bpermute_b32 v107, v226, v106
	s_and_saveexec_b64 s[2:3], s[42:43]
	s_cbranch_execz .LBB0_783
	v_lshl_add_u64 v[108:109], v[186:187], 2, s[36:37]
	s_waitcnt lgkmcnt(0)
	v_add_f32_e32 v106, v106, v107
	global_atomic_add_f32 v[108:109], v106, off
.LBB0_783:
	s_or_b64 exec, exec, s[2:3]
	v_add_u32_e32 v194, 32, v186
	v_ashrrev_i32_e32 v195, 31, v194
	s_waitcnt lgkmcnt(0)
	v_lshlrev_b64 v[106:107], 12, v[194:195]
	v_lshl_add_u64 v[106:107], s[22:23], 0, v[106:107]
	v_add_co_u32_e32 v114, vcc, 0x4000, v190
	v_lshl_add_u64 v[196:197], v[192:193], 2, v[106:107]
	s_nop 0
	v_addc_co_u32_e32 v115, vcc, 0, v191, vcc
	global_load_dwordx4 v[122:125], v[196:197], off offset:16 nt
	global_load_dwordx4 v[134:137], v[196:197], off nt
	global_load_dwordx4 v[106:109], v[196:197], off offset:528 nt
	global_load_dwordx4 v[110:113], v[196:197], off offset:512 nt
	global_load_dwordx4 v[142:145], v[114:115], off
	s_nop 0
	global_load_dwordx4 v[114:117], v[114:115], off offset:256
	s_nop 0
	global_load_dword v164, v[188:189], off offset:128
	v_fmamk_f32 v165, v165, 0x3a800000, v210
	v_cmp_gt_f32_e32 vcc, s30, v165
	v_mul_f32_e32 v166, 0x4b800000, v165
	v_lshlrev_b32_e32 v204, 16, v158
	v_cndmask_b32_e32 v165, v165, v166, vcc
	v_rsq_f32_e32 v165, v165
	v_and_b32_e32 v205, 0xffff0000, v158
	v_lshlrev_b32_e32 v206, 16, v159
	v_and_b32_e32 v207, 0xffff0000, v159
	v_mul_f32_e32 v166, 0x45800000, v165
	v_cndmask_b32_e32 v202, v165, v166, vcc
	v_lshlrev_b32_e32 v158, 16, v160
	v_and_b32_e32 v159, 0xffff0000, v160
	v_lshlrev_b32_e32 v160, 16, v161
	v_and_b32_e32 v161, 0xffff0000, v161
	v_pk_fma_f32 v[118:119], v[118:119], v[202:203], v[244:245] op_sel_hi:[1,0,1]
	v_pk_fma_f32 v[126:127], v[126:127], v[202:203], v[240:241] op_sel_hi:[1,0,1]
	v_mul_f32_e32 v118, 0xbfb8aa3b, v118
	v_mul_f32_e32 v126, 0xbfb8aa3b, v126
	v_pk_fma_f32 v[120:121], v[120:121], v[202:203], v[246:247] op_sel_hi:[1,0,1]
	v_exp_f32_e32 v166, v126
	v_exp_f32_e32 v126, v118
	v_mul_f32_e32 v118, 0xbfb8aa3b, v127
	v_pk_fma_f32 v[128:129], v[128:129], v[202:203], v[242:243] op_sel_hi:[1,0,1]
	v_exp_f32_e32 v167, v118
	v_mul_f32_e32 v118, 0xbfb8aa3b, v119
	v_mul_f32_e32 v119, 0xbfb8aa3b, v120
	v_exp_f32_e32 v127, v118
	v_mul_f32_e32 v118, 0xbfb8aa3b, v128
	v_exp_f32_e32 v120, v119
	v_mul_f32_e32 v119, 0xbfb8aa3b, v129
	v_exp_f32_e32 v118, v118
	v_exp_f32_e32 v119, v119
	v_pk_add_f32 v[126:127], v[126:127], 1.0 op_sel_hi:[1,0]
	v_mul_f32_e32 v121, 0xbfb8aa3b, v121
	v_exp_f32_e32 v121, v121
	v_pk_add_f32 v[128:129], v[118:119], 1.0 op_sel_hi:[1,0]
	v_pk_add_f32 v[118:119], v[166:167], 1.0 op_sel_hi:[1,0]
	v_pk_add_f32 v[120:121], v[120:121], 1.0 op_sel_hi:[1,0]
	v_div_scale_f32 v165, s[2:3], v119, v119, 1.0
	v_rcp_f32_e32 v166, v165
	s_nop 0
	v_fma_f32 v167, -v165, v166, 1.0
	v_fmac_f32_e32 v166, v167, v166
	v_div_scale_f32 v167, vcc, 1.0, v119, 1.0
	v_mul_f32_e32 v170, v167, v166
	v_fma_f32 v171, -v165, v170, v167
	v_fmac_f32_e32 v170, v171, v166
	v_fma_f32 v165, -v165, v170, v167
	v_div_fmas_f32 v165, v165, v166, v170
	v_div_fixup_f32 v119, v165, v119, 1.0
	v_div_scale_f32 v165, s[2:3], v118, v118, 1.0
	v_rcp_f32_e32 v166, v165
	s_nop 0
	v_fma_f32 v167, -v165, v166, 1.0
	v_fmac_f32_e32 v166, v167, v166
	v_div_scale_f32 v167, vcc, 1.0, v118, 1.0
	v_mul_f32_e32 v170, v167, v166
	v_fma_f32 v171, -v165, v170, v167
	v_fmac_f32_e32 v170, v171, v166
	v_fma_f32 v165, -v165, v170, v167
	v_div_fmas_f32 v165, v165, v166, v170
	v_div_fixup_f32 v118, v165, v118, 1.0
	v_div_scale_f32 v165, s[2:3], v129, v129, 1.0
	v_rcp_f32_e32 v166, v165
	s_waitcnt vmcnt(11)
; #define NTL(p) __builtin_nontemporal_load((const f32x4*)(p))
; #define NTS(v, p) __builtin_nontemporal_store((v), (f32x4*)(p))
; __device__ __forceinline__ float bf_lo(unsigned w) { return __uint_as_float(w << 16); }
; __device__ __forceinline__ float bf_hi(unsigned w) { return __uint_as_float(w & 0xffff0000u); }
; __device__ __forceinline__ float sigmoidf_(float x) { return 1.0f / (1.0f + __expf(-x)); }
;     __device__ __forceinline__ void operator()(AccT& acc, const Unit& u, int wr, int wc, int fr, int fq) const {
;     ...
;         for (int r = 0; r < 8; ++r) { const int ai = r >> 2, m = r & 3; const int row = row0 + ai * 128 + m * 16;
;             if (r < 7) { const int rn = row0 + ((r + 1) >> 2) * 128 + ((r + 1) & 3) * 16; const float* hn = H + (size_t)rn * DM + col0; const bf16_t* pn = ppbase + (((r + 1) >> 2) * 128 + ((r + 1) & 3) * 16) * 256;
;                 hv[(r + 1) & 1][0] = NTL(hn); hv[(r + 1) & 1][1] = NTL(hn + 4); hv[(r + 1) & 1][2] = NTL(hn + 128); hv[(r + 1) & 1][3] = NTL(hn + 132);
;                 pv[(r + 1) & 1][0] = *(const u32x4*)pn; pv[(r + 1) & 1][1] = *(const u32x4*)(pn + 128); rs[(r + 1) & 1] = rss2[rn]; }
;             float* hp = H + (size_t)row * DM + col0; float ss = 0.f; const float rstd = rsqrtf(rs[r & 1] * (1.0f / DM) + 1e-6f);
; #pragma unroll
;             for (int bj = 0; bj < 2; ++bj) { const u32x4 pw = pv[r & 1][bj];
;                 const f32x4 b0 = *(const f32x4*)(bias + col0 + bj * 128), b1 = *(const f32x4*)(bias + col0 + bj * 128 + 4);
;                 const f32x4 p0 = (f32x4){bf_lo(pw.x), bf_hi(pw.x), bf_lo(pw.y), bf_hi(pw.y)}, p1 = (f32x4){bf_lo(pw.z), bf_hi(pw.z), bf_lo(pw.w), bf_hi(pw.w)};
;                 f32x4 g0 = acc[ai][bj][m][0] * rstd + b0, g1 = acc[ai][bj][m][1] * rstd + b1;
; #pragma unroll
;                 for (int j = 0; j < 4; ++j) { g0[j] = sigmoidf_(g0[j]); g1[j] = sigmoidf_(g1[j]); }
;                 const f32x4 v0 = hv[r & 1][2 * bj] + p0 * g0, v1 = hv[r & 1][2 * bj + 1] + p1 * g1;
;                 NTS(v0, hp + bj * 128); NTS(v1, hp + bj * 128 + 4);
; #pragma unroll
;                 for (int j = 0; j < 4; ++j) ss += v0[j] * v0[j] + v1[j] * v1[j]; }
;             ss += __shfl_xor(ss, 16); ss += __shfl_xor(ss, 32);
;             if (fq == 0) unsafeAtomicAdd(rss3 + row, ss); __builtin_amdgcn_sched_barrier(0); }
	v_pk_fma_f32 v[118:119], v[118:119], v[204:205], v[154:155]
	v_fma_f32 v167, -v165, v166, 1.0
	v_fmac_f32_e32 v166, v167, v166
	v_div_scale_f32 v167, vcc, 1.0, v129, 1.0
	v_mul_f32_e32 v170, v167, v166
	v_fma_f32 v171, -v165, v170, v167
	v_fmac_f32_e32 v170, v171, v166
	v_fma_f32 v165, -v165, v170, v167
	v_div_fmas_f32 v165, v165, v166, v170
	v_div_fixup_f32 v129, v165, v129, 1.0
	v_div_scale_f32 v165, s[2:3], v128, v128, 1.0
	v_rcp_f32_e32 v166, v165
	s_nop 0
	v_fma_f32 v167, -v165, v166, 1.0
	v_fmac_f32_e32 v166, v167, v166
	v_div_scale_f32 v167, vcc, 1.0, v128, 1.0
	v_mul_f32_e32 v170, v167, v166
	v_fma_f32 v171, -v165, v170, v167
	v_fmac_f32_e32 v170, v171, v166
	v_fma_f32 v165, -v165, v170, v167
	v_div_fmas_f32 v165, v165, v166, v170
	v_div_fixup_f32 v128, v165, v128, 1.0
	v_div_scale_f32 v165, s[2:3], v127, v127, 1.0
	v_rcp_f32_e32 v166, v165
	s_nop 0
	v_fma_f32 v167, -v165, v166, 1.0
	v_fmac_f32_e32 v166, v167, v166
	v_div_scale_f32 v167, vcc, 1.0, v127, 1.0
	v_mul_f32_e32 v170, v167, v166
	v_fma_f32 v171, -v165, v170, v167
	v_fmac_f32_e32 v170, v171, v166
	v_fma_f32 v165, -v165, v170, v167
	v_div_fmas_f32 v165, v165, v166, v170
	v_div_fixup_f32 v127, v165, v127, 1.0
	v_div_scale_f32 v165, s[2:3], v126, v126, 1.0
	v_rcp_f32_e32 v166, v165
	s_nop 0
	v_fma_f32 v167, -v165, v166, 1.0
	v_fmac_f32_e32 v166, v167, v166
	v_div_scale_f32 v167, vcc, 1.0, v126, 1.0
	v_mul_f32_e32 v170, v167, v166
	v_fma_f32 v171, -v165, v170, v167
	v_fmac_f32_e32 v170, v171, v166
	v_fma_f32 v165, -v165, v170, v167
	v_div_fmas_f32 v165, v165, v166, v170
	v_div_fixup_f32 v126, v165, v126, 1.0
	v_div_scale_f32 v165, s[2:3], v121, v121, 1.0
	v_rcp_f32_e32 v166, v165
	v_pk_fma_f32 v[126:127], v[126:127], v[158:159], v[150:151]
	v_fma_f32 v167, -v165, v166, 1.0
	v_fmac_f32_e32 v166, v167, v166
	v_div_scale_f32 v167, vcc, 1.0, v121, 1.0
	v_mul_f32_e32 v170, v167, v166
	v_fma_f32 v171, -v165, v170, v167
	v_fmac_f32_e32 v170, v171, v166
	v_fma_f32 v165, -v165, v170, v167
	v_div_fmas_f32 v165, v165, v166, v170
	v_div_fixup_f32 v167, v165, v121, 1.0
	v_div_scale_f32 v121, s[2:3], v120, v120, 1.0
	v_rcp_f32_e32 v165, v121
	s_nop 0
	v_fma_f32 v166, -v121, v165, 1.0
	v_fmac_f32_e32 v165, v166, v165
	v_div_scale_f32 v166, vcc, 1.0, v120, 1.0
	v_mul_f32_e32 v170, v166, v165
	v_fma_f32 v171, -v121, v170, v166
	v_fmac_f32_e32 v170, v171, v165
	v_fma_f32 v121, -v121, v170, v166
	v_div_fmas_f32 v121, v121, v165, v170
	v_div_fixup_f32 v166, v121, v120, 1.0
	v_pk_fma_f32 v[120:121], v[128:129], v[206:207], v[156:157]
	v_pk_fma_f32 v[128:129], v[166:167], v[160:161], v[152:153]
	global_store_dwordx4 v[200:201], v[118:121], off nt
	global_store_dwordx4 v[200:201], v[126:129], off offset:16 nt
	s_nop 0
	s_nop 0
	v_mul_f32_e32 v126, v126, v126
	v_fmac_f32_e32 v126, v118, v118
	v_mul_f32_e32 v118, v127, v127
	v_fmac_f32_e32 v118, v119, v119
	v_add_f32_e32 v118, v126, v118
	v_mul_f32_e32 v119, v128, v128
	v_lshlrev_b32_e32 v126, 16, v146
	v_and_b32_e32 v127, 0xffff0000, v146
	v_fmac_f32_e32 v119, v120, v120
	v_add_f32_e32 v118, v119, v118
	v_mul_f32_e32 v119, v129, v129
	v_lshlrev_b32_e32 v128, 16, v147
	v_and_b32_e32 v129, 0xffff0000, v147
	v_fmac_f32_e32 v119, v121, v121
	v_add_f32_e32 v150, v119, v118
	v_lshlrev_b32_e32 v118, 16, v148
	v_and_b32_e32 v119, 0xffff0000, v148
	v_lshlrev_b32_e32 v120, 16, v149
	v_and_b32_e32 v121, 0xffff0000, v149
	v_pk_fma_f32 v[98:99], v[98:99], v[202:203], v[232:233] op_sel_hi:[1,0,1]
	v_pk_fma_f32 v[102:103], v[102:103], v[202:203], v[248:249] op_sel_hi:[1,0,1]
	v_mul_f32_e32 v98, 0xbfb8aa3b, v98
	v_pk_fma_f32 v[100:101], v[100:101], v[202:203], v[234:235] op_sel_hi:[1,0,1]
	v_exp_f32_e32 v146, v98
	v_mul_f32_e32 v98, 0xbfb8aa3b, v103
	v_pk_fma_f32 v[104:105], v[104:105], v[202:203], v[250:251] op_sel_hi:[1,0,1]
	v_exp_f32_e32 v103, v98
	v_mul_f32_e32 v98, 0xbfb8aa3b, v99
	v_mul_f32_e32 v99, 0xbfb8aa3b, v100
	v_mul_f32_e32 v102, 0xbfb8aa3b, v102
	v_exp_f32_e32 v147, v98
	v_mul_f32_e32 v98, 0xbfb8aa3b, v104
	v_exp_f32_e32 v100, v99
	v_mul_f32_e32 v99, 0xbfb8aa3b, v105
	v_exp_f32_e32 v102, v102
	v_exp_f32_e32 v98, v98
	v_exp_f32_e32 v99, v99
	v_mul_f32_e32 v101, 0xbfb8aa3b, v101
	v_exp_f32_e32 v101, v101
	v_pk_add_f32 v[104:105], v[98:99], 1.0 op_sel_hi:[1,0]
	v_pk_add_f32 v[98:99], v[102:103], 1.0 op_sel_hi:[1,0]
	v_pk_add_f32 v[100:101], v[100:101], 1.0 op_sel_hi:[1,0]
	v_div_scale_f32 v102, s[2:3], v99, v99, 1.0
	v_rcp_f32_e32 v103, v102
	s_nop 0
	v_fma_f32 v148, -v102, v103, 1.0
	v_fmac_f32_e32 v103, v148, v103
	v_div_scale_f32 v148, vcc, 1.0, v99, 1.0
	v_mul_f32_e32 v149, v148, v103
	v_fma_f32 v151, -v102, v149, v148
	v_fmac_f32_e32 v149, v151, v103
	v_fma_f32 v102, -v102, v149, v148
	v_div_fmas_f32 v102, v102, v103, v149
	v_div_fixup_f32 v99, v102, v99, 1.0
	v_div_scale_f32 v102, s[2:3], v98, v98, 1.0
	v_rcp_f32_e32 v103, v102
	s_nop 0
	v_fma_f32 v148, -v102, v103, 1.0
	v_fmac_f32_e32 v103, v148, v103
	v_div_scale_f32 v148, vcc, 1.0, v98, 1.0
	v_mul_f32_e32 v149, v148, v103
	v_fma_f32 v151, -v102, v149, v148
	v_fmac_f32_e32 v149, v151, v103
	v_fma_f32 v102, -v102, v149, v148
	v_div_fmas_f32 v102, v102, v103, v149
	v_div_fixup_f32 v98, v102, v98, 1.0
	v_div_scale_f32 v102, s[2:3], v105, v105, 1.0
	v_rcp_f32_e32 v103, v102
	s_waitcnt vmcnt(11)
; #define NTL(p) __builtin_nontemporal_load((const f32x4*)(p))
; #define NTS(v, p) __builtin_nontemporal_store((v), (f32x4*)(p))
; __device__ __forceinline__ float bf_lo(unsigned w) { return __uint_as_float(w << 16); }
; __device__ __forceinline__ float bf_hi(unsigned w) { return __uint_as_float(w & 0xffff0000u); }
; __device__ __forceinline__ float sigmoidf_(float x) { return 1.0f / (1.0f + __expf(-x)); }
;     __device__ __forceinline__ void operator()(AccT& acc, const Unit& u, int wr, int wc, int fr, int fq) const {
;     ...
;         for (int r = 0; r < 8; ++r) { const int ai = r >> 2, m = r & 3; const int row = row0 + ai * 128 + m * 16;
;             if (r < 7) { const int rn = row0 + ((r + 1) >> 2) * 128 + ((r + 1) & 3) * 16; const float* hn = H + (size_t)rn * DM + col0; const bf16_t* pn = ppbase + (((r + 1) >> 2) * 128 + ((r + 1) & 3) * 16) * 256;
;                 hv[(r + 1) & 1][0] = NTL(hn); hv[(r + 1) & 1][1] = NTL(hn + 4); hv[(r + 1) & 1][2] = NTL(hn + 128); hv[(r + 1) & 1][3] = NTL(hn + 132);
;                 pv[(r + 1) & 1][0] = *(const u32x4*)pn; pv[(r + 1) & 1][1] = *(const u32x4*)(pn + 128); rs[(r + 1) & 1] = rss2[rn]; }
;             float* hp = H + (size_t)row * DM + col0; float ss = 0.f; const float rstd = rsqrtf(rs[r & 1] * (1.0f / DM) + 1e-6f);
; #pragma unroll
;             for (int bj = 0; bj < 2; ++bj) { const u32x4 pw = pv[r & 1][bj];
;                 const f32x4 b0 = *(const f32x4*)(bias + col0 + bj * 128), b1 = *(const f32x4*)(bias + col0 + bj * 128 + 4);
;                 const f32x4 p0 = (f32x4){bf_lo(pw.x), bf_hi(pw.x), bf_lo(pw.y), bf_hi(pw.y)}, p1 = (f32x4){bf_lo(pw.z), bf_hi(pw.z), bf_lo(pw.w), bf_hi(pw.w)};
;                 f32x4 g0 = acc[ai][bj][m][0] * rstd + b0, g1 = acc[ai][bj][m][1] * rstd + b1;
; #pragma unroll
;                 for (int j = 0; j < 4; ++j) { g0[j] = sigmoidf_(g0[j]); g1[j] = sigmoidf_(g1[j]); }
;                 const f32x4 v0 = hv[r & 1][2 * bj] + p0 * g0, v1 = hv[r & 1][2 * bj + 1] + p1 * g1;
;                 NTS(v0, hp + bj * 128); NTS(v1, hp + bj * 128 + 4);
; #pragma unroll
;                 for (int j = 0; j < 4; ++j) ss += v0[j] * v0[j] + v1[j] * v1[j]; }
;             ss += __shfl_xor(ss, 16); ss += __shfl_xor(ss, 32);
;             if (fq == 0) unsafeAtomicAdd(rss3 + row, ss); __builtin_amdgcn_sched_barrier(0); }
	v_pk_fma_f32 v[98:99], v[98:99], v[126:127], v[138:139]
	v_fma_f32 v148, -v102, v103, 1.0
	v_fmac_f32_e32 v103, v148, v103
	v_div_scale_f32 v148, vcc, 1.0, v105, 1.0
	v_mul_f32_e32 v149, v148, v103
	v_fma_f32 v151, -v102, v149, v148
	v_fmac_f32_e32 v149, v151, v103
	v_fma_f32 v102, -v102, v149, v148
	v_div_fmas_f32 v102, v102, v103, v149
	v_div_fixup_f32 v103, v102, v105, 1.0
	v_div_scale_f32 v102, s[2:3], v104, v104, 1.0
	v_rcp_f32_e32 v105, v102
	s_nop 0
	v_fma_f32 v148, -v102, v105, 1.0
	v_fmac_f32_e32 v105, v148, v105
	v_div_scale_f32 v148, vcc, 1.0, v104, 1.0
	v_mul_f32_e32 v149, v148, v105
	v_fma_f32 v151, -v102, v149, v148
	v_fmac_f32_e32 v149, v151, v105
	v_fma_f32 v102, -v102, v149, v148
	v_div_fmas_f32 v102, v102, v105, v149
	v_div_fixup_f32 v102, v102, v104, 1.0
	v_pk_add_f32 v[104:105], v[146:147], 1.0 op_sel_hi:[1,0]
	s_nop 0
	v_div_scale_f32 v146, s[2:3], v105, v105, 1.0
	v_rcp_f32_e32 v147, v146
	s_nop 0
	v_fma_f32 v148, -v146, v147, 1.0
	v_fmac_f32_e32 v147, v148, v147
	v_div_scale_f32 v148, vcc, 1.0, v105, 1.0
	v_mul_f32_e32 v149, v148, v147
	v_fma_f32 v151, -v146, v149, v148
	v_fmac_f32_e32 v149, v151, v147
	v_fma_f32 v146, -v146, v149, v148
	v_div_fmas_f32 v146, v146, v147, v149
	v_div_fixup_f32 v147, v146, v105, 1.0
	v_div_scale_f32 v105, s[2:3], v104, v104, 1.0
	v_rcp_f32_e32 v146, v105
	s_nop 0
	v_fma_f32 v148, -v105, v146, 1.0
	v_fmac_f32_e32 v146, v148, v146
	v_div_scale_f32 v148, vcc, 1.0, v104, 1.0
	v_mul_f32_e32 v149, v148, v146
	v_fma_f32 v151, -v105, v149, v148
	v_fmac_f32_e32 v149, v151, v146
	v_fma_f32 v105, -v105, v149, v148
	v_div_fmas_f32 v105, v105, v146, v149
	v_div_fixup_f32 v146, v105, v104, 1.0
	v_div_scale_f32 v104, s[2:3], v101, v101, 1.0
	v_rcp_f32_e32 v105, v104
	s_nop 0
	v_fma_f32 v148, -v104, v105, 1.0
	v_fmac_f32_e32 v105, v148, v105
	v_div_scale_f32 v148, vcc, 1.0, v101, 1.0
	v_mul_f32_e32 v149, v148, v105
	v_fma_f32 v151, -v104, v149, v148
	v_fmac_f32_e32 v149, v151, v105
	v_fma_f32 v104, -v104, v149, v148
	v_div_fmas_f32 v104, v104, v105, v149
	v_div_fixup_f32 v105, v104, v101, 1.0
	v_div_scale_f32 v101, s[2:3], v100, v100, 1.0
	v_rcp_f32_e32 v104, v101
	s_nop 0
	v_fma_f32 v148, -v101, v104, 1.0
	v_fmac_f32_e32 v104, v148, v104
	v_div_scale_f32 v148, vcc, 1.0, v100, 1.0
	v_mul_f32_e32 v149, v148, v104
	v_fma_f32 v151, -v101, v149, v148
	v_fmac_f32_e32 v149, v151, v104
	v_fma_f32 v101, -v101, v149, v148
	v_div_fmas_f32 v101, v101, v104, v149
	v_div_fixup_f32 v104, v101, v100, 1.0
	v_pk_fma_f32 v[100:101], v[102:103], v[128:129], v[140:141]
	v_pk_fma_f32 v[102:103], v[146:147], v[118:119], v[130:131]
	v_pk_fma_f32 v[104:105], v[104:105], v[120:121], v[132:133]
	global_store_dwordx4 v[200:201], v[98:101], off offset:512 nt
	global_store_dwordx4 v[200:201], v[102:105], off offset:528 nt
	s_nop 1
	v_mul_f32_e32 v102, v102, v102
	v_fmac_f32_e32 v102, v98, v98
	v_add_f32_e32 v98, v150, v102
	v_mul_f32_e32 v102, v103, v103
	v_fmac_f32_e32 v102, v99, v99
	v_mul_f32_e32 v99, v104, v104
	v_add_f32_e32 v98, v102, v98
	v_fmac_f32_e32 v99, v100, v100
	v_add_f32_e32 v98, v99, v98
	v_mul_f32_e32 v99, v105, v105
	v_fmac_f32_e32 v99, v101, v101
	v_add_f32_e32 v98, v99, v98
	ds_bpermute_b32 v99, v225, v98
	s_waitcnt lgkmcnt(0)
	v_add_f32_e32 v98, v98, v99
	ds_bpermute_b32 v99, v226, v98
	s_and_saveexec_b64 s[2:3], s[42:43]
	s_cbranch_execz .LBB0_785
	v_lshl_add_u64 v[100:101], v[198:199], 2, s[36:37]
	s_waitcnt lgkmcnt(0)
	v_add_f32_e32 v98, v98, v99
	global_atomic_add_f32 v[100:101], v98, off
.LBB0_785:
	s_or_b64 exec, exec, s[2:3]
	v_add_u32_e32 v146, 48, v186
	v_ashrrev_i32_e32 v147, 31, v146
	s_waitcnt lgkmcnt(0)
	v_lshlrev_b64 v[98:99], 12, v[146:147]
	v_lshl_add_u64 v[98:99], s[22:23], 0, v[98:99]
	v_add_co_u32_e32 v118, vcc, 0x6000, v190
	v_lshl_add_u64 v[148:149], v[192:193], 2, v[98:99]
	s_nop 0
	v_addc_co_u32_e32 v119, vcc, 0, v191, vcc
	global_load_dwordx4 v[126:129], v[148:149], off offset:16 nt
	global_load_dwordx4 v[130:133], v[148:149], off nt
	global_load_dwordx4 v[98:101], v[148:149], off offset:528 nt
	global_load_dwordx4 v[102:105], v[148:149], off offset:512 nt
	global_load_dwordx4 v[138:141], v[118:119], off
	s_nop 0
	global_load_dwordx4 v[118:121], v[118:119], off offset:256
	s_nop 0
	global_load_dword v151, v[188:189], off offset:192
	s_waitcnt vmcnt(11)
; #define NTL(p) __builtin_nontemporal_load((const f32x4*)(p))
; #define NTS(v, p) __builtin_nontemporal_store((v), (f32x4*)(p))
; __device__ __forceinline__ float bf_lo(unsigned w) { return __uint_as_float(w << 16); }
; __device__ __forceinline__ float bf_hi(unsigned w) { return __uint_as_float(w & 0xffff0000u); }
; __device__ __forceinline__ float sigmoidf_(float x) { return 1.0f / (1.0f + __expf(-x)); }
;     __device__ __forceinline__ void operator()(AccT& acc, const Unit& u, int wr, int wc, int fr, int fq) const {
;     ...
;         for (int r = 0; r < 8; ++r) { const int ai = r >> 2, m = r & 3; const int row = row0 + ai * 128 + m * 16;
;             if (r < 7) { const int rn = row0 + ((r + 1) >> 2) * 128 + ((r + 1) & 3) * 16; const float* hn = H + (size_t)rn * DM + col0; const bf16_t* pn = ppbase + (((r + 1) >> 2) * 128 + ((r + 1) & 3) * 16) * 256;
;                 hv[(r + 1) & 1][0] = NTL(hn); hv[(r + 1) & 1][1] = NTL(hn + 4); hv[(r + 1) & 1][2] = NTL(hn + 128); hv[(r + 1) & 1][3] = NTL(hn + 132);
;                 pv[(r + 1) & 1][0] = *(const u32x4*)pn; pv[(r + 1) & 1][1] = *(const u32x4*)(pn + 128); rs[(r + 1) & 1] = rss2[rn]; }
;             float* hp = H + (size_t)row * DM + col0; float ss = 0.f; const float rstd = rsqrtf(rs[r & 1] * (1.0f / DM) + 1e-6f);
; #pragma unroll
;             for (int bj = 0; bj < 2; ++bj) { const u32x4 pw = pv[r & 1][bj];
;                 const f32x4 b0 = *(const f32x4*)(bias + col0 + bj * 128), b1 = *(const f32x4*)(bias + col0 + bj * 128 + 4);
;                 const f32x4 p0 = (f32x4){bf_lo(pw.x), bf_hi(pw.x), bf_lo(pw.y), bf_hi(pw.y)}, p1 = (f32x4){bf_lo(pw.z), bf_hi(pw.z), bf_lo(pw.w), bf_hi(pw.w)};
;                 f32x4 g0 = acc[ai][bj][m][0] * rstd + b0, g1 = acc[ai][bj][m][1] * rstd + b1;
; #pragma unroll
;                 for (int j = 0; j < 4; ++j) { g0[j] = sigmoidf_(g0[j]); g1[j] = sigmoidf_(g1[j]); }
;                 const f32x4 v0 = hv[r & 1][2 * bj] + p0 * g0, v1 = hv[r & 1][2 * bj + 1] + p1 * g1;
;                 NTS(v0, hp + bj * 128); NTS(v1, hp + bj * 128 + 4);
	v_fmamk_f32 v150, v164, 0x3a800000, v210
	v_cmp_gt_f32_e32 vcc, s30, v150
	v_mul_f32_e32 v152, 0x4b800000, v150
	v_and_b32_e32 v153, 0xffff0000, v142
	v_cndmask_b32_e32 v150, v150, v152, vcc
	v_rsq_f32_e32 v150, v150
	v_lshlrev_b32_e32 v154, 16, v143
	v_and_b32_e32 v155, 0xffff0000, v143
	v_and_b32_e32 v143, 0xffff0000, v144
	v_mul_f32_e32 v152, 0x45800000, v150
	v_cndmask_b32_e32 v150, v150, v152, vcc
	v_lshlrev_b32_e32 v152, 16, v142
	v_lshlrev_b32_e32 v142, 16, v144
	v_lshlrev_b32_e32 v144, 16, v145
	v_and_b32_e32 v145, 0xffff0000, v145
	v_pk_fma_f32 v[90:91], v[90:91], v[150:151], v[244:245] op_sel_hi:[1,0,1]
	v_pk_fma_f32 v[94:95], v[94:95], v[150:151], v[240:241] op_sel_hi:[1,0,1]
	v_mul_f32_e32 v90, 0xbfb8aa3b, v90
	v_mul_f32_e32 v94, 0xbfb8aa3b, v94
	v_pk_fma_f32 v[92:93], v[92:93], v[150:151], v[246:247] op_sel_hi:[1,0,1]
	v_exp_f32_e32 v156, v94
	v_exp_f32_e32 v94, v90
	v_mul_f32_e32 v90, 0xbfb8aa3b, v95
	v_pk_fma_f32 v[96:97], v[96:97], v[150:151], v[242:243] op_sel_hi:[1,0,1]
	v_exp_f32_e32 v157, v90
	v_mul_f32_e32 v90, 0xbfb8aa3b, v91
	v_mul_f32_e32 v91, 0xbfb8aa3b, v92
	v_exp_f32_e32 v95, v90
	v_mul_f32_e32 v90, 0xbfb8aa3b, v96
	v_exp_f32_e32 v92, v91
	v_mul_f32_e32 v91, 0xbfb8aa3b, v97
	v_exp_f32_e32 v90, v90
	v_exp_f32_e32 v91, v91
	v_pk_add_f32 v[94:95], v[94:95], 1.0 op_sel_hi:[1,0]
	v_mul_f32_e32 v93, 0xbfb8aa3b, v93
	v_exp_f32_e32 v93, v93
	v_pk_add_f32 v[96:97], v[90:91], 1.0 op_sel_hi:[1,0]
	v_pk_add_f32 v[90:91], v[156:157], 1.0 op_sel_hi:[1,0]
	v_pk_add_f32 v[92:93], v[92:93], 1.0 op_sel_hi:[1,0]
	v_div_scale_f32 v156, s[2:3], v91, v91, 1.0
	v_rcp_f32_e32 v157, v156
	s_nop 0
	v_fma_f32 v158, -v156, v157, 1.0
	v_fmac_f32_e32 v157, v158, v157
	v_div_scale_f32 v158, vcc, 1.0, v91, 1.0
	v_mul_f32_e32 v159, v158, v157
	v_fma_f32 v160, -v156, v159, v158
	v_fmac_f32_e32 v159, v160, v157
	v_fma_f32 v156, -v156, v159, v158
	v_div_fmas_f32 v156, v156, v157, v159
	v_div_fixup_f32 v91, v156, v91, 1.0
	v_div_scale_f32 v156, s[2:3], v90, v90, 1.0
	v_rcp_f32_e32 v157, v156
	s_nop 0
	v_fma_f32 v158, -v156, v157, 1.0
	v_fmac_f32_e32 v157, v158, v157
	v_div_scale_f32 v158, vcc, 1.0, v90, 1.0
	v_mul_f32_e32 v159, v158, v157
	v_fma_f32 v160, -v156, v159, v158
	v_fmac_f32_e32 v159, v160, v157
	v_fma_f32 v156, -v156, v159, v158
	v_div_fmas_f32 v156, v156, v157, v159
	v_div_fixup_f32 v90, v156, v90, 1.0
	v_div_scale_f32 v156, s[2:3], v97, v97, 1.0
	v_rcp_f32_e32 v157, v156
	v_pk_fma_f32 v[90:91], v[90:91], v[152:153], v[134:135]
	v_fma_f32 v158, -v156, v157, 1.0
	v_fmac_f32_e32 v157, v158, v157
	v_div_scale_f32 v158, vcc, 1.0, v97, 1.0
	v_mul_f32_e32 v159, v158, v157
	v_fma_f32 v160, -v156, v159, v158
	v_fmac_f32_e32 v159, v160, v157
	v_fma_f32 v156, -v156, v159, v158
	v_div_fmas_f32 v156, v156, v157, v159
	v_div_fixup_f32 v97, v156, v97, 1.0
	v_div_scale_f32 v156, s[2:3], v96, v96, 1.0
	v_rcp_f32_e32 v157, v156
	s_nop 0
	v_fma_f32 v158, -v156, v157, 1.0
	v_fmac_f32_e32 v157, v158, v157
	v_div_scale_f32 v158, vcc, 1.0, v96, 1.0
	v_mul_f32_e32 v159, v158, v157
	v_fma_f32 v160, -v156, v159, v158
	v_fmac_f32_e32 v159, v160, v157
	v_fma_f32 v156, -v156, v159, v158
	v_div_fmas_f32 v156, v156, v157, v159
	v_div_fixup_f32 v96, v156, v96, 1.0
	v_div_scale_f32 v156, s[2:3], v95, v95, 1.0
	v_rcp_f32_e32 v157, v156
	s_nop 0
	v_fma_f32 v158, -v156, v157, 1.0
	v_fmac_f32_e32 v157, v158, v157
	v_div_scale_f32 v158, vcc, 1.0, v95, 1.0
	v_mul_f32_e32 v159, v158, v157
	v_fma_f32 v160, -v156, v159, v158
	v_fmac_f32_e32 v159, v160, v157
	v_fma_f32 v156, -v156, v159, v158
	v_div_fmas_f32 v156, v156, v157, v159
	v_div_fixup_f32 v95, v156, v95, 1.0
	v_div_scale_f32 v156, s[2:3], v94, v94, 1.0
	v_rcp_f32_e32 v157, v156
	s_nop 0
	v_fma_f32 v158, -v156, v157, 1.0
	v_fmac_f32_e32 v157, v158, v157
	v_div_scale_f32 v158, vcc, 1.0, v94, 1.0
	v_mul_f32_e32 v159, v158, v157
	v_fma_f32 v160, -v156, v159, v158
	v_fmac_f32_e32 v159, v160, v157
	v_fma_f32 v156, -v156, v159, v158
	v_div_fmas_f32 v156, v156, v157, v159
	v_div_fixup_f32 v94, v156, v94, 1.0
	v_div_scale_f32 v156, s[2:3], v93, v93, 1.0
	v_rcp_f32_e32 v157, v156
	v_pk_fma_f32 v[94:95], v[94:95], v[142:143], v[122:123]
	v_fma_f32 v158, -v156, v157, 1.0
	v_fmac_f32_e32 v157, v158, v157
	v_div_scale_f32 v158, vcc, 1.0, v93, 1.0
	v_mul_f32_e32 v159, v158, v157
	v_fma_f32 v160, -v156, v159, v158
	v_fmac_f32_e32 v159, v160, v157
	v_fma_f32 v156, -v156, v159, v158
	v_div_fmas_f32 v156, v156, v157, v159
	v_div_fixup_f32 v157, v156, v93, 1.0
	v_div_scale_f32 v93, s[2:3], v92, v92, 1.0
	v_rcp_f32_e32 v156, v93
	s_nop 0
	v_fma_f32 v158, -v93, v156, 1.0
	v_fmac_f32_e32 v156, v158, v156
	v_div_scale_f32 v158, vcc, 1.0, v92, 1.0
	v_mul_f32_e32 v159, v158, v156
	v_fma_f32 v160, -v93, v159, v158
	v_fmac_f32_e32 v159, v160, v156
	v_fma_f32 v93, -v93, v159, v158
	v_div_fmas_f32 v93, v93, v156, v159
	v_div_fixup_f32 v156, v93, v92, 1.0
	v_pk_fma_f32 v[92:93], v[96:97], v[154:155], v[136:137]
	v_pk_fma_f32 v[96:97], v[156:157], v[144:145], v[124:125]
	global_store_dwordx4 v[196:197], v[90:93], off nt
	global_store_dwordx4 v[196:197], v[94:97], off offset:16 nt
	s_nop 0
	s_nop 0
	v_mul_f32_e32 v94, v94, v94
	v_fmac_f32_e32 v94, v90, v90
	v_mul_f32_e32 v90, v95, v95
	v_fmac_f32_e32 v90, v91, v91
	v_add_f32_e32 v90, v94, v90
	v_mul_f32_e32 v91, v96, v96
	v_lshlrev_b32_e32 v94, 16, v114
	v_and_b32_e32 v95, 0xffff0000, v114
	v_fmac_f32_e32 v91, v92, v92
	v_add_f32_e32 v90, v91, v90
	v_mul_f32_e32 v91, v97, v97
	v_lshlrev_b32_e32 v96, 16, v115
	v_and_b32_e32 v97, 0xffff0000, v115
	v_fmac_f32_e32 v91, v93, v93
	v_add_f32_e32 v122, v91, v90
	v_lshlrev_b32_e32 v90, 16, v116
	v_and_b32_e32 v91, 0xffff0000, v116
	v_lshlrev_b32_e32 v92, 16, v117
; #define NTL(p) __builtin_nontemporal_load((const f32x4*)(p))
; #define NTS(v, p) __builtin_nontemporal_store((v), (f32x4*)(p))
; __device__ __forceinline__ float bf_lo(unsigned w) { return __uint_as_float(w << 16); }
; __device__ __forceinline__ float bf_hi(unsigned w) { return __uint_as_float(w & 0xffff0000u); }
; __device__ __forceinline__ float sigmoidf_(float x) { return 1.0f / (1.0f + __expf(-x)); }
;     __device__ __forceinline__ void operator()(AccT& acc, const Unit& u, int wr, int wc, int fr, int fq) const {
;     ...
;         for (int r = 0; r < 8; ++r) { const int ai = r >> 2, m = r & 3; const int row = row0 + ai * 128 + m * 16;
;             if (r < 7) { const int rn = row0 + ((r + 1) >> 2) * 128 + ((r + 1) & 3) * 16; const float* hn = H + (size_t)rn * DM + col0; const bf16_t* pn = ppbase + (((r + 1) >> 2) * 128 + ((r + 1) & 3) * 16) * 256;
;                 hv[(r + 1) & 1][0] = NTL(hn); hv[(r + 1) & 1][1] = NTL(hn + 4); hv[(r + 1) & 1][2] = NTL(hn + 128); hv[(r + 1) & 1][3] = NTL(hn + 132);
;                 pv[(r + 1) & 1][0] = *(const u32x4*)pn; pv[(r + 1) & 1][1] = *(const u32x4*)(pn + 128); rs[(r + 1) & 1] = rss2[rn]; }
;             float* hp = H + (size_t)row * DM + col0; float ss = 0.f; const float rstd = rsqrtf(rs[r & 1] * (1.0f / DM) + 1e-6f);
; #pragma unroll
;             for (int bj = 0; bj < 2; ++bj) { const u32x4 pw = pv[r & 1][bj];
;                 const f32x4 b0 = *(const f32x4*)(bias + col0 + bj * 128), b1 = *(const f32x4*)(bias + col0 + bj * 128 + 4);
;                 const f32x4 p0 = (f32x4){bf_lo(pw.x), bf_hi(pw.x), bf_lo(pw.y), bf_hi(pw.y)}, p1 = (f32x4){bf_lo(pw.z), bf_hi(pw.z), bf_lo(pw.w), bf_hi(pw.w)};
;                 f32x4 g0 = acc[ai][bj][m][0] * rstd + b0, g1 = acc[ai][bj][m][1] * rstd + b1;
; #pragma unroll
;                 for (int j = 0; j < 4; ++j) { g0[j] = sigmoidf_(g0[j]); g1[j] = sigmoidf_(g1[j]); }
;                 const f32x4 v0 = hv[r & 1][2 * bj] + p0 * g0, v1 = hv[r & 1][2 * bj + 1] + p1 * g1;
;                 NTS(v0, hp + bj * 128); NTS(v1, hp + bj * 128 + 4);
; #pragma unroll
;                 for (int j = 0; j < 4; ++j) ss += v0[j] * v0[j] + v1[j] * v1[j]; }
;             ss += __shfl_xor(ss, 16); ss += __shfl_xor(ss, 32);
;             if (fq == 0) unsafeAtomicAdd(rss3 + row, ss); __builtin_amdgcn_sched_barrier(0); }
	v_and_b32_e32 v93, 0xffff0000, v117
	v_pk_fma_f32 v[82:83], v[82:83], v[150:151], v[232:233] op_sel_hi:[1,0,1]
	v_pk_fma_f32 v[86:87], v[86:87], v[150:151], v[248:249] op_sel_hi:[1,0,1]
	v_mul_f32_e32 v82, 0xbfb8aa3b, v82
	v_pk_fma_f32 v[84:85], v[84:85], v[150:151], v[234:235] op_sel_hi:[1,0,1]
	v_exp_f32_e32 v114, v82
	v_mul_f32_e32 v82, 0xbfb8aa3b, v87
	v_pk_fma_f32 v[88:89], v[88:89], v[150:151], v[250:251] op_sel_hi:[1,0,1]
	v_exp_f32_e32 v87, v82
	v_mul_f32_e32 v82, 0xbfb8aa3b, v83
	v_mul_f32_e32 v83, 0xbfb8aa3b, v84
	v_mul_f32_e32 v86, 0xbfb8aa3b, v86
	v_exp_f32_e32 v115, v82
	v_mul_f32_e32 v82, 0xbfb8aa3b, v88
	v_exp_f32_e32 v84, v83
	v_mul_f32_e32 v83, 0xbfb8aa3b, v89
	v_exp_f32_e32 v86, v86
	v_exp_f32_e32 v82, v82
	v_exp_f32_e32 v83, v83
	v_mul_f32_e32 v85, 0xbfb8aa3b, v85
	v_exp_f32_e32 v85, v85
	v_pk_add_f32 v[88:89], v[82:83], 1.0 op_sel_hi:[1,0]
	v_pk_add_f32 v[82:83], v[86:87], 1.0 op_sel_hi:[1,0]
	v_pk_add_f32 v[84:85], v[84:85], 1.0 op_sel_hi:[1,0]
	v_div_scale_f32 v86, s[2:3], v83, v83, 1.0
	v_rcp_f32_e32 v87, v86
	s_nop 0
	v_fma_f32 v116, -v86, v87, 1.0
	v_fmac_f32_e32 v87, v116, v87
	v_div_scale_f32 v116, vcc, 1.0, v83, 1.0
	v_mul_f32_e32 v117, v116, v87
	v_fma_f32 v123, -v86, v117, v116
	v_fmac_f32_e32 v117, v123, v87
	v_fma_f32 v86, -v86, v117, v116
	v_div_fmas_f32 v86, v86, v87, v117
	v_div_fixup_f32 v83, v86, v83, 1.0
	v_div_scale_f32 v86, s[2:3], v82, v82, 1.0
	v_rcp_f32_e32 v87, v86
	s_nop 0
	v_fma_f32 v116, -v86, v87, 1.0
	v_fmac_f32_e32 v87, v116, v87
	v_div_scale_f32 v116, vcc, 1.0, v82, 1.0
	v_mul_f32_e32 v117, v116, v87
	v_fma_f32 v123, -v86, v117, v116
	v_fmac_f32_e32 v117, v123, v87
	v_fma_f32 v86, -v86, v117, v116
	v_div_fmas_f32 v86, v86, v87, v117
	v_div_fixup_f32 v82, v86, v82, 1.0
	v_div_scale_f32 v86, s[2:3], v89, v89, 1.0
	v_rcp_f32_e32 v87, v86
	v_pk_fma_f32 v[82:83], v[82:83], v[94:95], v[110:111]
	v_fma_f32 v116, -v86, v87, 1.0
	v_fmac_f32_e32 v87, v116, v87
	v_div_scale_f32 v116, vcc, 1.0, v89, 1.0
	v_mul_f32_e32 v117, v116, v87
	v_fma_f32 v123, -v86, v117, v116
	v_fmac_f32_e32 v117, v123, v87
	v_fma_f32 v86, -v86, v117, v116
	v_div_fmas_f32 v86, v86, v87, v117
	v_div_fixup_f32 v87, v86, v89, 1.0
	v_div_scale_f32 v86, s[2:3], v88, v88, 1.0
	v_rcp_f32_e32 v89, v86
	s_nop 0
	v_fma_f32 v116, -v86, v89, 1.0
	v_fmac_f32_e32 v89, v116, v89
	v_div_scale_f32 v116, vcc, 1.0, v88, 1.0
	v_mul_f32_e32 v117, v116, v89
	v_fma_f32 v123, -v86, v117, v116
	v_fmac_f32_e32 v117, v123, v89
	v_fma_f32 v86, -v86, v117, v116
	v_div_fmas_f32 v86, v86, v89, v117
	v_div_fixup_f32 v86, v86, v88, 1.0
	v_pk_add_f32 v[88:89], v[114:115], 1.0 op_sel_hi:[1,0]
	s_nop 0
	v_div_scale_f32 v114, s[2:3], v89, v89, 1.0
	v_rcp_f32_e32 v115, v114
	s_nop 0
	v_fma_f32 v116, -v114, v115, 1.0
	v_fmac_f32_e32 v115, v116, v115
	v_div_scale_f32 v116, vcc, 1.0, v89, 1.0
	v_mul_f32_e32 v117, v116, v115
	v_fma_f32 v123, -v114, v117, v116
	v_fmac_f32_e32 v117, v123, v115
	v_fma_f32 v114, -v114, v117, v116
	v_div_fmas_f32 v114, v114, v115, v117
	v_div_fixup_f32 v115, v114, v89, 1.0
	v_div_scale_f32 v89, s[2:3], v88, v88, 1.0
	v_rcp_f32_e32 v114, v89
	s_nop 0
	v_fma_f32 v116, -v89, v114, 1.0
	v_fmac_f32_e32 v114, v116, v114
	v_div_scale_f32 v116, vcc, 1.0, v88, 1.0
	v_mul_f32_e32 v117, v116, v114
	v_fma_f32 v123, -v89, v117, v116
	v_fmac_f32_e32 v117, v123, v114
	v_fma_f32 v89, -v89, v117, v116
	v_div_fmas_f32 v89, v89, v114, v117
	v_div_fixup_f32 v114, v89, v88, 1.0
	v_div_scale_f32 v88, s[2:3], v85, v85, 1.0
	v_rcp_f32_e32 v89, v88
	s_nop 0
	v_fma_f32 v116, -v88, v89, 1.0
	v_fmac_f32_e32 v89, v116, v89
	v_div_scale_f32 v116, vcc, 1.0, v85, 1.0
	v_mul_f32_e32 v117, v116, v89
	v_fma_f32 v123, -v88, v117, v116
	v_fmac_f32_e32 v117, v123, v89
	v_fma_f32 v88, -v88, v117, v116
	v_div_fmas_f32 v88, v88, v89, v117
	v_div_fixup_f32 v89, v88, v85, 1.0
	v_div_scale_f32 v85, s[2:3], v84, v84, 1.0
	v_rcp_f32_e32 v88, v85
	s_nop 0
	v_fma_f32 v116, -v85, v88, 1.0
	v_fmac_f32_e32 v88, v116, v88
	v_div_scale_f32 v116, vcc, 1.0, v84, 1.0
	v_mul_f32_e32 v117, v116, v88
	v_fma_f32 v123, -v85, v117, v116
	v_fmac_f32_e32 v117, v123, v88
	v_fma_f32 v85, -v85, v117, v116
	v_div_fmas_f32 v85, v85, v88, v117
	v_div_fixup_f32 v88, v85, v84, 1.0
	v_pk_fma_f32 v[84:85], v[86:87], v[96:97], v[112:113]
	v_pk_fma_f32 v[86:87], v[114:115], v[90:91], v[106:107]
	v_pk_fma_f32 v[88:89], v[88:89], v[92:93], v[108:109]
	global_store_dwordx4 v[196:197], v[82:85], off offset:512 nt
	global_store_dwordx4 v[196:197], v[86:89], off offset:528 nt
	s_nop 1
	v_mul_f32_e32 v86, v86, v86
	v_fmac_f32_e32 v86, v82, v82
	v_add_f32_e32 v82, v122, v86
	v_mul_f32_e32 v86, v87, v87
	v_fmac_f32_e32 v86, v83, v83
	v_mul_f32_e32 v83, v88, v88
	v_add_f32_e32 v82, v86, v82
	v_fmac_f32_e32 v83, v84, v84
	v_add_f32_e32 v82, v83, v82
	v_mul_f32_e32 v83, v89, v89
	v_fmac_f32_e32 v83, v85, v85
	v_add_f32_e32 v82, v83, v82
	ds_bpermute_b32 v83, v225, v82
	s_waitcnt lgkmcnt(0)
	v_add_f32_e32 v82, v82, v83
	ds_bpermute_b32 v83, v226, v82
	s_and_saveexec_b64 s[2:3], s[42:43]
	s_cbranch_execz .LBB0_787
	v_lshl_add_u64 v[84:85], v[194:195], 2, s[36:37]
	s_waitcnt lgkmcnt(0)
	v_add_f32_e32 v82, v82, v83
	global_atomic_add_f32 v[84:85], v82, off
; #define NTL(p) __builtin_nontemporal_load((const f32x4*)(p))
; #define NTS(v, p) __builtin_nontemporal_store((v), (f32x4*)(p))
; __device__ __forceinline__ float bf_lo(unsigned w) { return __uint_as_float(w << 16); }
; __device__ __forceinline__ float bf_hi(unsigned w) { return __uint_as_float(w & 0xffff0000u); }
; __device__ __forceinline__ float sigmoidf_(float x) { return 1.0f / (1.0f + __expf(-x)); }
;     __device__ __forceinline__ void operator()(AccT& acc, const Unit& u, int wr, int wc, int fr, int fq) const {
;     ...
;         for (int r = 0; r < 8; ++r) { const int ai = r >> 2, m = r & 3; const int row = row0 + ai * 128 + m * 16;
;             if (r < 7) { const int rn = row0 + ((r + 1) >> 2) * 128 + ((r + 1) & 3) * 16; const float* hn = H + (size_t)rn * DM + col0; const bf16_t* pn = ppbase + (((r + 1) >> 2) * 128 + ((r + 1) & 3) * 16) * 256;
;                 hv[(r + 1) & 1][0] = NTL(hn); hv[(r + 1) & 1][1] = NTL(hn + 4); hv[(r + 1) & 1][2] = NTL(hn + 128); hv[(r + 1) & 1][3] = NTL(hn + 132);
;                 pv[(r + 1) & 1][0] = *(const u32x4*)pn; pv[(r + 1) & 1][1] = *(const u32x4*)(pn + 128); rs[(r + 1) & 1] = rss2[rn]; }
;             float* hp = H + (size_t)row * DM + col0; float ss = 0.f; const float rstd = rsqrtf(rs[r & 1] * (1.0f / DM) + 1e-6f);
; #pragma unroll
;             for (int bj = 0; bj < 2; ++bj) { const u32x4 pw = pv[r & 1][bj];
;                 const f32x4 b0 = *(const f32x4*)(bias + col0 + bj * 128), b1 = *(const f32x4*)(bias + col0 + bj * 128 + 4);
;                 const f32x4 p0 = (f32x4){bf_lo(pw.x), bf_hi(pw.x), bf_lo(pw.y), bf_hi(pw.y)}, p1 = (f32x4){bf_lo(pw.z), bf_hi(pw.z), bf_lo(pw.w), bf_hi(pw.w)};
;                 f32x4 g0 = acc[ai][bj][m][0] * rstd + b0, g1 = acc[ai][bj][m][1] * rstd + b1;
; #pragma unroll
;                 for (int j = 0; j < 4; ++j) { g0[j] = sigmoidf_(g0[j]); g1[j] = sigmoidf_(g1[j]); }
;                 const f32x4 v0 = hv[r & 1][2 * bj] + p0 * g0, v1 = hv[r & 1][2 * bj + 1] + p1 * g1;
;                 NTS(v0, hp + bj * 128); NTS(v1, hp + bj * 128 + 4);
.LBB0_787:
	s_or_b64 exec, exec, s[2:3]
	v_add_u32_e32 v114, 0x80, v186
	v_ashrrev_i32_e32 v115, 31, v114
	s_waitcnt lgkmcnt(0)
	v_lshlrev_b64 v[82:83], 12, v[114:115]
	v_lshl_add_u64 v[82:83], s[22:23], 0, v[82:83]
	v_add_co_u32_e32 v90, vcc, 0x10000, v190
	v_lshl_add_u64 v[122:123], v[192:193], 2, v[82:83]
	s_nop 0
	v_addc_co_u32_e32 v91, vcc, 0, v191, vcc
	global_load_dwordx4 v[94:97], v[122:123], off offset:16 nt
	global_load_dwordx4 v[106:109], v[122:123], off nt
	global_load_dwordx4 v[82:85], v[122:123], off offset:528 nt
	global_load_dwordx4 v[86:89], v[122:123], off offset:512 nt
	global_load_dwordx4 v[110:113], v[90:91], off
	s_nop 0
	global_load_dwordx4 v[90:93], v[90:91], off offset:256
	s_nop 0
	global_load_dword v142, v[188:189], off offset:512
	s_waitcnt vmcnt(11)
	v_fmamk_f32 v116, v151, 0x3a800000, v210
	v_cmp_gt_f32_e32 vcc, s30, v116
	v_mul_f32_e32 v117, 0x4b800000, v116
	v_lshlrev_b32_e32 v124, 16, v140
	v_cndmask_b32_e32 v116, v116, v117, vcc
	v_rsq_f32_e32 v116, v116
	v_and_b32_e32 v125, 0xffff0000, v140
	v_lshlrev_b32_e32 v134, 16, v141
	v_and_b32_e32 v135, 0xffff0000, v141
	v_mul_f32_e32 v117, 0x45800000, v116
	v_cndmask_b32_e32 v116, v116, v117, vcc
	v_lshlrev_b32_e32 v136, 16, v138
	v_and_b32_e32 v137, 0xffff0000, v138
	v_lshlrev_b32_e32 v138, 16, v139
	v_and_b32_e32 v139, 0xffff0000, v139
	v_pk_fma_f32 v[74:75], v[74:75], v[116:117], v[244:245] op_sel_hi:[1,0,1]
	v_pk_fma_f32 v[78:79], v[78:79], v[116:117], v[240:241] op_sel_hi:[1,0,1]
	v_mul_f32_e32 v74, 0xbfb8aa3b, v74
	v_mul_f32_e32 v78, 0xbfb8aa3b, v78
	v_pk_fma_f32 v[76:77], v[76:77], v[116:117], v[246:247] op_sel_hi:[1,0,1]
	v_exp_f32_e32 v140, v78
	v_exp_f32_e32 v78, v74
	v_mul_f32_e32 v74, 0xbfb8aa3b, v79
	v_pk_fma_f32 v[80:81], v[80:81], v[116:117], v[242:243] op_sel_hi:[1,0,1]
	v_exp_f32_e32 v141, v74
	v_mul_f32_e32 v74, 0xbfb8aa3b, v75
	v_mul_f32_e32 v75, 0xbfb8aa3b, v76
	v_exp_f32_e32 v79, v74
	v_mul_f32_e32 v74, 0xbfb8aa3b, v80
	v_exp_f32_e32 v76, v75
	v_mul_f32_e32 v75, 0xbfb8aa3b, v81
	v_exp_f32_e32 v74, v74
	v_exp_f32_e32 v75, v75
	v_pk_add_f32 v[78:79], v[78:79], 1.0 op_sel_hi:[1,0]
	v_mul_f32_e32 v77, 0xbfb8aa3b, v77
	v_exp_f32_e32 v77, v77
	v_pk_add_f32 v[80:81], v[74:75], 1.0 op_sel_hi:[1,0]
	v_pk_add_f32 v[74:75], v[140:141], 1.0 op_sel_hi:[1,0]
	v_pk_add_f32 v[76:77], v[76:77], 1.0 op_sel_hi:[1,0]
	v_div_scale_f32 v117, s[2:3], v75, v75, 1.0
	v_rcp_f32_e32 v140, v117
	s_nop 0
	v_fma_f32 v141, -v117, v140, 1.0
	v_fmac_f32_e32 v140, v141, v140
	v_div_scale_f32 v141, vcc, 1.0, v75, 1.0
	v_mul_f32_e32 v143, v141, v140
	v_fma_f32 v144, -v117, v143, v141
	v_fmac_f32_e32 v143, v144, v140
	v_fma_f32 v117, -v117, v143, v141
	v_div_fmas_f32 v117, v117, v140, v143
	v_div_fixup_f32 v75, v117, v75, 1.0
	v_div_scale_f32 v117, s[2:3], v74, v74, 1.0
	v_rcp_f32_e32 v140, v117
	s_nop 0
	v_fma_f32 v141, -v117, v140, 1.0
	v_fmac_f32_e32 v140, v141, v140
	v_div_scale_f32 v141, vcc, 1.0, v74, 1.0
	v_mul_f32_e32 v143, v141, v140
	v_fma_f32 v144, -v117, v143, v141
	v_fmac_f32_e32 v143, v144, v140
	v_fma_f32 v117, -v117, v143, v141
	v_div_fmas_f32 v117, v117, v140, v143
	v_div_fixup_f32 v74, v117, v74, 1.0
	v_div_scale_f32 v117, s[2:3], v81, v81, 1.0
	v_rcp_f32_e32 v140, v117
	v_pk_fma_f32 v[74:75], v[74:75], v[136:137], v[130:131]
	v_fma_f32 v141, -v117, v140, 1.0
	v_fmac_f32_e32 v140, v141, v140
	v_div_scale_f32 v141, vcc, 1.0, v81, 1.0
	v_mul_f32_e32 v143, v141, v140
	v_fma_f32 v144, -v117, v143, v141
	v_fmac_f32_e32 v143, v144, v140
	v_fma_f32 v117, -v117, v143, v141
	v_div_fmas_f32 v117, v117, v140, v143
	v_div_fixup_f32 v81, v117, v81, 1.0
	v_div_scale_f32 v117, s[2:3], v80, v80, 1.0
	v_rcp_f32_e32 v140, v117
	s_nop 0
	v_fma_f32 v141, -v117, v140, 1.0
	v_fmac_f32_e32 v140, v141, v140
	v_div_scale_f32 v141, vcc, 1.0, v80, 1.0
	v_mul_f32_e32 v143, v141, v140
	v_fma_f32 v144, -v117, v143, v141
	v_fmac_f32_e32 v143, v144, v140
	v_fma_f32 v117, -v117, v143, v141
	v_div_fmas_f32 v117, v117, v140, v143
	v_div_fixup_f32 v80, v117, v80, 1.0
	v_div_scale_f32 v117, s[2:3], v79, v79, 1.0
	v_rcp_f32_e32 v140, v117
	s_nop 0
	v_fma_f32 v141, -v117, v140, 1.0
	v_fmac_f32_e32 v140, v141, v140
	v_div_scale_f32 v141, vcc, 1.0, v79, 1.0
	v_mul_f32_e32 v143, v141, v140
	v_fma_f32 v144, -v117, v143, v141
	v_fmac_f32_e32 v143, v144, v140
	v_fma_f32 v117, -v117, v143, v141
	v_div_fmas_f32 v117, v117, v140, v143
	v_div_fixup_f32 v79, v117, v79, 1.0
	v_div_scale_f32 v117, s[2:3], v78, v78, 1.0
	v_rcp_f32_e32 v140, v117
	s_nop 0
	v_fma_f32 v141, -v117, v140, 1.0
	v_fmac_f32_e32 v140, v141, v140
	v_div_scale_f32 v141, vcc, 1.0, v78, 1.0
	v_mul_f32_e32 v143, v141, v140
	v_fma_f32 v144, -v117, v143, v141
	v_fmac_f32_e32 v143, v144, v140
	v_fma_f32 v117, -v117, v143, v141
	v_div_fmas_f32 v117, v117, v140, v143
	v_div_fixup_f32 v78, v117, v78, 1.0
	v_div_scale_f32 v117, s[2:3], v77, v77, 1.0
	v_rcp_f32_e32 v140, v117
	v_pk_fma_f32 v[78:79], v[78:79], v[124:125], v[126:127]
	v_fma_f32 v141, -v117, v140, 1.0
	v_fmac_f32_e32 v140, v141, v140
	v_div_scale_f32 v141, vcc, 1.0, v77, 1.0
	v_mul_f32_e32 v143, v141, v140
	v_fma_f32 v144, -v117, v143, v141
	v_fmac_f32_e32 v143, v144, v140
	v_fma_f32 v117, -v117, v143, v141
	v_div_fmas_f32 v117, v117, v140, v143
	v_div_fixup_f32 v141, v117, v77, 1.0
	v_div_scale_f32 v77, s[2:3], v76, v76, 1.0
	v_rcp_f32_e32 v117, v77
	s_nop 0
	v_fma_f32 v140, -v77, v117, 1.0
	v_fmac_f32_e32 v117, v140, v117
	v_div_scale_f32 v140, vcc, 1.0, v76, 1.0
	v_mul_f32_e32 v143, v140, v117
	v_fma_f32 v144, -v77, v143, v140
	v_fmac_f32_e32 v143, v144, v117
	v_fma_f32 v77, -v77, v143, v140
	v_div_fmas_f32 v77, v77, v117, v143
	v_div_fixup_f32 v140, v77, v76, 1.0
; #define NTL(p) __builtin_nontemporal_load((const f32x4*)(p))
; #define NTS(v, p) __builtin_nontemporal_store((v), (f32x4*)(p))
; __device__ __forceinline__ float bf_lo(unsigned w) { return __uint_as_float(w << 16); }
; __device__ __forceinline__ float bf_hi(unsigned w) { return __uint_as_float(w & 0xffff0000u); }
; __device__ __forceinline__ float sigmoidf_(float x) { return 1.0f / (1.0f + __expf(-x)); }
;     __device__ __forceinline__ void operator()(AccT& acc, const Unit& u, int wr, int wc, int fr, int fq) const {
;     ...
;         for (int r = 0; r < 8; ++r) { const int ai = r >> 2, m = r & 3; const int row = row0 + ai * 128 + m * 16;
;             if (r < 7) { const int rn = row0 + ((r + 1) >> 2) * 128 + ((r + 1) & 3) * 16; const float* hn = H + (size_t)rn * DM + col0; const bf16_t* pn = ppbase + (((r + 1) >> 2) * 128 + ((r + 1) & 3) * 16) * 256;
;                 hv[(r + 1) & 1][0] = NTL(hn); hv[(r + 1) & 1][1] = NTL(hn + 4); hv[(r + 1) & 1][2] = NTL(hn + 128); hv[(r + 1) & 1][3] = NTL(hn + 132);
;                 pv[(r + 1) & 1][0] = *(const u32x4*)pn; pv[(r + 1) & 1][1] = *(const u32x4*)(pn + 128); rs[(r + 1) & 1] = rss2[rn]; }
;             float* hp = H + (size_t)row * DM + col0; float ss = 0.f; const float rstd = rsqrtf(rs[r & 1] * (1.0f / DM) + 1e-6f);
; #pragma unroll
;             for (int bj = 0; bj < 2; ++bj) { const u32x4 pw = pv[r & 1][bj];
;                 const f32x4 b0 = *(const f32x4*)(bias + col0 + bj * 128), b1 = *(const f32x4*)(bias + col0 + bj * 128 + 4);
;                 const f32x4 p0 = (f32x4){bf_lo(pw.x), bf_hi(pw.x), bf_lo(pw.y), bf_hi(pw.y)}, p1 = (f32x4){bf_lo(pw.z), bf_hi(pw.z), bf_lo(pw.w), bf_hi(pw.w)};
;                 f32x4 g0 = acc[ai][bj][m][0] * rstd + b0, g1 = acc[ai][bj][m][1] * rstd + b1;
; #pragma unroll
;                 for (int j = 0; j < 4; ++j) { g0[j] = sigmoidf_(g0[j]); g1[j] = sigmoidf_(g1[j]); }
;                 const f32x4 v0 = hv[r & 1][2 * bj] + p0 * g0, v1 = hv[r & 1][2 * bj + 1] + p1 * g1;
;                 NTS(v0, hp + bj * 128); NTS(v1, hp + bj * 128 + 4);
; #pragma unroll
;                 for (int j = 0; j < 4; ++j) ss += v0[j] * v0[j] + v1[j] * v1[j]; }
;             ss += __shfl_xor(ss, 16); ss += __shfl_xor(ss, 32);
;             if (fq == 0) unsafeAtomicAdd(rss3 + row, ss); __builtin_amdgcn_sched_barrier(0); }
	v_pk_fma_f32 v[76:77], v[80:81], v[138:139], v[132:133]
	v_pk_fma_f32 v[80:81], v[140:141], v[134:135], v[128:129]
	global_store_dwordx4 v[148:149], v[74:77], off nt
	global_store_dwordx4 v[148:149], v[78:81], off offset:16 nt
	s_nop 0
	s_nop 0
	v_mul_f32_e32 v78, v78, v78
	v_fmac_f32_e32 v78, v74, v74
	v_mul_f32_e32 v74, v79, v79
	v_fmac_f32_e32 v74, v75, v75
	v_mul_f32_e32 v75, v80, v80
	v_add_f32_e32 v74, v78, v74
	v_fmac_f32_e32 v75, v76, v76
	v_add_f32_e32 v74, v75, v74
	v_mul_f32_e32 v75, v81, v81
	v_fmac_f32_e32 v75, v77, v77
	v_add_f32_e32 v117, v75, v74
	v_lshlrev_b32_e32 v78, 16, v118
	v_and_b32_e32 v79, 0xffff0000, v118
	v_lshlrev_b32_e32 v80, 16, v119
	v_and_b32_e32 v81, 0xffff0000, v119
	v_lshlrev_b32_e32 v74, 16, v120
	v_and_b32_e32 v75, 0xffff0000, v120
	v_lshlrev_b32_e32 v76, 16, v121
	v_and_b32_e32 v77, 0xffff0000, v121
	v_pk_fma_f32 v[66:67], v[66:67], v[116:117], v[232:233] op_sel_hi:[1,0,1]
	v_pk_fma_f32 v[70:71], v[70:71], v[116:117], v[248:249] op_sel_hi:[1,0,1]
	v_mul_f32_e32 v66, 0xbfb8aa3b, v66
	v_pk_fma_f32 v[68:69], v[68:69], v[116:117], v[234:235] op_sel_hi:[1,0,1]
	v_exp_f32_e32 v118, v66
	v_mul_f32_e32 v66, 0xbfb8aa3b, v71
	v_pk_fma_f32 v[72:73], v[72:73], v[116:117], v[250:251] op_sel_hi:[1,0,1]
	v_exp_f32_e32 v71, v66
	v_mul_f32_e32 v66, 0xbfb8aa3b, v67
	v_mul_f32_e32 v67, 0xbfb8aa3b, v68
	v_mul_f32_e32 v70, 0xbfb8aa3b, v70
	v_exp_f32_e32 v119, v66
	v_mul_f32_e32 v66, 0xbfb8aa3b, v72
	v_exp_f32_e32 v68, v67
	v_mul_f32_e32 v67, 0xbfb8aa3b, v73
	v_exp_f32_e32 v70, v70
	v_exp_f32_e32 v66, v66
	v_exp_f32_e32 v67, v67
	v_mul_f32_e32 v69, 0xbfb8aa3b, v69
	v_exp_f32_e32 v69, v69
	v_pk_add_f32 v[72:73], v[66:67], 1.0 op_sel_hi:[1,0]
	v_pk_add_f32 v[66:67], v[70:71], 1.0 op_sel_hi:[1,0]
	v_pk_add_f32 v[68:69], v[68:69], 1.0 op_sel_hi:[1,0]
	v_div_scale_f32 v70, s[2:3], v67, v67, 1.0
	v_rcp_f32_e32 v71, v70
	s_nop 0
	v_fma_f32 v116, -v70, v71, 1.0
	v_fmac_f32_e32 v71, v116, v71
	v_div_scale_f32 v116, vcc, 1.0, v67, 1.0
	v_mul_f32_e32 v120, v116, v71
	v_fma_f32 v121, -v70, v120, v116
	v_fmac_f32_e32 v120, v121, v71
	v_fma_f32 v70, -v70, v120, v116
	v_div_fmas_f32 v70, v70, v71, v120
	v_div_fixup_f32 v67, v70, v67, 1.0
	v_div_scale_f32 v70, s[2:3], v66, v66, 1.0
	v_rcp_f32_e32 v71, v70
	s_nop 0
	v_fma_f32 v116, -v70, v71, 1.0
	v_fmac_f32_e32 v71, v116, v71
	v_div_scale_f32 v116, vcc, 1.0, v66, 1.0
	v_mul_f32_e32 v120, v116, v71
	v_fma_f32 v121, -v70, v120, v116
	v_fmac_f32_e32 v120, v121, v71
	v_fma_f32 v70, -v70, v120, v116
	v_div_fmas_f32 v70, v70, v71, v120
	v_div_fixup_f32 v66, v70, v66, 1.0
	v_div_scale_f32 v70, s[2:3], v73, v73, 1.0
	v_rcp_f32_e32 v71, v70
	v_pk_fma_f32 v[66:67], v[66:67], v[78:79], v[102:103]
	v_fma_f32 v116, -v70, v71, 1.0
	v_fmac_f32_e32 v71, v116, v71
	v_div_scale_f32 v116, vcc, 1.0, v73, 1.0
	v_mul_f32_e32 v120, v116, v71
	v_fma_f32 v121, -v70, v120, v116
	v_fmac_f32_e32 v120, v121, v71
	v_fma_f32 v70, -v70, v120, v116
	v_div_fmas_f32 v70, v70, v71, v120
	v_div_fixup_f32 v71, v70, v73, 1.0
	v_div_scale_f32 v70, s[2:3], v72, v72, 1.0
	v_rcp_f32_e32 v73, v70
	s_nop 0
	v_fma_f32 v116, -v70, v73, 1.0
	v_fmac_f32_e32 v73, v116, v73
	v_div_scale_f32 v116, vcc, 1.0, v72, 1.0
	v_mul_f32_e32 v120, v116, v73
	v_fma_f32 v121, -v70, v120, v116
	v_fmac_f32_e32 v120, v121, v73
	v_fma_f32 v70, -v70, v120, v116
	v_div_fmas_f32 v70, v70, v73, v120
	v_div_fixup_f32 v70, v70, v72, 1.0
	v_pk_add_f32 v[72:73], v[118:119], 1.0 op_sel_hi:[1,0]
	s_nop 0
	v_div_scale_f32 v116, s[2:3], v73, v73, 1.0
	v_rcp_f32_e32 v118, v116
	s_nop 0
	v_fma_f32 v119, -v116, v118, 1.0
	v_fmac_f32_e32 v118, v119, v118
	v_div_scale_f32 v119, vcc, 1.0, v73, 1.0
	v_mul_f32_e32 v120, v119, v118
	v_fma_f32 v121, -v116, v120, v119
	v_fmac_f32_e32 v120, v121, v118
	v_fma_f32 v116, -v116, v120, v119
	v_div_fmas_f32 v116, v116, v118, v120
	v_div_fixup_f32 v119, v116, v73, 1.0
	v_div_scale_f32 v73, s[2:3], v72, v72, 1.0
	v_rcp_f32_e32 v116, v73
	s_nop 0
	v_fma_f32 v118, -v73, v116, 1.0
	v_fmac_f32_e32 v116, v118, v116
	v_div_scale_f32 v118, vcc, 1.0, v72, 1.0
	v_mul_f32_e32 v120, v118, v116
	v_fma_f32 v121, -v73, v120, v118
	v_fmac_f32_e32 v120, v121, v116
	v_fma_f32 v73, -v73, v120, v118
	v_div_fmas_f32 v73, v73, v116, v120
	v_div_fixup_f32 v118, v73, v72, 1.0
	v_div_scale_f32 v72, s[2:3], v69, v69, 1.0
	v_rcp_f32_e32 v73, v72
	s_nop 0
	v_fma_f32 v116, -v72, v73, 1.0
	v_fmac_f32_e32 v73, v116, v73
	v_div_scale_f32 v116, vcc, 1.0, v69, 1.0
	v_mul_f32_e32 v120, v116, v73
	v_fma_f32 v121, -v72, v120, v116
	v_fmac_f32_e32 v120, v121, v73
	v_fma_f32 v72, -v72, v120, v116
	v_div_fmas_f32 v72, v72, v73, v120
	v_div_fixup_f32 v73, v72, v69, 1.0
	v_div_scale_f32 v69, s[2:3], v68, v68, 1.0
	v_rcp_f32_e32 v72, v69
	s_nop 0
	v_fma_f32 v116, -v69, v72, 1.0
	v_fmac_f32_e32 v72, v116, v72
	v_div_scale_f32 v116, vcc, 1.0, v68, 1.0
	v_mul_f32_e32 v120, v116, v72
	v_fma_f32 v121, -v69, v120, v116
	v_fmac_f32_e32 v120, v121, v72
	v_fma_f32 v69, -v69, v120, v116
	v_div_fmas_f32 v69, v69, v72, v120
	v_div_fixup_f32 v72, v69, v68, 1.0
	v_pk_fma_f32 v[68:69], v[70:71], v[80:81], v[104:105]
	v_pk_fma_f32 v[70:71], v[118:119], v[74:75], v[98:99]
	v_pk_fma_f32 v[72:73], v[72:73], v[76:77], v[100:101]
	global_store_dwordx4 v[148:149], v[66:69], off offset:512 nt
	global_store_dwordx4 v[148:149], v[70:73], off offset:528 nt
	s_nop 1
	v_mul_f32_e32 v70, v70, v70
	v_fmac_f32_e32 v70, v66, v66
	v_add_f32_e32 v66, v117, v70
	v_mul_f32_e32 v70, v71, v71
	v_fmac_f32_e32 v70, v67, v67
	v_mul_f32_e32 v67, v72, v72
	v_add_f32_e32 v66, v70, v66
	v_fmac_f32_e32 v67, v68, v68
	v_add_f32_e32 v66, v67, v66
	v_mul_f32_e32 v67, v73, v73
	v_fmac_f32_e32 v67, v69, v69
	v_add_f32_e32 v66, v67, v66
	ds_bpermute_b32 v67, v225, v66
	s_waitcnt lgkmcnt(0)
	v_add_f32_e32 v66, v66, v67
	ds_bpermute_b32 v67, v226, v66
	s_and_saveexec_b64 s[2:3], s[42:43]
	s_cbranch_execz .LBB0_789
	v_lshl_add_u64 v[68:69], v[146:147], 2, s[36:37]
	s_waitcnt lgkmcnt(0)
	v_add_f32_e32 v66, v66, v67
	global_atomic_add_f32 v[68:69], v66, off
; #define NTL(p) __builtin_nontemporal_load((const f32x4*)(p))
; #define NTS(v, p) __builtin_nontemporal_store((v), (f32x4*)(p))
; __device__ __forceinline__ float bf_lo(unsigned w) { return __uint_as_float(w << 16); }
; __device__ __forceinline__ float bf_hi(unsigned w) { return __uint_as_float(w & 0xffff0000u); }
; __device__ __forceinline__ float sigmoidf_(float x) { return 1.0f / (1.0f + __expf(-x)); }
;     __device__ __forceinline__ void operator()(AccT& acc, const Unit& u, int wr, int wc, int fr, int fq) const {
;     ...
;         for (int r = 0; r < 8; ++r) { const int ai = r >> 2, m = r & 3; const int row = row0 + ai * 128 + m * 16;
;             if (r < 7) { const int rn = row0 + ((r + 1) >> 2) * 128 + ((r + 1) & 3) * 16; const float* hn = H + (size_t)rn * DM + col0; const bf16_t* pn = ppbase + (((r + 1) >> 2) * 128 + ((r + 1) & 3) * 16) * 256;
;                 hv[(r + 1) & 1][0] = NTL(hn); hv[(r + 1) & 1][1] = NTL(hn + 4); hv[(r + 1) & 1][2] = NTL(hn + 128); hv[(r + 1) & 1][3] = NTL(hn + 132);
;                 pv[(r + 1) & 1][0] = *(const u32x4*)pn; pv[(r + 1) & 1][1] = *(const u32x4*)(pn + 128); rs[(r + 1) & 1] = rss2[rn]; }
;             float* hp = H + (size_t)row * DM + col0; float ss = 0.f; const float rstd = rsqrtf(rs[r & 1] * (1.0f / DM) + 1e-6f);
; #pragma unroll
;             for (int bj = 0; bj < 2; ++bj) { const u32x4 pw = pv[r & 1][bj];
;                 const f32x4 b0 = *(const f32x4*)(bias + col0 + bj * 128), b1 = *(const f32x4*)(bias + col0 + bj * 128 + 4);
;                 const f32x4 p0 = (f32x4){bf_lo(pw.x), bf_hi(pw.x), bf_lo(pw.y), bf_hi(pw.y)}, p1 = (f32x4){bf_lo(pw.z), bf_hi(pw.z), bf_lo(pw.w), bf_hi(pw.w)};
;                 f32x4 g0 = acc[ai][bj][m][0] * rstd + b0, g1 = acc[ai][bj][m][1] * rstd + b1;
; #pragma unroll
;                 for (int j = 0; j < 4; ++j) { g0[j] = sigmoidf_(g0[j]); g1[j] = sigmoidf_(g1[j]); }
;                 const f32x4 v0 = hv[r & 1][2 * bj] + p0 * g0, v1 = hv[r & 1][2 * bj + 1] + p1 * g1;
;                 NTS(v0, hp + bj * 128); NTS(v1, hp + bj * 128 + 4);
.LBB0_789:
	s_or_b64 exec, exec, s[2:3]
	v_add_u32_e32 v116, 0x90, v186
	v_ashrrev_i32_e32 v117, 31, v116
	s_waitcnt lgkmcnt(0)
	v_lshlrev_b64 v[66:67], 12, v[116:117]
	v_lshl_add_u64 v[66:67], s[22:23], 0, v[66:67]
	v_add_co_u32_e32 v74, vcc, 0x12000, v190
	v_lshl_add_u64 v[118:119], v[192:193], 2, v[66:67]
	s_nop 0
	v_addc_co_u32_e32 v75, vcc, 0, v191, vcc
	global_load_dwordx4 v[78:81], v[118:119], off offset:16 nt
	global_load_dwordx4 v[98:101], v[118:119], off nt
	global_load_dwordx4 v[66:69], v[118:119], off offset:528 nt
	global_load_dwordx4 v[70:73], v[118:119], off offset:512 nt
	global_load_dwordx4 v[102:105], v[74:75], off
	s_nop 0
	global_load_dwordx4 v[74:77], v[74:75], off offset:256
	s_nop 0
	global_load_dword v121, v[188:189], off offset:576
	s_waitcnt vmcnt(11)
	v_fmamk_f32 v120, v142, 0x3a800000, v210
	v_cmp_gt_f32_e32 vcc, s30, v120
	v_mul_f32_e32 v124, 0x4b800000, v120
	v_and_b32_e32 v125, 0xffff0000, v110
	v_cndmask_b32_e32 v120, v120, v124, vcc
	v_rsq_f32_e32 v120, v120
	v_lshlrev_b32_e32 v126, 16, v111
	v_and_b32_e32 v127, 0xffff0000, v111
	v_and_b32_e32 v111, 0xffff0000, v112
	v_mul_f32_e32 v124, 0x45800000, v120
	v_cndmask_b32_e32 v120, v120, v124, vcc
	v_lshlrev_b32_e32 v124, 16, v110
	v_lshlrev_b32_e32 v110, 16, v112
	v_lshlrev_b32_e32 v112, 16, v113
	v_and_b32_e32 v113, 0xffff0000, v113
	v_pk_fma_f32 v[58:59], v[58:59], v[120:121], v[244:245] op_sel_hi:[1,0,1]
	v_pk_fma_f32 v[62:63], v[62:63], v[120:121], v[240:241] op_sel_hi:[1,0,1]
	v_mul_f32_e32 v58, 0xbfb8aa3b, v58
	v_mul_f32_e32 v62, 0xbfb8aa3b, v62
	v_pk_fma_f32 v[60:61], v[60:61], v[120:121], v[246:247] op_sel_hi:[1,0,1]
	v_exp_f32_e32 v128, v62
	v_exp_f32_e32 v62, v58
	v_mul_f32_e32 v58, 0xbfb8aa3b, v63
	v_pk_fma_f32 v[64:65], v[64:65], v[120:121], v[242:243] op_sel_hi:[1,0,1]
	v_exp_f32_e32 v129, v58
	v_mul_f32_e32 v58, 0xbfb8aa3b, v59
	v_mul_f32_e32 v59, 0xbfb8aa3b, v60
	v_exp_f32_e32 v63, v58
	v_mul_f32_e32 v58, 0xbfb8aa3b, v64
	v_exp_f32_e32 v60, v59
	v_mul_f32_e32 v59, 0xbfb8aa3b, v65
	v_exp_f32_e32 v58, v58
	v_exp_f32_e32 v59, v59
	v_pk_add_f32 v[62:63], v[62:63], 1.0 op_sel_hi:[1,0]
	v_mul_f32_e32 v61, 0xbfb8aa3b, v61
	v_exp_f32_e32 v61, v61
	v_pk_add_f32 v[64:65], v[58:59], 1.0 op_sel_hi:[1,0]
	v_pk_add_f32 v[58:59], v[128:129], 1.0 op_sel_hi:[1,0]
	v_pk_add_f32 v[60:61], v[60:61], 1.0 op_sel_hi:[1,0]
	v_div_scale_f32 v128, s[2:3], v59, v59, 1.0
	v_rcp_f32_e32 v129, v128
	s_nop 0
	v_fma_f32 v130, -v128, v129, 1.0
	v_fmac_f32_e32 v129, v130, v129
	v_div_scale_f32 v130, vcc, 1.0, v59, 1.0
	v_mul_f32_e32 v131, v130, v129
	v_fma_f32 v132, -v128, v131, v130
	v_fmac_f32_e32 v131, v132, v129
	v_fma_f32 v128, -v128, v131, v130
	v_div_fmas_f32 v128, v128, v129, v131
	v_div_fixup_f32 v59, v128, v59, 1.0
	v_div_scale_f32 v128, s[2:3], v58, v58, 1.0
	v_rcp_f32_e32 v129, v128
	s_nop 0
	v_fma_f32 v130, -v128, v129, 1.0
	v_fmac_f32_e32 v129, v130, v129
	v_div_scale_f32 v130, vcc, 1.0, v58, 1.0
	v_mul_f32_e32 v131, v130, v129
	v_fma_f32 v132, -v128, v131, v130
	v_fmac_f32_e32 v131, v132, v129
	v_fma_f32 v128, -v128, v131, v130
	v_div_fmas_f32 v128, v128, v129, v131
	v_div_fixup_f32 v58, v128, v58, 1.0
	v_div_scale_f32 v128, s[2:3], v65, v65, 1.0
	v_rcp_f32_e32 v129, v128
	v_pk_fma_f32 v[58:59], v[58:59], v[124:125], v[106:107]
	v_fma_f32 v130, -v128, v129, 1.0
	v_fmac_f32_e32 v129, v130, v129
	v_div_scale_f32 v130, vcc, 1.0, v65, 1.0
	v_mul_f32_e32 v131, v130, v129
	v_fma_f32 v132, -v128, v131, v130
	v_fmac_f32_e32 v131, v132, v129
	v_fma_f32 v128, -v128, v131, v130
	v_div_fmas_f32 v128, v128, v129, v131
	v_div_fixup_f32 v65, v128, v65, 1.0
	v_div_scale_f32 v128, s[2:3], v64, v64, 1.0
	v_rcp_f32_e32 v129, v128
	s_nop 0
	v_fma_f32 v130, -v128, v129, 1.0
	v_fmac_f32_e32 v129, v130, v129
	v_div_scale_f32 v130, vcc, 1.0, v64, 1.0
	v_mul_f32_e32 v131, v130, v129
	v_fma_f32 v132, -v128, v131, v130
	v_fmac_f32_e32 v131, v132, v129
	v_fma_f32 v128, -v128, v131, v130
	v_div_fmas_f32 v128, v128, v129, v131
	v_div_fixup_f32 v64, v128, v64, 1.0
	v_div_scale_f32 v128, s[2:3], v63, v63, 1.0
	v_rcp_f32_e32 v129, v128
	s_nop 0
	v_fma_f32 v130, -v128, v129, 1.0
	v_fmac_f32_e32 v129, v130, v129
	v_div_scale_f32 v130, vcc, 1.0, v63, 1.0
	v_mul_f32_e32 v131, v130, v129
	v_fma_f32 v132, -v128, v131, v130
	v_fmac_f32_e32 v131, v132, v129
	v_fma_f32 v128, -v128, v131, v130
	v_div_fmas_f32 v128, v128, v129, v131
	v_div_fixup_f32 v63, v128, v63, 1.0
	v_div_scale_f32 v128, s[2:3], v62, v62, 1.0
	v_rcp_f32_e32 v129, v128
	s_nop 0
	v_fma_f32 v130, -v128, v129, 1.0
	v_fmac_f32_e32 v129, v130, v129
	v_div_scale_f32 v130, vcc, 1.0, v62, 1.0
	v_mul_f32_e32 v131, v130, v129
	v_fma_f32 v132, -v128, v131, v130
	v_fmac_f32_e32 v131, v132, v129
	v_fma_f32 v128, -v128, v131, v130
	v_div_fmas_f32 v128, v128, v129, v131
	v_div_fixup_f32 v62, v128, v62, 1.0
	v_div_scale_f32 v128, s[2:3], v61, v61, 1.0
	v_rcp_f32_e32 v129, v128
	v_pk_fma_f32 v[62:63], v[62:63], v[110:111], v[94:95]
	v_fma_f32 v130, -v128, v129, 1.0
	v_fmac_f32_e32 v129, v130, v129
	v_div_scale_f32 v130, vcc, 1.0, v61, 1.0
	v_mul_f32_e32 v131, v130, v129
	v_fma_f32 v132, -v128, v131, v130
	v_fmac_f32_e32 v131, v132, v129
	v_fma_f32 v128, -v128, v131, v130
	v_div_fmas_f32 v128, v128, v129, v131
	v_div_fixup_f32 v129, v128, v61, 1.0
	v_div_scale_f32 v61, s[2:3], v60, v60, 1.0
	v_rcp_f32_e32 v128, v61
	s_nop 0
	v_fma_f32 v130, -v61, v128, 1.0
	v_fmac_f32_e32 v128, v130, v128
	v_div_scale_f32 v130, vcc, 1.0, v60, 1.0
	v_mul_f32_e32 v131, v130, v128
	v_fma_f32 v132, -v61, v131, v130
	v_fmac_f32_e32 v131, v132, v128
	v_fma_f32 v61, -v61, v131, v130
	v_div_fmas_f32 v61, v61, v128, v131
	v_div_fixup_f32 v128, v61, v60, 1.0
; #define NTL(p) __builtin_nontemporal_load((const f32x4*)(p))
; #define NTS(v, p) __builtin_nontemporal_store((v), (f32x4*)(p))
; __device__ __forceinline__ float bf_lo(unsigned w) { return __uint_as_float(w << 16); }
; __device__ __forceinline__ float bf_hi(unsigned w) { return __uint_as_float(w & 0xffff0000u); }
; __device__ __forceinline__ float sigmoidf_(float x) { return 1.0f / (1.0f + __expf(-x)); }
;     __device__ __forceinline__ void operator()(AccT& acc, const Unit& u, int wr, int wc, int fr, int fq) const {
;     ...
;         for (int r = 0; r < 8; ++r) { const int ai = r >> 2, m = r & 3; const int row = row0 + ai * 128 + m * 16;
;             if (r < 7) { const int rn = row0 + ((r + 1) >> 2) * 128 + ((r + 1) & 3) * 16; const float* hn = H + (size_t)rn * DM + col0; const bf16_t* pn = ppbase + (((r + 1) >> 2) * 128 + ((r + 1) & 3) * 16) * 256;
;                 hv[(r + 1) & 1][0] = NTL(hn); hv[(r + 1) & 1][1] = NTL(hn + 4); hv[(r + 1) & 1][2] = NTL(hn + 128); hv[(r + 1) & 1][3] = NTL(hn + 132);
;                 pv[(r + 1) & 1][0] = *(const u32x4*)pn; pv[(r + 1) & 1][1] = *(const u32x4*)(pn + 128); rs[(r + 1) & 1] = rss2[rn]; }
;             float* hp = H + (size_t)row * DM + col0; float ss = 0.f; const float rstd = rsqrtf(rs[r & 1] * (1.0f / DM) + 1e-6f);
; #pragma unroll
;             for (int bj = 0; bj < 2; ++bj) { const u32x4 pw = pv[r & 1][bj];
;                 const f32x4 b0 = *(const f32x4*)(bias + col0 + bj * 128), b1 = *(const f32x4*)(bias + col0 + bj * 128 + 4);
;                 const f32x4 p0 = (f32x4){bf_lo(pw.x), bf_hi(pw.x), bf_lo(pw.y), bf_hi(pw.y)}, p1 = (f32x4){bf_lo(pw.z), bf_hi(pw.z), bf_lo(pw.w), bf_hi(pw.w)};
;                 f32x4 g0 = acc[ai][bj][m][0] * rstd + b0, g1 = acc[ai][bj][m][1] * rstd + b1;
; #pragma unroll
;                 for (int j = 0; j < 4; ++j) { g0[j] = sigmoidf_(g0[j]); g1[j] = sigmoidf_(g1[j]); }
;                 const f32x4 v0 = hv[r & 1][2 * bj] + p0 * g0, v1 = hv[r & 1][2 * bj + 1] + p1 * g1;
;                 NTS(v0, hp + bj * 128); NTS(v1, hp + bj * 128 + 4);
; #pragma unroll
;                 for (int j = 0; j < 4; ++j) ss += v0[j] * v0[j] + v1[j] * v1[j]; }
;             ss += __shfl_xor(ss, 16); ss += __shfl_xor(ss, 32);
;             if (fq == 0) unsafeAtomicAdd(rss3 + row, ss); __builtin_amdgcn_sched_barrier(0); }
	v_pk_fma_f32 v[60:61], v[64:65], v[126:127], v[108:109]
	v_pk_fma_f32 v[64:65], v[128:129], v[112:113], v[96:97]
	global_store_dwordx4 v[122:123], v[58:61], off nt
	global_store_dwordx4 v[122:123], v[62:65], off offset:16 nt
	s_nop 0
	s_nop 0
	v_mul_f32_e32 v62, v62, v62
	v_fmac_f32_e32 v62, v58, v58
	v_mul_f32_e32 v58, v63, v63
	v_fmac_f32_e32 v58, v59, v59
	v_add_f32_e32 v58, v62, v58
	v_mul_f32_e32 v59, v64, v64
	v_lshlrev_b32_e32 v62, 16, v90
	v_and_b32_e32 v63, 0xffff0000, v90
	v_fmac_f32_e32 v59, v60, v60
	v_add_f32_e32 v58, v59, v58
	v_mul_f32_e32 v59, v65, v65
	v_lshlrev_b32_e32 v64, 16, v91
	v_and_b32_e32 v65, 0xffff0000, v91
	v_fmac_f32_e32 v59, v61, v61
	v_add_f32_e32 v94, v59, v58
	v_lshlrev_b32_e32 v58, 16, v92
	v_and_b32_e32 v59, 0xffff0000, v92
	v_lshlrev_b32_e32 v60, 16, v93
	v_and_b32_e32 v61, 0xffff0000, v93
	v_pk_fma_f32 v[50:51], v[50:51], v[120:121], v[232:233] op_sel_hi:[1,0,1]
	v_pk_fma_f32 v[54:55], v[54:55], v[120:121], v[248:249] op_sel_hi:[1,0,1]
	v_mul_f32_e32 v50, 0xbfb8aa3b, v50
	v_pk_fma_f32 v[52:53], v[52:53], v[120:121], v[234:235] op_sel_hi:[1,0,1]
	v_exp_f32_e32 v90, v50
	v_mul_f32_e32 v50, 0xbfb8aa3b, v55
	v_pk_fma_f32 v[56:57], v[56:57], v[120:121], v[250:251] op_sel_hi:[1,0,1]
	v_exp_f32_e32 v55, v50
	v_mul_f32_e32 v50, 0xbfb8aa3b, v51
	v_mul_f32_e32 v51, 0xbfb8aa3b, v52
	v_mul_f32_e32 v54, 0xbfb8aa3b, v54
	v_exp_f32_e32 v91, v50
	v_mul_f32_e32 v50, 0xbfb8aa3b, v56
	v_exp_f32_e32 v52, v51
	v_mul_f32_e32 v51, 0xbfb8aa3b, v57
	v_exp_f32_e32 v54, v54
	v_exp_f32_e32 v50, v50
	v_exp_f32_e32 v51, v51
	v_mul_f32_e32 v53, 0xbfb8aa3b, v53
	v_exp_f32_e32 v53, v53
	v_pk_add_f32 v[56:57], v[50:51], 1.0 op_sel_hi:[1,0]
	v_pk_add_f32 v[50:51], v[54:55], 1.0 op_sel_hi:[1,0]
	v_pk_add_f32 v[52:53], v[52:53], 1.0 op_sel_hi:[1,0]
	v_div_scale_f32 v54, s[2:3], v51, v51, 1.0
	v_rcp_f32_e32 v55, v54
	s_nop 0
	v_fma_f32 v92, -v54, v55, 1.0
	v_fmac_f32_e32 v55, v92, v55
	v_div_scale_f32 v92, vcc, 1.0, v51, 1.0
	v_mul_f32_e32 v93, v92, v55
	v_fma_f32 v95, -v54, v93, v92
	v_fmac_f32_e32 v93, v95, v55
	v_fma_f32 v54, -v54, v93, v92
	v_div_fmas_f32 v54, v54, v55, v93
	v_div_fixup_f32 v51, v54, v51, 1.0
	v_div_scale_f32 v54, s[2:3], v50, v50, 1.0
	v_rcp_f32_e32 v55, v54
	s_nop 0
	v_fma_f32 v92, -v54, v55, 1.0
	v_fmac_f32_e32 v55, v92, v55
	v_div_scale_f32 v92, vcc, 1.0, v50, 1.0
	v_mul_f32_e32 v93, v92, v55
	v_fma_f32 v95, -v54, v93, v92
	v_fmac_f32_e32 v93, v95, v55
	v_fma_f32 v54, -v54, v93, v92
	v_div_fmas_f32 v54, v54, v55, v93
	v_div_fixup_f32 v50, v54, v50, 1.0
	v_div_scale_f32 v54, s[2:3], v57, v57, 1.0
	v_rcp_f32_e32 v55, v54
	v_pk_fma_f32 v[50:51], v[50:51], v[62:63], v[86:87]
	v_fma_f32 v92, -v54, v55, 1.0
	v_fmac_f32_e32 v55, v92, v55
	v_div_scale_f32 v92, vcc, 1.0, v57, 1.0
	v_mul_f32_e32 v93, v92, v55
	v_fma_f32 v95, -v54, v93, v92
	v_fmac_f32_e32 v93, v95, v55
	v_fma_f32 v54, -v54, v93, v92
	v_div_fmas_f32 v54, v54, v55, v93
	v_div_fixup_f32 v55, v54, v57, 1.0
	v_div_scale_f32 v54, s[2:3], v56, v56, 1.0
	v_rcp_f32_e32 v57, v54
	s_nop 0
	v_fma_f32 v92, -v54, v57, 1.0
	v_fmac_f32_e32 v57, v92, v57
	v_div_scale_f32 v92, vcc, 1.0, v56, 1.0
	v_mul_f32_e32 v93, v92, v57
	v_fma_f32 v95, -v54, v93, v92
	v_fmac_f32_e32 v93, v95, v57
	v_fma_f32 v54, -v54, v93, v92
	v_div_fmas_f32 v54, v54, v57, v93
	v_div_fixup_f32 v54, v54, v56, 1.0
	v_pk_add_f32 v[56:57], v[90:91], 1.0 op_sel_hi:[1,0]
	s_nop 0
	v_div_scale_f32 v90, s[2:3], v57, v57, 1.0
	v_rcp_f32_e32 v91, v90
	s_nop 0
	v_fma_f32 v92, -v90, v91, 1.0
	v_fmac_f32_e32 v91, v92, v91
	v_div_scale_f32 v92, vcc, 1.0, v57, 1.0
	v_mul_f32_e32 v93, v92, v91
	v_fma_f32 v95, -v90, v93, v92
	v_fmac_f32_e32 v93, v95, v91
	v_fma_f32 v90, -v90, v93, v92
	v_div_fmas_f32 v90, v90, v91, v93
	v_div_fixup_f32 v91, v90, v57, 1.0
	v_div_scale_f32 v57, s[2:3], v56, v56, 1.0
	v_rcp_f32_e32 v90, v57
	s_nop 0
	v_fma_f32 v92, -v57, v90, 1.0
	v_fmac_f32_e32 v90, v92, v90
	v_div_scale_f32 v92, vcc, 1.0, v56, 1.0
	v_mul_f32_e32 v93, v92, v90
	v_fma_f32 v95, -v57, v93, v92
	v_fmac_f32_e32 v93, v95, v90
	v_fma_f32 v57, -v57, v93, v92
	v_div_fmas_f32 v57, v57, v90, v93
	v_div_fixup_f32 v90, v57, v56, 1.0
	v_div_scale_f32 v56, s[2:3], v53, v53, 1.0
	v_rcp_f32_e32 v57, v56
	s_nop 0
	v_fma_f32 v92, -v56, v57, 1.0
	v_fmac_f32_e32 v57, v92, v57
	v_div_scale_f32 v92, vcc, 1.0, v53, 1.0
	v_mul_f32_e32 v93, v92, v57
	v_fma_f32 v95, -v56, v93, v92
	v_fmac_f32_e32 v93, v95, v57
	v_fma_f32 v56, -v56, v93, v92
	v_div_fmas_f32 v56, v56, v57, v93
	v_div_fixup_f32 v57, v56, v53, 1.0
	v_div_scale_f32 v53, s[2:3], v52, v52, 1.0
	v_rcp_f32_e32 v56, v53
	s_nop 0
	v_fma_f32 v92, -v53, v56, 1.0
	v_fmac_f32_e32 v56, v92, v56
	v_div_scale_f32 v92, vcc, 1.0, v52, 1.0
	v_mul_f32_e32 v93, v92, v56
	v_fma_f32 v95, -v53, v93, v92
	v_fmac_f32_e32 v93, v95, v56
	v_fma_f32 v53, -v53, v93, v92
	v_div_fmas_f32 v53, v53, v56, v93
	v_div_fixup_f32 v56, v53, v52, 1.0
	v_pk_fma_f32 v[52:53], v[54:55], v[64:65], v[88:89]
	v_pk_fma_f32 v[54:55], v[90:91], v[58:59], v[82:83]
	v_pk_fma_f32 v[56:57], v[56:57], v[60:61], v[84:85]
	global_store_dwordx4 v[122:123], v[50:53], off offset:512 nt
	global_store_dwordx4 v[122:123], v[54:57], off offset:528 nt
	s_nop 1
	v_mul_f32_e32 v54, v54, v54
	v_fmac_f32_e32 v54, v50, v50
	v_add_f32_e32 v50, v94, v54
	v_mul_f32_e32 v54, v55, v55
	v_fmac_f32_e32 v54, v51, v51
	v_mul_f32_e32 v51, v56, v56
	v_add_f32_e32 v50, v54, v50
	v_fmac_f32_e32 v51, v52, v52
	v_add_f32_e32 v50, v51, v50
	v_mul_f32_e32 v51, v57, v57
	v_fmac_f32_e32 v51, v53, v53
	v_add_f32_e32 v50, v51, v50
	ds_bpermute_b32 v51, v225, v50
	s_waitcnt lgkmcnt(0)
	v_add_f32_e32 v50, v50, v51
	ds_bpermute_b32 v51, v226, v50
	s_and_saveexec_b64 s[2:3], s[42:43]
	s_cbranch_execz .LBB0_791
	v_lshl_add_u64 v[52:53], v[114:115], 2, s[36:37]
	s_waitcnt lgkmcnt(0)
	v_add_f32_e32 v50, v50, v51
	global_atomic_add_f32 v[52:53], v50, off
; #define NTL(p) __builtin_nontemporal_load((const f32x4*)(p))
; #define NTS(v, p) __builtin_nontemporal_store((v), (f32x4*)(p))
; __device__ __forceinline__ float bf_lo(unsigned w) { return __uint_as_float(w << 16); }
; __device__ __forceinline__ float bf_hi(unsigned w) { return __uint_as_float(w & 0xffff0000u); }
; __device__ __forceinline__ float sigmoidf_(float x) { return 1.0f / (1.0f + __expf(-x)); }
;     __device__ __forceinline__ void operator()(AccT& acc, const Unit& u, int wr, int wc, int fr, int fq) const {
;     ...
;         for (int r = 0; r < 8; ++r) { const int ai = r >> 2, m = r & 3; const int row = row0 + ai * 128 + m * 16;
;             if (r < 7) { const int rn = row0 + ((r + 1) >> 2) * 128 + ((r + 1) & 3) * 16; const float* hn = H + (size_t)rn * DM + col0; const bf16_t* pn = ppbase + (((r + 1) >> 2) * 128 + ((r + 1) & 3) * 16) * 256;
;                 hv[(r + 1) & 1][0] = NTL(hn); hv[(r + 1) & 1][1] = NTL(hn + 4); hv[(r + 1) & 1][2] = NTL(hn + 128); hv[(r + 1) & 1][3] = NTL(hn + 132);
;                 pv[(r + 1) & 1][0] = *(const u32x4*)pn; pv[(r + 1) & 1][1] = *(const u32x4*)(pn + 128); rs[(r + 1) & 1] = rss2[rn]; }
;             float* hp = H + (size_t)row * DM + col0; float ss = 0.f; const float rstd = rsqrtf(rs[r & 1] * (1.0f / DM) + 1e-6f);
; #pragma unroll
;             for (int bj = 0; bj < 2; ++bj) { const u32x4 pw = pv[r & 1][bj];
;                 const f32x4 b0 = *(const f32x4*)(bias + col0 + bj * 128), b1 = *(const f32x4*)(bias + col0 + bj * 128 + 4);
;                 const f32x4 p0 = (f32x4){bf_lo(pw.x), bf_hi(pw.x), bf_lo(pw.y), bf_hi(pw.y)}, p1 = (f32x4){bf_lo(pw.z), bf_hi(pw.z), bf_lo(pw.w), bf_hi(pw.w)};
;                 f32x4 g0 = acc[ai][bj][m][0] * rstd + b0, g1 = acc[ai][bj][m][1] * rstd + b1;
; #pragma unroll
;                 for (int j = 0; j < 4; ++j) { g0[j] = sigmoidf_(g0[j]); g1[j] = sigmoidf_(g1[j]); }
;                 const f32x4 v0 = hv[r & 1][2 * bj] + p0 * g0, v1 = hv[r & 1][2 * bj + 1] + p1 * g1;
;                 NTS(v0, hp + bj * 128); NTS(v1, hp + bj * 128 + 4);
.LBB0_791:
	s_or_b64 exec, exec, s[2:3]
	v_add_u32_e32 v90, 0xa0, v186
	v_ashrrev_i32_e32 v91, 31, v90
	s_waitcnt lgkmcnt(0)
	v_lshlrev_b64 v[50:51], 12, v[90:91]
	v_lshl_add_u64 v[50:51], s[22:23], 0, v[50:51]
	v_add_co_u32_e32 v58, vcc, 0x14000, v190
	v_lshl_add_u64 v[92:93], v[192:193], 2, v[50:51]
	s_nop 0
	v_addc_co_u32_e32 v59, vcc, 0, v191, vcc
	global_load_dwordx4 v[62:65], v[92:93], off offset:16 nt
	global_load_dwordx4 v[82:85], v[92:93], off nt
	global_load_dwordx4 v[50:53], v[92:93], off offset:528 nt
	global_load_dwordx4 v[54:57], v[92:93], off offset:512 nt
	global_load_dwordx4 v[86:89], v[58:59], off
	s_nop 0
	global_load_dwordx4 v[58:61], v[58:59], off offset:256
	s_nop 0
	global_load_dword v95, v[188:189], off offset:640
	s_waitcnt vmcnt(11)
	v_fmamk_f32 v94, v121, 0x3a800000, v210
	v_cmp_gt_f32_e32 vcc, s30, v94
	v_mul_f32_e32 v96, 0x4b800000, v94
	v_and_b32_e32 v97, 0xffff0000, v104
	v_cndmask_b32_e32 v94, v94, v96, vcc
	v_rsq_f32_e32 v94, v94
	v_lshlrev_b32_e32 v106, 16, v102
	v_and_b32_e32 v107, 0xffff0000, v102
	v_lshlrev_b32_e32 v108, 16, v103
	v_mul_f32_e32 v96, 0x45800000, v94
	v_cndmask_b32_e32 v94, v94, v96, vcc
	v_lshlrev_b32_e32 v96, 16, v104
	v_and_b32_e32 v109, 0xffff0000, v103
	v_lshlrev_b32_e32 v102, 16, v105
	v_and_b32_e32 v103, 0xffff0000, v105
	v_pk_fma_f32 v[42:43], v[42:43], v[94:95], v[244:245] op_sel_hi:[1,0,1]
	v_pk_fma_f32 v[46:47], v[46:47], v[94:95], v[240:241] op_sel_hi:[1,0,1]
	v_mul_f32_e32 v42, 0xbfb8aa3b, v42
	v_mul_f32_e32 v46, 0xbfb8aa3b, v46
	v_pk_fma_f32 v[44:45], v[44:45], v[94:95], v[246:247] op_sel_hi:[1,0,1]
	v_exp_f32_e32 v104, v46
	v_exp_f32_e32 v46, v42
	v_mul_f32_e32 v42, 0xbfb8aa3b, v47
	v_pk_fma_f32 v[48:49], v[48:49], v[94:95], v[242:243] op_sel_hi:[1,0,1]
	v_exp_f32_e32 v105, v42
	v_mul_f32_e32 v42, 0xbfb8aa3b, v43
	v_mul_f32_e32 v43, 0xbfb8aa3b, v44
	v_exp_f32_e32 v47, v42
	v_mul_f32_e32 v42, 0xbfb8aa3b, v48
	v_exp_f32_e32 v44, v43
	v_mul_f32_e32 v43, 0xbfb8aa3b, v49
	v_exp_f32_e32 v42, v42
	v_exp_f32_e32 v43, v43
	v_pk_add_f32 v[46:47], v[46:47], 1.0 op_sel_hi:[1,0]
	v_mul_f32_e32 v45, 0xbfb8aa3b, v45
	v_exp_f32_e32 v45, v45
	v_pk_add_f32 v[48:49], v[42:43], 1.0 op_sel_hi:[1,0]
	v_pk_add_f32 v[42:43], v[104:105], 1.0 op_sel_hi:[1,0]
	v_pk_add_f32 v[44:45], v[44:45], 1.0 op_sel_hi:[1,0]
	v_div_scale_f32 v104, s[2:3], v43, v43, 1.0
	v_rcp_f32_e32 v105, v104
	s_nop 0
	v_fma_f32 v110, -v104, v105, 1.0
	v_fmac_f32_e32 v105, v110, v105
	v_div_scale_f32 v110, vcc, 1.0, v43, 1.0
	v_mul_f32_e32 v111, v110, v105
	v_fma_f32 v112, -v104, v111, v110
	v_fmac_f32_e32 v111, v112, v105
	v_fma_f32 v104, -v104, v111, v110
	v_div_fmas_f32 v104, v104, v105, v111
	v_div_fixup_f32 v43, v104, v43, 1.0
	v_div_scale_f32 v104, s[2:3], v42, v42, 1.0
	v_rcp_f32_e32 v105, v104
	s_nop 0
	v_fma_f32 v110, -v104, v105, 1.0
	v_fmac_f32_e32 v105, v110, v105
	v_div_scale_f32 v110, vcc, 1.0, v42, 1.0
	v_mul_f32_e32 v111, v110, v105
	v_fma_f32 v112, -v104, v111, v110
	v_fmac_f32_e32 v111, v112, v105
	v_fma_f32 v104, -v104, v111, v110
	v_div_fmas_f32 v104, v104, v105, v111
	v_div_fixup_f32 v42, v104, v42, 1.0
	v_div_scale_f32 v104, s[2:3], v49, v49, 1.0
	v_rcp_f32_e32 v105, v104
	v_pk_fma_f32 v[42:43], v[42:43], v[106:107], v[98:99]
	v_fma_f32 v110, -v104, v105, 1.0
	v_fmac_f32_e32 v105, v110, v105
	v_div_scale_f32 v110, vcc, 1.0, v49, 1.0
	v_mul_f32_e32 v111, v110, v105
	v_fma_f32 v112, -v104, v111, v110
	v_fmac_f32_e32 v111, v112, v105
	v_fma_f32 v104, -v104, v111, v110
	v_div_fmas_f32 v104, v104, v105, v111
	v_div_fixup_f32 v49, v104, v49, 1.0
	v_div_scale_f32 v104, s[2:3], v48, v48, 1.0
	v_rcp_f32_e32 v105, v104
	s_nop 0
	v_fma_f32 v110, -v104, v105, 1.0
	v_fmac_f32_e32 v105, v110, v105
	v_div_scale_f32 v110, vcc, 1.0, v48, 1.0
	v_mul_f32_e32 v111, v110, v105
	v_fma_f32 v112, -v104, v111, v110
	v_fmac_f32_e32 v111, v112, v105
	v_fma_f32 v104, -v104, v111, v110
	v_div_fmas_f32 v104, v104, v105, v111
	v_div_fixup_f32 v48, v104, v48, 1.0
	v_div_scale_f32 v104, s[2:3], v47, v47, 1.0
	v_rcp_f32_e32 v105, v104
	s_nop 0
	v_fma_f32 v110, -v104, v105, 1.0
	v_fmac_f32_e32 v105, v110, v105
	v_div_scale_f32 v110, vcc, 1.0, v47, 1.0
	v_mul_f32_e32 v111, v110, v105
	v_fma_f32 v112, -v104, v111, v110
	v_fmac_f32_e32 v111, v112, v105
	v_fma_f32 v104, -v104, v111, v110
	v_div_fmas_f32 v104, v104, v105, v111
	v_div_fixup_f32 v47, v104, v47, 1.0
	v_div_scale_f32 v104, s[2:3], v46, v46, 1.0
	v_rcp_f32_e32 v105, v104
	s_nop 0
	v_fma_f32 v110, -v104, v105, 1.0
	v_fmac_f32_e32 v105, v110, v105
	v_div_scale_f32 v110, vcc, 1.0, v46, 1.0
	v_mul_f32_e32 v111, v110, v105
	v_fma_f32 v112, -v104, v111, v110
	v_fmac_f32_e32 v111, v112, v105
	v_fma_f32 v104, -v104, v111, v110
	v_div_fmas_f32 v104, v104, v105, v111
	v_div_fixup_f32 v46, v104, v46, 1.0
	v_div_scale_f32 v104, s[2:3], v45, v45, 1.0
	v_rcp_f32_e32 v105, v104
	v_pk_fma_f32 v[46:47], v[46:47], v[96:97], v[78:79]
	v_fma_f32 v110, -v104, v105, 1.0
	v_fmac_f32_e32 v105, v110, v105
	v_div_scale_f32 v110, vcc, 1.0, v45, 1.0
	v_mul_f32_e32 v111, v110, v105
	v_fma_f32 v112, -v104, v111, v110
	v_fmac_f32_e32 v111, v112, v105
	v_fma_f32 v104, -v104, v111, v110
	v_div_fmas_f32 v104, v104, v105, v111
	v_div_fixup_f32 v105, v104, v45, 1.0
	v_div_scale_f32 v45, s[2:3], v44, v44, 1.0
	v_rcp_f32_e32 v104, v45
	s_nop 0
	v_fma_f32 v110, -v45, v104, 1.0
	v_fmac_f32_e32 v104, v110, v104
	v_div_scale_f32 v110, vcc, 1.0, v44, 1.0
	v_mul_f32_e32 v111, v110, v104
	v_fma_f32 v112, -v45, v111, v110
	v_fmac_f32_e32 v111, v112, v104
	v_fma_f32 v45, -v45, v111, v110
	v_div_fmas_f32 v45, v45, v104, v111
	v_div_fixup_f32 v104, v45, v44, 1.0
	v_pk_fma_f32 v[44:45], v[48:49], v[108:109], v[100:101]
; #define NTL(p) __builtin_nontemporal_load((const f32x4*)(p))
; #define NTS(v, p) __builtin_nontemporal_store((v), (f32x4*)(p))
; __device__ __forceinline__ float bf_lo(unsigned w) { return __uint_as_float(w << 16); }
; __device__ __forceinline__ float bf_hi(unsigned w) { return __uint_as_float(w & 0xffff0000u); }
; __device__ __forceinline__ float sigmoidf_(float x) { return 1.0f / (1.0f + __expf(-x)); }
;     __device__ __forceinline__ void operator()(AccT& acc, const Unit& u, int wr, int wc, int fr, int fq) const {
;     ...
;         for (int r = 0; r < 8; ++r) { const int ai = r >> 2, m = r & 3; const int row = row0 + ai * 128 + m * 16;
;             if (r < 7) { const int rn = row0 + ((r + 1) >> 2) * 128 + ((r + 1) & 3) * 16; const float* hn = H + (size_t)rn * DM + col0; const bf16_t* pn = ppbase + (((r + 1) >> 2) * 128 + ((r + 1) & 3) * 16) * 256;
;                 hv[(r + 1) & 1][0] = NTL(hn); hv[(r + 1) & 1][1] = NTL(hn + 4); hv[(r + 1) & 1][2] = NTL(hn + 128); hv[(r + 1) & 1][3] = NTL(hn + 132);
;                 pv[(r + 1) & 1][0] = *(const u32x4*)pn; pv[(r + 1) & 1][1] = *(const u32x4*)(pn + 128); rs[(r + 1) & 1] = rss2[rn]; }
;             float* hp = H + (size_t)row * DM + col0; float ss = 0.f; const float rstd = rsqrtf(rs[r & 1] * (1.0f / DM) + 1e-6f);
; #pragma unroll
;             for (int bj = 0; bj < 2; ++bj) { const u32x4 pw = pv[r & 1][bj];
;                 const f32x4 b0 = *(const f32x4*)(bias + col0 + bj * 128), b1 = *(const f32x4*)(bias + col0 + bj * 128 + 4);
;                 const f32x4 p0 = (f32x4){bf_lo(pw.x), bf_hi(pw.x), bf_lo(pw.y), bf_hi(pw.y)}, p1 = (f32x4){bf_lo(pw.z), bf_hi(pw.z), bf_lo(pw.w), bf_hi(pw.w)};
;                 f32x4 g0 = acc[ai][bj][m][0] * rstd + b0, g1 = acc[ai][bj][m][1] * rstd + b1;
; #pragma unroll
;                 for (int j = 0; j < 4; ++j) { g0[j] = sigmoidf_(g0[j]); g1[j] = sigmoidf_(g1[j]); }
;                 const f32x4 v0 = hv[r & 1][2 * bj] + p0 * g0, v1 = hv[r & 1][2 * bj + 1] + p1 * g1;
;                 NTS(v0, hp + bj * 128); NTS(v1, hp + bj * 128 + 4);
; #pragma unroll
;                 for (int j = 0; j < 4; ++j) ss += v0[j] * v0[j] + v1[j] * v1[j]; }
;             ss += __shfl_xor(ss, 16); ss += __shfl_xor(ss, 32);
;             if (fq == 0) unsafeAtomicAdd(rss3 + row, ss); __builtin_amdgcn_sched_barrier(0); }
	v_pk_fma_f32 v[48:49], v[104:105], v[102:103], v[80:81]
	global_store_dwordx4 v[118:119], v[42:45], off nt
	global_store_dwordx4 v[118:119], v[46:49], off offset:16 nt
	s_nop 0
	s_nop 0
	v_mul_f32_e32 v46, v46, v46
	v_fmac_f32_e32 v46, v42, v42
	v_mul_f32_e32 v42, v47, v47
	v_fmac_f32_e32 v42, v43, v43
	v_add_f32_e32 v42, v46, v42
	v_mul_f32_e32 v43, v48, v48
	v_lshlrev_b32_e32 v46, 16, v74
	v_and_b32_e32 v47, 0xffff0000, v74
	v_fmac_f32_e32 v43, v44, v44
	v_add_f32_e32 v42, v43, v42
	v_mul_f32_e32 v43, v49, v49
	v_lshlrev_b32_e32 v48, 16, v75
	v_and_b32_e32 v49, 0xffff0000, v75
	v_fmac_f32_e32 v43, v45, v45
	v_add_f32_e32 v78, v43, v42
	v_lshlrev_b32_e32 v42, 16, v76
	v_and_b32_e32 v43, 0xffff0000, v76
	v_lshlrev_b32_e32 v44, 16, v77
	v_and_b32_e32 v45, 0xffff0000, v77
	v_pk_fma_f32 v[34:35], v[34:35], v[94:95], v[232:233] op_sel_hi:[1,0,1]
	v_pk_fma_f32 v[38:39], v[38:39], v[94:95], v[248:249] op_sel_hi:[1,0,1]
	v_mul_f32_e32 v34, 0xbfb8aa3b, v34
	v_pk_fma_f32 v[36:37], v[36:37], v[94:95], v[234:235] op_sel_hi:[1,0,1]
	v_exp_f32_e32 v74, v34
	v_mul_f32_e32 v34, 0xbfb8aa3b, v39
	v_pk_fma_f32 v[40:41], v[40:41], v[94:95], v[250:251] op_sel_hi:[1,0,1]
	v_exp_f32_e32 v39, v34
	v_mul_f32_e32 v34, 0xbfb8aa3b, v35
	v_mul_f32_e32 v35, 0xbfb8aa3b, v36
	v_mul_f32_e32 v38, 0xbfb8aa3b, v38
	v_exp_f32_e32 v75, v34
	v_mul_f32_e32 v34, 0xbfb8aa3b, v40
	v_exp_f32_e32 v36, v35
	v_mul_f32_e32 v35, 0xbfb8aa3b, v41
	v_exp_f32_e32 v38, v38
	v_exp_f32_e32 v34, v34
	v_exp_f32_e32 v35, v35
	v_mul_f32_e32 v37, 0xbfb8aa3b, v37
	v_exp_f32_e32 v37, v37
	v_pk_add_f32 v[40:41], v[34:35], 1.0 op_sel_hi:[1,0]
	v_pk_add_f32 v[34:35], v[38:39], 1.0 op_sel_hi:[1,0]
	v_pk_add_f32 v[36:37], v[36:37], 1.0 op_sel_hi:[1,0]
	v_div_scale_f32 v38, s[2:3], v35, v35, 1.0
	v_rcp_f32_e32 v39, v38
	s_nop 0
	v_fma_f32 v76, -v38, v39, 1.0
	v_fmac_f32_e32 v39, v76, v39
	v_div_scale_f32 v76, vcc, 1.0, v35, 1.0
	v_mul_f32_e32 v77, v76, v39
	v_fma_f32 v79, -v38, v77, v76
	v_fmac_f32_e32 v77, v79, v39
	v_fma_f32 v38, -v38, v77, v76
	v_div_fmas_f32 v38, v38, v39, v77
	v_div_fixup_f32 v35, v38, v35, 1.0
	v_div_scale_f32 v38, s[2:3], v34, v34, 1.0
	v_rcp_f32_e32 v39, v38
	s_nop 0
	v_fma_f32 v76, -v38, v39, 1.0
	v_fmac_f32_e32 v39, v76, v39
	v_div_scale_f32 v76, vcc, 1.0, v34, 1.0
	v_mul_f32_e32 v77, v76, v39
	v_fma_f32 v79, -v38, v77, v76
	v_fmac_f32_e32 v77, v79, v39
	v_fma_f32 v38, -v38, v77, v76
	v_div_fmas_f32 v38, v38, v39, v77
	v_div_fixup_f32 v34, v38, v34, 1.0
	v_div_scale_f32 v38, s[2:3], v41, v41, 1.0
	v_rcp_f32_e32 v39, v38
	v_pk_fma_f32 v[34:35], v[34:35], v[46:47], v[70:71]
	v_fma_f32 v76, -v38, v39, 1.0
	v_fmac_f32_e32 v39, v76, v39
	v_div_scale_f32 v76, vcc, 1.0, v41, 1.0
	v_mul_f32_e32 v77, v76, v39
	v_fma_f32 v79, -v38, v77, v76
	v_fmac_f32_e32 v77, v79, v39
	v_fma_f32 v38, -v38, v77, v76
	v_div_fmas_f32 v38, v38, v39, v77
	v_div_fixup_f32 v39, v38, v41, 1.0
	v_div_scale_f32 v38, s[2:3], v40, v40, 1.0
	v_rcp_f32_e32 v41, v38
	s_nop 0
	v_fma_f32 v76, -v38, v41, 1.0
	v_fmac_f32_e32 v41, v76, v41
	v_div_scale_f32 v76, vcc, 1.0, v40, 1.0
	v_mul_f32_e32 v77, v76, v41
	v_fma_f32 v79, -v38, v77, v76
	v_fmac_f32_e32 v77, v79, v41
	v_fma_f32 v38, -v38, v77, v76
	v_div_fmas_f32 v38, v38, v41, v77
	v_div_fixup_f32 v38, v38, v40, 1.0
	v_pk_add_f32 v[40:41], v[74:75], 1.0 op_sel_hi:[1,0]
	s_nop 0
	v_div_scale_f32 v74, s[2:3], v41, v41, 1.0
	v_rcp_f32_e32 v75, v74
	s_nop 0
	v_fma_f32 v76, -v74, v75, 1.0
	v_fmac_f32_e32 v75, v76, v75
	v_div_scale_f32 v76, vcc, 1.0, v41, 1.0
	v_mul_f32_e32 v77, v76, v75
	v_fma_f32 v79, -v74, v77, v76
	v_fmac_f32_e32 v77, v79, v75
	v_fma_f32 v74, -v74, v77, v76
	v_div_fmas_f32 v74, v74, v75, v77
	v_div_fixup_f32 v75, v74, v41, 1.0
	v_div_scale_f32 v41, s[2:3], v40, v40, 1.0
	v_rcp_f32_e32 v74, v41
	s_nop 0
	v_fma_f32 v76, -v41, v74, 1.0
	v_fmac_f32_e32 v74, v76, v74
	v_div_scale_f32 v76, vcc, 1.0, v40, 1.0
	v_mul_f32_e32 v77, v76, v74
	v_fma_f32 v79, -v41, v77, v76
	v_fmac_f32_e32 v77, v79, v74
	v_fma_f32 v41, -v41, v77, v76
	v_div_fmas_f32 v41, v41, v74, v77
	v_div_fixup_f32 v74, v41, v40, 1.0
	v_div_scale_f32 v40, s[2:3], v37, v37, 1.0
	v_rcp_f32_e32 v41, v40
	s_nop 0
	v_fma_f32 v76, -v40, v41, 1.0
	v_fmac_f32_e32 v41, v76, v41
	v_div_scale_f32 v76, vcc, 1.0, v37, 1.0
	v_mul_f32_e32 v77, v76, v41
	v_fma_f32 v79, -v40, v77, v76
	v_fmac_f32_e32 v77, v79, v41
	v_fma_f32 v40, -v40, v77, v76
	v_div_fmas_f32 v40, v40, v41, v77
	v_div_fixup_f32 v41, v40, v37, 1.0
	v_div_scale_f32 v37, s[2:3], v36, v36, 1.0
	v_rcp_f32_e32 v40, v37
	s_nop 0
	v_fma_f32 v76, -v37, v40, 1.0
	v_fmac_f32_e32 v40, v76, v40
	v_div_scale_f32 v76, vcc, 1.0, v36, 1.0
	v_mul_f32_e32 v77, v76, v40
	v_fma_f32 v79, -v37, v77, v76
	v_fmac_f32_e32 v77, v79, v40
	v_fma_f32 v37, -v37, v77, v76
	v_div_fmas_f32 v37, v37, v40, v77
	v_div_fixup_f32 v40, v37, v36, 1.0
	v_pk_fma_f32 v[36:37], v[38:39], v[48:49], v[72:73]
	v_pk_fma_f32 v[38:39], v[74:75], v[42:43], v[66:67]
	v_pk_fma_f32 v[40:41], v[40:41], v[44:45], v[68:69]
	global_store_dwordx4 v[118:119], v[34:37], off offset:512 nt
	global_store_dwordx4 v[118:119], v[38:41], off offset:528 nt
	s_nop 1
	v_mul_f32_e32 v38, v38, v38
	v_fmac_f32_e32 v38, v34, v34
	v_add_f32_e32 v34, v78, v38
	v_mul_f32_e32 v38, v39, v39
	v_fmac_f32_e32 v38, v35, v35
	v_mul_f32_e32 v35, v40, v40
	v_add_f32_e32 v34, v38, v34
	v_fmac_f32_e32 v35, v36, v36
	v_add_f32_e32 v34, v35, v34
	v_mul_f32_e32 v35, v41, v41
	v_fmac_f32_e32 v35, v37, v37
	v_add_f32_e32 v34, v35, v34
	ds_bpermute_b32 v35, v225, v34
	s_waitcnt lgkmcnt(0)
	v_add_f32_e32 v34, v34, v35
	ds_bpermute_b32 v35, v226, v34
	s_and_saveexec_b64 s[2:3], s[42:43]
	s_cbranch_execz .LBB0_793
	v_lshl_add_u64 v[36:37], v[116:117], 2, s[36:37]
	s_waitcnt lgkmcnt(0)
	v_add_f32_e32 v34, v34, v35
	global_atomic_add_f32 v[36:37], v34, off
; #define NTL(p) __builtin_nontemporal_load((const f32x4*)(p))
; #define NTS(v, p) __builtin_nontemporal_store((v), (f32x4*)(p))
; __device__ __forceinline__ float bf_lo(unsigned w) { return __uint_as_float(w << 16); }
; __device__ __forceinline__ float bf_hi(unsigned w) { return __uint_as_float(w & 0xffff0000u); }
; __device__ __forceinline__ float sigmoidf_(float x) { return 1.0f / (1.0f + __expf(-x)); }
;     __device__ __forceinline__ void operator()(AccT& acc, const Unit& u, int wr, int wc, int fr, int fq) const {
;     ...
;         for (int r = 0; r < 8; ++r) { const int ai = r >> 2, m = r & 3; const int row = row0 + ai * 128 + m * 16;
;             if (r < 7) { const int rn = row0 + ((r + 1) >> 2) * 128 + ((r + 1) & 3) * 16; const float* hn = H + (size_t)rn * DM + col0; const bf16_t* pn = ppbase + (((r + 1) >> 2) * 128 + ((r + 1) & 3) * 16) * 256;
;                 hv[(r + 1) & 1][0] = NTL(hn); hv[(r + 1) & 1][1] = NTL(hn + 4); hv[(r + 1) & 1][2] = NTL(hn + 128); hv[(r + 1) & 1][3] = NTL(hn + 132);
;                 pv[(r + 1) & 1][0] = *(const u32x4*)pn; pv[(r + 1) & 1][1] = *(const u32x4*)(pn + 128); rs[(r + 1) & 1] = rss2[rn]; }
;             float* hp = H + (size_t)row * DM + col0; float ss = 0.f; const float rstd = rsqrtf(rs[r & 1] * (1.0f / DM) + 1e-6f);
; #pragma unroll
;             for (int bj = 0; bj < 2; ++bj) { const u32x4 pw = pv[r & 1][bj];
;                 const f32x4 b0 = *(const f32x4*)(bias + col0 + bj * 128), b1 = *(const f32x4*)(bias + col0 + bj * 128 + 4);
;                 const f32x4 p0 = (f32x4){bf_lo(pw.x), bf_hi(pw.x), bf_lo(pw.y), bf_hi(pw.y)}, p1 = (f32x4){bf_lo(pw.z), bf_hi(pw.z), bf_lo(pw.w), bf_hi(pw.w)};
;                 f32x4 g0 = acc[ai][bj][m][0] * rstd + b0, g1 = acc[ai][bj][m][1] * rstd + b1;
; #pragma unroll
;                 for (int j = 0; j < 4; ++j) { g0[j] = sigmoidf_(g0[j]); g1[j] = sigmoidf_(g1[j]); }
;                 const f32x4 v0 = hv[r & 1][2 * bj] + p0 * g0, v1 = hv[r & 1][2 * bj + 1] + p1 * g1;
;                 NTS(v0, hp + bj * 128); NTS(v1, hp + bj * 128 + 4);
.LBB0_793:
	s_or_b64 exec, exec, s[2:3]
	v_add_u32_e32 v74, 0xb0, v186
	v_ashrrev_i32_e32 v75, 31, v74
	s_waitcnt lgkmcnt(0)
	v_lshlrev_b64 v[34:35], 12, v[74:75]
	v_lshl_add_u64 v[34:35], s[22:23], 0, v[34:35]
	v_add_co_u32_e32 v42, vcc, 0x16000, v190
	v_lshl_add_u64 v[76:77], v[192:193], 2, v[34:35]
	s_nop 0
	v_addc_co_u32_e32 v43, vcc, 0, v191, vcc
	global_load_dwordx4 v[46:49], v[76:77], off offset:16 nt
	global_load_dwordx4 v[66:69], v[76:77], off nt
	global_load_dwordx4 v[34:37], v[76:77], off offset:528 nt
	global_load_dwordx4 v[38:41], v[76:77], off offset:512 nt
	global_load_dwordx4 v[70:73], v[42:43], off
	s_nop 0
	global_load_dwordx4 v[42:45], v[42:43], off offset:256
	s_nop 0
	global_load_dword v79, v[188:189], off offset:704
	s_waitcnt vmcnt(11)
	v_fmamk_f32 v78, v95, 0x3a800000, v210
	v_cmp_gt_f32_e32 vcc, s30, v78
	v_mul_f32_e32 v80, 0x4b800000, v78
	v_and_b32_e32 v81, 0xffff0000, v88
	v_cndmask_b32_e32 v78, v78, v80, vcc
	v_rsq_f32_e32 v78, v78
	v_lshlrev_b32_e32 v94, 16, v86
	v_and_b32_e32 v95, 0xffff0000, v86
	v_lshlrev_b32_e32 v96, 16, v87
	v_mul_f32_e32 v80, 0x45800000, v78
	v_cndmask_b32_e32 v78, v78, v80, vcc
	v_lshlrev_b32_e32 v80, 16, v88
	v_and_b32_e32 v97, 0xffff0000, v87
	v_lshlrev_b32_e32 v86, 16, v89
	v_and_b32_e32 v87, 0xffff0000, v89
	v_pk_fma_f32 v[26:27], v[26:27], v[78:79], v[244:245] op_sel_hi:[1,0,1]
	v_pk_fma_f32 v[30:31], v[30:31], v[78:79], v[240:241] op_sel_hi:[1,0,1]
	v_mul_f32_e32 v26, 0xbfb8aa3b, v26
	v_mul_f32_e32 v30, 0xbfb8aa3b, v30
	v_pk_fma_f32 v[28:29], v[28:29], v[78:79], v[246:247] op_sel_hi:[1,0,1]
	v_exp_f32_e32 v88, v30
	v_exp_f32_e32 v30, v26
	v_mul_f32_e32 v26, 0xbfb8aa3b, v31
	v_pk_fma_f32 v[32:33], v[32:33], v[78:79], v[242:243] op_sel_hi:[1,0,1]
	v_exp_f32_e32 v89, v26
	v_mul_f32_e32 v26, 0xbfb8aa3b, v27
	v_mul_f32_e32 v27, 0xbfb8aa3b, v28
	v_exp_f32_e32 v31, v26
	v_mul_f32_e32 v26, 0xbfb8aa3b, v32
	v_exp_f32_e32 v28, v27
	v_mul_f32_e32 v27, 0xbfb8aa3b, v33
	v_exp_f32_e32 v26, v26
	v_exp_f32_e32 v27, v27
	v_pk_add_f32 v[30:31], v[30:31], 1.0 op_sel_hi:[1,0]
	v_mul_f32_e32 v29, 0xbfb8aa3b, v29
	v_exp_f32_e32 v29, v29
	v_pk_add_f32 v[32:33], v[26:27], 1.0 op_sel_hi:[1,0]
	v_pk_add_f32 v[26:27], v[88:89], 1.0 op_sel_hi:[1,0]
	v_pk_add_f32 v[28:29], v[28:29], 1.0 op_sel_hi:[1,0]
	v_div_scale_f32 v88, s[2:3], v27, v27, 1.0
	v_rcp_f32_e32 v89, v88
	s_nop 0
	v_fma_f32 v98, -v88, v89, 1.0
	v_fmac_f32_e32 v89, v98, v89
	v_div_scale_f32 v98, vcc, 1.0, v27, 1.0
	v_mul_f32_e32 v99, v98, v89
	v_fma_f32 v100, -v88, v99, v98
	v_fmac_f32_e32 v99, v100, v89
	v_fma_f32 v88, -v88, v99, v98
	v_div_fmas_f32 v88, v88, v89, v99
	v_div_fixup_f32 v27, v88, v27, 1.0
	v_div_scale_f32 v88, s[2:3], v26, v26, 1.0
	v_rcp_f32_e32 v89, v88
	s_nop 0
	v_fma_f32 v98, -v88, v89, 1.0
	v_fmac_f32_e32 v89, v98, v89
	v_div_scale_f32 v98, vcc, 1.0, v26, 1.0
	v_mul_f32_e32 v99, v98, v89
	v_fma_f32 v100, -v88, v99, v98
	v_fmac_f32_e32 v99, v100, v89
	v_fma_f32 v88, -v88, v99, v98
	v_div_fmas_f32 v88, v88, v89, v99
	v_div_fixup_f32 v26, v88, v26, 1.0
	v_div_scale_f32 v88, s[2:3], v33, v33, 1.0
	v_rcp_f32_e32 v89, v88
	v_pk_fma_f32 v[26:27], v[26:27], v[94:95], v[82:83]
	v_fma_f32 v98, -v88, v89, 1.0
	v_fmac_f32_e32 v89, v98, v89
	v_div_scale_f32 v98, vcc, 1.0, v33, 1.0
	v_mul_f32_e32 v99, v98, v89
	v_fma_f32 v100, -v88, v99, v98
	v_fmac_f32_e32 v99, v100, v89
	v_fma_f32 v88, -v88, v99, v98
	v_div_fmas_f32 v88, v88, v89, v99
	v_div_fixup_f32 v33, v88, v33, 1.0
	v_div_scale_f32 v88, s[2:3], v32, v32, 1.0
	v_rcp_f32_e32 v89, v88
	s_nop 0
	v_fma_f32 v98, -v88, v89, 1.0
	v_fmac_f32_e32 v89, v98, v89
	v_div_scale_f32 v98, vcc, 1.0, v32, 1.0
	v_mul_f32_e32 v99, v98, v89
	v_fma_f32 v100, -v88, v99, v98
	v_fmac_f32_e32 v99, v100, v89
	v_fma_f32 v88, -v88, v99, v98
	v_div_fmas_f32 v88, v88, v89, v99
	v_div_fixup_f32 v32, v88, v32, 1.0
	v_div_scale_f32 v88, s[2:3], v31, v31, 1.0
	v_rcp_f32_e32 v89, v88
	s_nop 0
	v_fma_f32 v98, -v88, v89, 1.0
	v_fmac_f32_e32 v89, v98, v89
	v_div_scale_f32 v98, vcc, 1.0, v31, 1.0
	v_mul_f32_e32 v99, v98, v89
	v_fma_f32 v100, -v88, v99, v98
	v_fmac_f32_e32 v99, v100, v89
	v_fma_f32 v88, -v88, v99, v98
	v_div_fmas_f32 v88, v88, v89, v99
	v_div_fixup_f32 v31, v88, v31, 1.0
	v_div_scale_f32 v88, s[2:3], v30, v30, 1.0
	v_rcp_f32_e32 v89, v88
	s_nop 0
	v_fma_f32 v98, -v88, v89, 1.0
	v_fmac_f32_e32 v89, v98, v89
	v_div_scale_f32 v98, vcc, 1.0, v30, 1.0
	v_mul_f32_e32 v99, v98, v89
	v_fma_f32 v100, -v88, v99, v98
	v_fmac_f32_e32 v99, v100, v89
	v_fma_f32 v88, -v88, v99, v98
	v_div_fmas_f32 v88, v88, v89, v99
	v_div_fixup_f32 v30, v88, v30, 1.0
	v_div_scale_f32 v88, s[2:3], v29, v29, 1.0
	v_rcp_f32_e32 v89, v88
	v_pk_fma_f32 v[30:31], v[30:31], v[80:81], v[62:63]
	v_fma_f32 v98, -v88, v89, 1.0
	v_fmac_f32_e32 v89, v98, v89
	v_div_scale_f32 v98, vcc, 1.0, v29, 1.0
	v_mul_f32_e32 v99, v98, v89
	v_fma_f32 v100, -v88, v99, v98
	v_fmac_f32_e32 v99, v100, v89
	v_fma_f32 v88, -v88, v99, v98
	v_div_fmas_f32 v88, v88, v89, v99
	v_div_fixup_f32 v89, v88, v29, 1.0
	v_div_scale_f32 v29, s[2:3], v28, v28, 1.0
	v_rcp_f32_e32 v88, v29
	s_nop 0
	v_fma_f32 v98, -v29, v88, 1.0
	v_fmac_f32_e32 v88, v98, v88
	v_div_scale_f32 v98, vcc, 1.0, v28, 1.0
	v_mul_f32_e32 v99, v98, v88
	v_fma_f32 v100, -v29, v99, v98
	v_fmac_f32_e32 v99, v100, v88
	v_fma_f32 v29, -v29, v99, v98
	v_div_fmas_f32 v29, v29, v88, v99
	v_div_fixup_f32 v88, v29, v28, 1.0
	v_pk_fma_f32 v[28:29], v[32:33], v[96:97], v[84:85]
	v_pk_fma_f32 v[32:33], v[88:89], v[86:87], v[64:65]
	global_store_dwordx4 v[92:93], v[26:29], off nt
	global_store_dwordx4 v[92:93], v[30:33], off offset:16 nt
	s_nop 0
	s_nop 0
	v_mul_f32_e32 v30, v30, v30
	v_fmac_f32_e32 v30, v26, v26
; #define NTS(v, p) __builtin_nontemporal_store((v), (f32x4*)(p))
; __device__ __forceinline__ float bf_lo(unsigned w) { return __uint_as_float(w << 16); }
; __device__ __forceinline__ float bf_hi(unsigned w) { return __uint_as_float(w & 0xffff0000u); }
; __device__ __forceinline__ float sigmoidf_(float x) { return 1.0f / (1.0f + __expf(-x)); }
;     __device__ __forceinline__ void operator()(AccT& acc, const Unit& u, int wr, int wc, int fr, int fq) const {
;     ...
;             float* hp = H + (size_t)row * DM + col0; float ss = 0.f; const float rstd = rsqrtf(rs[r & 1] * (1.0f / DM) + 1e-6f);
; #pragma unroll
;             for (int bj = 0; bj < 2; ++bj) { const u32x4 pw = pv[r & 1][bj];
;                 const f32x4 b0 = *(const f32x4*)(bias + col0 + bj * 128), b1 = *(const f32x4*)(bias + col0 + bj * 128 + 4);
;                 const f32x4 p0 = (f32x4){bf_lo(pw.x), bf_hi(pw.x), bf_lo(pw.y), bf_hi(pw.y)}, p1 = (f32x4){bf_lo(pw.z), bf_hi(pw.z), bf_lo(pw.w), bf_hi(pw.w)};
;                 f32x4 g0 = acc[ai][bj][m][0] * rstd + b0, g1 = acc[ai][bj][m][1] * rstd + b1;
; #pragma unroll
;                 for (int j = 0; j < 4; ++j) { g0[j] = sigmoidf_(g0[j]); g1[j] = sigmoidf_(g1[j]); }
;                 const f32x4 v0 = hv[r & 1][2 * bj] + p0 * g0, v1 = hv[r & 1][2 * bj + 1] + p1 * g1;
;                 NTS(v0, hp + bj * 128); NTS(v1, hp + bj * 128 + 4);
; #pragma unroll
;                 for (int j = 0; j < 4; ++j) ss += v0[j] * v0[j] + v1[j] * v1[j]; }
;             ss += __shfl_xor(ss, 16); ss += __shfl_xor(ss, 32);
;             if (fq == 0) unsafeAtomicAdd(rss3 + row, ss); __builtin_amdgcn_sched_barrier(0); }
	v_mul_f32_e32 v26, v31, v31
	v_fmac_f32_e32 v26, v27, v27
	v_add_f32_e32 v26, v30, v26
	v_mul_f32_e32 v27, v32, v32
	v_lshlrev_b32_e32 v30, 16, v58
	v_and_b32_e32 v31, 0xffff0000, v58
	v_fmac_f32_e32 v27, v28, v28
	v_add_f32_e32 v26, v27, v26
	v_mul_f32_e32 v27, v33, v33
	v_lshlrev_b32_e32 v32, 16, v59
	v_and_b32_e32 v33, 0xffff0000, v59
	v_fmac_f32_e32 v27, v29, v29
	v_add_f32_e32 v62, v27, v26
	v_lshlrev_b32_e32 v26, 16, v60
	v_and_b32_e32 v27, 0xffff0000, v60
	v_lshlrev_b32_e32 v28, 16, v61
	v_and_b32_e32 v29, 0xffff0000, v61
	v_pk_fma_f32 v[18:19], v[18:19], v[78:79], v[232:233] op_sel_hi:[1,0,1]
	v_pk_fma_f32 v[22:23], v[22:23], v[78:79], v[248:249] op_sel_hi:[1,0,1]
	v_mul_f32_e32 v18, 0xbfb8aa3b, v18
	v_pk_fma_f32 v[20:21], v[20:21], v[78:79], v[234:235] op_sel_hi:[1,0,1]
	v_exp_f32_e32 v58, v18
	v_mul_f32_e32 v18, 0xbfb8aa3b, v23
	v_pk_fma_f32 v[24:25], v[24:25], v[78:79], v[250:251] op_sel_hi:[1,0,1]
	v_exp_f32_e32 v23, v18
	v_mul_f32_e32 v18, 0xbfb8aa3b, v19
	v_mul_f32_e32 v19, 0xbfb8aa3b, v20
	v_mul_f32_e32 v22, 0xbfb8aa3b, v22
	v_exp_f32_e32 v59, v18
	v_mul_f32_e32 v18, 0xbfb8aa3b, v24
	v_exp_f32_e32 v20, v19
	v_mul_f32_e32 v19, 0xbfb8aa3b, v25
	v_exp_f32_e32 v22, v22
	v_exp_f32_e32 v18, v18
	v_exp_f32_e32 v19, v19
	v_mul_f32_e32 v21, 0xbfb8aa3b, v21
	v_exp_f32_e32 v21, v21
	v_pk_add_f32 v[24:25], v[18:19], 1.0 op_sel_hi:[1,0]
	v_pk_add_f32 v[18:19], v[22:23], 1.0 op_sel_hi:[1,0]
	v_pk_add_f32 v[20:21], v[20:21], 1.0 op_sel_hi:[1,0]
	v_div_scale_f32 v22, s[2:3], v19, v19, 1.0
	v_rcp_f32_e32 v23, v22
	s_nop 0
	v_fma_f32 v60, -v22, v23, 1.0
	v_fmac_f32_e32 v23, v60, v23
	v_div_scale_f32 v60, vcc, 1.0, v19, 1.0
	v_mul_f32_e32 v61, v60, v23
	v_fma_f32 v63, -v22, v61, v60
	v_fmac_f32_e32 v61, v63, v23
	v_fma_f32 v22, -v22, v61, v60
	v_div_fmas_f32 v22, v22, v23, v61
	v_div_fixup_f32 v19, v22, v19, 1.0
	v_div_scale_f32 v22, s[2:3], v18, v18, 1.0
	v_rcp_f32_e32 v23, v22
	s_nop 0
	v_fma_f32 v60, -v22, v23, 1.0
	v_fmac_f32_e32 v23, v60, v23
	v_div_scale_f32 v60, vcc, 1.0, v18, 1.0
	v_mul_f32_e32 v61, v60, v23
	v_fma_f32 v63, -v22, v61, v60
	v_fmac_f32_e32 v61, v63, v23
	v_fma_f32 v22, -v22, v61, v60
	v_div_fmas_f32 v22, v22, v23, v61
	v_div_fixup_f32 v18, v22, v18, 1.0
	v_div_scale_f32 v22, s[2:3], v25, v25, 1.0
	v_rcp_f32_e32 v23, v22
	v_pk_fma_f32 v[18:19], v[18:19], v[30:31], v[54:55]
	v_fma_f32 v60, -v22, v23, 1.0
	v_fmac_f32_e32 v23, v60, v23
	v_div_scale_f32 v60, vcc, 1.0, v25, 1.0
	v_mul_f32_e32 v61, v60, v23
	v_fma_f32 v63, -v22, v61, v60
	v_fmac_f32_e32 v61, v63, v23
	v_fma_f32 v22, -v22, v61, v60
	v_div_fmas_f32 v22, v22, v23, v61
	v_div_fixup_f32 v23, v22, v25, 1.0
	v_div_scale_f32 v22, s[2:3], v24, v24, 1.0
	v_rcp_f32_e32 v25, v22
	s_nop 0
	v_fma_f32 v60, -v22, v25, 1.0
	v_fmac_f32_e32 v25, v60, v25
	v_div_scale_f32 v60, vcc, 1.0, v24, 1.0
	v_mul_f32_e32 v61, v60, v25
	v_fma_f32 v63, -v22, v61, v60
	v_fmac_f32_e32 v61, v63, v25
	v_fma_f32 v22, -v22, v61, v60
	v_div_fmas_f32 v22, v22, v25, v61
	v_div_fixup_f32 v22, v22, v24, 1.0
	v_pk_add_f32 v[24:25], v[58:59], 1.0 op_sel_hi:[1,0]
	s_nop 0
	v_div_scale_f32 v58, s[2:3], v25, v25, 1.0
	v_rcp_f32_e32 v59, v58
	s_nop 0
	v_fma_f32 v60, -v58, v59, 1.0
	v_fmac_f32_e32 v59, v60, v59
	v_div_scale_f32 v60, vcc, 1.0, v25, 1.0
	v_mul_f32_e32 v61, v60, v59
	v_fma_f32 v63, -v58, v61, v60
	v_fmac_f32_e32 v61, v63, v59
	v_fma_f32 v58, -v58, v61, v60
	v_div_fmas_f32 v58, v58, v59, v61
	v_div_fixup_f32 v59, v58, v25, 1.0
	v_div_scale_f32 v25, s[2:3], v24, v24, 1.0
	v_rcp_f32_e32 v58, v25
	s_nop 0
	v_fma_f32 v60, -v25, v58, 1.0
	v_fmac_f32_e32 v58, v60, v58
	v_div_scale_f32 v60, vcc, 1.0, v24, 1.0
	v_mul_f32_e32 v61, v60, v58
	v_fma_f32 v63, -v25, v61, v60
	v_fmac_f32_e32 v61, v63, v58
	v_fma_f32 v25, -v25, v61, v60
	v_div_fmas_f32 v25, v25, v58, v61
	v_div_fixup_f32 v58, v25, v24, 1.0
	v_div_scale_f32 v24, s[2:3], v21, v21, 1.0
	v_rcp_f32_e32 v25, v24
	s_nop 0
	v_fma_f32 v60, -v24, v25, 1.0
	v_fmac_f32_e32 v25, v60, v25
	v_div_scale_f32 v60, vcc, 1.0, v21, 1.0
	v_mul_f32_e32 v61, v60, v25
	v_fma_f32 v63, -v24, v61, v60
	v_fmac_f32_e32 v61, v63, v25
	v_fma_f32 v24, -v24, v61, v60
	v_div_fmas_f32 v24, v24, v25, v61
	v_div_fixup_f32 v25, v24, v21, 1.0
	v_div_scale_f32 v21, s[2:3], v20, v20, 1.0
	v_rcp_f32_e32 v24, v21
	s_nop 0
	v_fma_f32 v60, -v21, v24, 1.0
	v_fmac_f32_e32 v24, v60, v24
	v_div_scale_f32 v60, vcc, 1.0, v20, 1.0
	v_mul_f32_e32 v61, v60, v24
	v_fma_f32 v63, -v21, v61, v60
	v_fmac_f32_e32 v61, v63, v24
	v_fma_f32 v21, -v21, v61, v60
	v_div_fmas_f32 v21, v21, v24, v61
	v_div_fixup_f32 v24, v21, v20, 1.0
	v_pk_fma_f32 v[20:21], v[22:23], v[32:33], v[56:57]
	v_pk_fma_f32 v[22:23], v[58:59], v[26:27], v[50:51]
	v_pk_fma_f32 v[24:25], v[24:25], v[28:29], v[52:53]
	global_store_dwordx4 v[92:93], v[18:21], off offset:512 nt
	global_store_dwordx4 v[92:93], v[22:25], off offset:528 nt
	s_nop 1
	v_mul_f32_e32 v22, v22, v22
	v_fmac_f32_e32 v22, v18, v18
	v_add_f32_e32 v18, v62, v22
	v_mul_f32_e32 v22, v23, v23
	v_fmac_f32_e32 v22, v19, v19
	v_mul_f32_e32 v19, v24, v24
	v_add_f32_e32 v18, v22, v18
	v_fmac_f32_e32 v19, v20, v20
	v_add_f32_e32 v18, v19, v18
	v_mul_f32_e32 v19, v25, v25
	v_fmac_f32_e32 v19, v21, v21
	v_add_f32_e32 v18, v19, v18
	ds_bpermute_b32 v19, v225, v18
	s_waitcnt lgkmcnt(0)
	v_add_f32_e32 v18, v18, v19
	ds_bpermute_b32 v19, v226, v18
	s_and_saveexec_b64 s[2:3], s[42:43]
	s_cbranch_execz .LBB0_795
	v_lshl_add_u64 v[20:21], v[90:91], 2, s[36:37]
	s_waitcnt lgkmcnt(0)
	v_add_f32_e32 v18, v18, v19
	global_atomic_add_f32 v[20:21], v18, off
; #define NTS(v, p) __builtin_nontemporal_store((v), (f32x4*)(p))
; __device__ __forceinline__ float bf_lo(unsigned w) { return __uint_as_float(w << 16); }
; __device__ __forceinline__ float bf_hi(unsigned w) { return __uint_as_float(w & 0xffff0000u); }
; __device__ __forceinline__ float sigmoidf_(float x) { return 1.0f / (1.0f + __expf(-x)); }
;     __device__ __forceinline__ void operator()(AccT& acc, const Unit& u, int wr, int wc, int fr, int fq) const {
;     ...
;             float* hp = H + (size_t)row * DM + col0; float ss = 0.f; const float rstd = rsqrtf(rs[r & 1] * (1.0f / DM) + 1e-6f);
; #pragma unroll
;             for (int bj = 0; bj < 2; ++bj) { const u32x4 pw = pv[r & 1][bj];
;                 const f32x4 b0 = *(const f32x4*)(bias + col0 + bj * 128), b1 = *(const f32x4*)(bias + col0 + bj * 128 + 4);
;                 const f32x4 p0 = (f32x4){bf_lo(pw.x), bf_hi(pw.x), bf_lo(pw.y), bf_hi(pw.y)}, p1 = (f32x4){bf_lo(pw.z), bf_hi(pw.z), bf_lo(pw.w), bf_hi(pw.w)};
;                 f32x4 g0 = acc[ai][bj][m][0] * rstd + b0, g1 = acc[ai][bj][m][1] * rstd + b1;
; #pragma unroll
;                 for (int j = 0; j < 4; ++j) { g0[j] = sigmoidf_(g0[j]); g1[j] = sigmoidf_(g1[j]); }
;                 const f32x4 v0 = hv[r & 1][2 * bj] + p0 * g0, v1 = hv[r & 1][2 * bj + 1] + p1 * g1;
;                 NTS(v0, hp + bj * 128); NTS(v1, hp + bj * 128 + 4);
; #pragma unroll
;                 for (int j = 0; j < 4; ++j) ss += v0[j] * v0[j] + v1[j] * v1[j]; }
.LBB0_795:
	s_or_b64 exec, exec, s[2:3]
	s_waitcnt vmcnt(4)
	v_fmamk_f32 v18, v79, 0x3a800000, v210
	v_cmp_gt_f32_e32 vcc, s30, v18
	s_waitcnt lgkmcnt(0)
	v_mul_f32_e32 v19, 0x4b800000, v18
	v_lshlrev_b32_e32 v22, 16, v70
	v_cndmask_b32_e32 v18, v18, v19, vcc
	v_rsq_f32_e32 v18, v18
	v_and_b32_e32 v23, 0xffff0000, v70
	v_lshlrev_b32_e32 v24, 16, v71
	v_and_b32_e32 v25, 0xffff0000, v71
	v_mul_f32_e32 v19, 0x45800000, v18
	v_cndmask_b32_e32 v18, v18, v19, vcc
	v_lshlrev_b32_e32 v20, 16, v72
	v_and_b32_e32 v21, 0xffff0000, v72
	v_lshlrev_b32_e32 v26, 16, v73
	v_and_b32_e32 v27, 0xffff0000, v73
	v_pk_fma_f32 v[10:11], v[10:11], v[18:19], v[244:245] op_sel_hi:[1,0,1]
	v_pk_fma_f32 v[14:15], v[14:15], v[18:19], v[240:241] op_sel_hi:[1,0,1]
	v_mul_f32_e32 v10, 0xbfb8aa3b, v10
	v_pk_fma_f32 v[32:33], v[16:17], v[18:19], v[242:243] op_sel_hi:[1,0,1]
	v_pk_fma_f32 v[16:17], v[12:13], v[18:19], v[246:247] op_sel_hi:[1,0,1]
	v_mul_f32_e32 v12, 0xbfb8aa3b, v14
	v_exp_f32_e32 v14, v10
	v_mul_f32_e32 v10, 0xbfb8aa3b, v15
	v_exp_f32_e32 v13, v10
	v_mul_f32_e32 v10, 0xbfb8aa3b, v11
	v_mul_f32_e32 v11, 0xbfb8aa3b, v16
	v_exp_f32_e32 v15, v10
	v_mul_f32_e32 v10, 0xbfb8aa3b, v32
	v_exp_f32_e32 v16, v11
	v_mul_f32_e32 v11, 0xbfb8aa3b, v33
	v_exp_f32_e32 v12, v12
	v_exp_f32_e32 v10, v10
	v_exp_f32_e32 v11, v11
	v_pk_add_f32 v[14:15], v[14:15], 1.0 op_sel_hi:[1,0]
	v_mul_f32_e32 v17, 0xbfb8aa3b, v17
	v_exp_f32_e32 v17, v17
	v_pk_add_f32 v[28:29], v[10:11], 1.0 op_sel_hi:[1,0]
	v_pk_add_f32 v[10:11], v[12:13], 1.0 op_sel_hi:[1,0]
	v_pk_add_f32 v[16:17], v[16:17], 1.0 op_sel_hi:[1,0]
	v_div_scale_f32 v12, s[2:3], v11, v11, 1.0
	v_rcp_f32_e32 v13, v12
	s_nop 0
	v_fma_f32 v19, -v12, v13, 1.0
	v_fmac_f32_e32 v13, v19, v13
	v_div_scale_f32 v19, vcc, 1.0, v11, 1.0
	v_mul_f32_e32 v30, v19, v13
	v_fma_f32 v31, -v12, v30, v19
	v_fmac_f32_e32 v30, v31, v13
	v_fma_f32 v12, -v12, v30, v19
	v_div_fmas_f32 v12, v12, v13, v30
	v_div_fixup_f32 v11, v12, v11, 1.0
	v_div_scale_f32 v12, s[2:3], v10, v10, 1.0
	v_rcp_f32_e32 v13, v12
	s_nop 0
	v_fma_f32 v19, -v12, v13, 1.0
	v_fmac_f32_e32 v13, v19, v13
	v_div_scale_f32 v19, vcc, 1.0, v10, 1.0
	v_mul_f32_e32 v30, v19, v13
	v_fma_f32 v31, -v12, v30, v19
	v_fmac_f32_e32 v30, v31, v13
	v_fma_f32 v12, -v12, v30, v19
	v_div_fmas_f32 v12, v12, v13, v30
	v_div_fixup_f32 v10, v12, v10, 1.0
	v_div_scale_f32 v12, s[2:3], v29, v29, 1.0
	v_rcp_f32_e32 v13, v12
	v_pk_fma_f32 v[10:11], v[10:11], v[22:23], v[66:67]
	v_fma_f32 v19, -v12, v13, 1.0
	v_fmac_f32_e32 v13, v19, v13
	v_div_scale_f32 v19, vcc, 1.0, v29, 1.0
	v_mul_f32_e32 v30, v19, v13
	v_fma_f32 v31, -v12, v30, v19
	v_fmac_f32_e32 v30, v31, v13
	v_fma_f32 v12, -v12, v30, v19
	v_div_fmas_f32 v12, v12, v13, v30
	v_div_fixup_f32 v13, v12, v29, 1.0
	v_div_scale_f32 v12, s[2:3], v28, v28, 1.0
	v_rcp_f32_e32 v19, v12
	s_nop 0
	v_fma_f32 v29, -v12, v19, 1.0
	v_fmac_f32_e32 v19, v29, v19
	v_div_scale_f32 v29, vcc, 1.0, v28, 1.0
	v_mul_f32_e32 v30, v29, v19
	v_fma_f32 v31, -v12, v30, v29
	v_fmac_f32_e32 v30, v31, v19
	v_fma_f32 v12, -v12, v30, v29
	v_div_fmas_f32 v12, v12, v19, v30
	v_div_scale_f32 v19, s[2:3], v15, v15, 1.0
	v_div_fixup_f32 v12, v12, v28, 1.0
	v_rcp_f32_e32 v28, v19
	v_pk_fma_f32 v[12:13], v[12:13], v[24:25], v[68:69]
	v_fma_f32 v29, -v19, v28, 1.0
	v_fmac_f32_e32 v28, v29, v28
	v_div_scale_f32 v29, vcc, 1.0, v15, 1.0
	v_mul_f32_e32 v30, v29, v28
	v_fma_f32 v31, -v19, v30, v29
	v_fmac_f32_e32 v30, v31, v28
	v_fma_f32 v19, -v19, v30, v29
	v_div_fmas_f32 v19, v19, v28, v30
	v_div_fixup_f32 v15, v19, v15, 1.0
	v_div_scale_f32 v19, s[2:3], v14, v14, 1.0
	v_rcp_f32_e32 v28, v19
	s_nop 0
	v_fma_f32 v29, -v19, v28, 1.0
	v_fmac_f32_e32 v28, v29, v28
	v_div_scale_f32 v29, vcc, 1.0, v14, 1.0
	v_mul_f32_e32 v30, v29, v28
	v_fma_f32 v31, -v19, v30, v29
	v_fmac_f32_e32 v30, v31, v28
	v_fma_f32 v19, -v19, v30, v29
	v_div_fmas_f32 v19, v19, v28, v30
	v_div_fixup_f32 v14, v19, v14, 1.0
	v_div_scale_f32 v19, s[2:3], v17, v17, 1.0
	v_rcp_f32_e32 v28, v19
	v_pk_fma_f32 v[14:15], v[14:15], v[20:21], v[46:47]
	v_fma_f32 v29, -v19, v28, 1.0
	v_fmac_f32_e32 v28, v29, v28
	v_div_scale_f32 v29, vcc, 1.0, v17, 1.0
	v_mul_f32_e32 v30, v29, v28
	v_fma_f32 v31, -v19, v30, v29
	v_fmac_f32_e32 v30, v31, v28
	v_fma_f32 v19, -v19, v30, v29
	v_div_fmas_f32 v19, v19, v28, v30
	v_div_fixup_f32 v17, v19, v17, 1.0
	v_div_scale_f32 v19, s[2:3], v16, v16, 1.0
	v_rcp_f32_e32 v28, v19
	s_nop 0
	v_fma_f32 v29, -v19, v28, 1.0
	v_fmac_f32_e32 v28, v29, v28
	v_div_scale_f32 v29, vcc, 1.0, v16, 1.0
	v_mul_f32_e32 v30, v29, v28
	v_fma_f32 v31, -v19, v30, v29
	v_fmac_f32_e32 v30, v31, v28
	v_fma_f32 v19, -v19, v30, v29
	v_div_fmas_f32 v19, v19, v28, v30
	v_div_fixup_f32 v16, v19, v16, 1.0
	v_pk_fma_f32 v[16:17], v[16:17], v[26:27], v[48:49]
	global_store_dwordx4 v[76:77], v[10:13], off nt
	global_store_dwordx4 v[76:77], v[14:17], off offset:16 nt
	s_nop 0
	s_nop 0
	v_mul_f32_e32 v14, v14, v14
	v_fmac_f32_e32 v14, v10, v10
	v_mul_f32_e32 v10, v15, v15
	v_fmac_f32_e32 v10, v11, v11
	v_mul_f32_e32 v11, v16, v16
	v_add_f32_e32 v10, v14, v10
	v_fmac_f32_e32 v11, v12, v12
	v_add_f32_e32 v10, v11, v10
; #define NTS(v, p) __builtin_nontemporal_store((v), (f32x4*)(p))
; __device__ __forceinline__ float bf_lo(unsigned w) { return __uint_as_float(w << 16); }
; __device__ __forceinline__ float bf_hi(unsigned w) { return __uint_as_float(w & 0xffff0000u); }
; __device__ __forceinline__ float sigmoidf_(float x) { return 1.0f / (1.0f + __expf(-x)); }
;     __device__ __forceinline__ void operator()(AccT& acc, const Unit& u, int wr, int wc, int fr, int fq) const {
;     ...
;             for (int bj = 0; bj < 2; ++bj) { const u32x4 pw = pv[r & 1][bj];
;                 const f32x4 b0 = *(const f32x4*)(bias + col0 + bj * 128), b1 = *(const f32x4*)(bias + col0 + bj * 128 + 4);
;                 const f32x4 p0 = (f32x4){bf_lo(pw.x), bf_hi(pw.x), bf_lo(pw.y), bf_hi(pw.y)}, p1 = (f32x4){bf_lo(pw.z), bf_hi(pw.z), bf_lo(pw.w), bf_hi(pw.w)};
;                 f32x4 g0 = acc[ai][bj][m][0] * rstd + b0, g1 = acc[ai][bj][m][1] * rstd + b1;
; #pragma unroll
;                 for (int j = 0; j < 4; ++j) { g0[j] = sigmoidf_(g0[j]); g1[j] = sigmoidf_(g1[j]); }
;                 const f32x4 v0 = hv[r & 1][2 * bj] + p0 * g0, v1 = hv[r & 1][2 * bj + 1] + p1 * g1;
;                 NTS(v0, hp + bj * 128); NTS(v1, hp + bj * 128 + 4);
; #pragma unroll
;                 for (int j = 0; j < 4; ++j) ss += v0[j] * v0[j] + v1[j] * v1[j]; }
;             ss += __shfl_xor(ss, 16); ss += __shfl_xor(ss, 32);
;             if (fq == 0) unsafeAtomicAdd(rss3 + row, ss); __builtin_amdgcn_sched_barrier(0); }
	v_mul_f32_e32 v11, v17, v17
	v_fmac_f32_e32 v11, v13, v13
	v_add_f32_e32 v19, v11, v10
	v_lshlrev_b32_e32 v14, 16, v42
	v_and_b32_e32 v15, 0xffff0000, v42
	v_lshlrev_b32_e32 v16, 16, v43
	v_and_b32_e32 v17, 0xffff0000, v43
	v_lshlrev_b32_e32 v10, 16, v44
	v_and_b32_e32 v11, 0xffff0000, v44
	v_lshlrev_b32_e32 v12, 16, v45
	v_and_b32_e32 v13, 0xffff0000, v45
	v_pk_fma_f32 v[2:3], v[2:3], v[18:19], v[232:233] op_sel_hi:[1,0,1]
	v_pk_fma_f32 v[6:7], v[6:7], v[18:19], v[248:249] op_sel_hi:[1,0,1]
	v_mul_f32_e32 v2, 0xbfb8aa3b, v2
	v_pk_fma_f32 v[4:5], v[4:5], v[18:19], v[234:235] op_sel_hi:[1,0,1]
	v_exp_f32_e32 v20, v2
	v_mul_f32_e32 v2, 0xbfb8aa3b, v7
	v_pk_fma_f32 v[8:9], v[8:9], v[18:19], v[250:251] op_sel_hi:[1,0,1]
	v_exp_f32_e32 v7, v2
	v_mul_f32_e32 v2, 0xbfb8aa3b, v3
	v_mul_f32_e32 v3, 0xbfb8aa3b, v4
	v_mul_f32_e32 v6, 0xbfb8aa3b, v6
	v_exp_f32_e32 v21, v2
	v_mul_f32_e32 v2, 0xbfb8aa3b, v8
	v_exp_f32_e32 v4, v3
	v_mul_f32_e32 v3, 0xbfb8aa3b, v9
	v_exp_f32_e32 v6, v6
	v_exp_f32_e32 v2, v2
	v_exp_f32_e32 v3, v3
	v_mul_f32_e32 v5, 0xbfb8aa3b, v5
	v_exp_f32_e32 v5, v5
	v_pk_add_f32 v[8:9], v[2:3], 1.0 op_sel_hi:[1,0]
	v_pk_add_f32 v[2:3], v[6:7], 1.0 op_sel_hi:[1,0]
	v_pk_add_f32 v[4:5], v[4:5], 1.0 op_sel_hi:[1,0]
	v_div_scale_f32 v6, s[2:3], v3, v3, 1.0
	v_rcp_f32_e32 v7, v6
	s_nop 0
	v_fma_f32 v18, -v6, v7, 1.0
	v_fmac_f32_e32 v7, v18, v7
	v_div_scale_f32 v18, vcc, 1.0, v3, 1.0
	v_mul_f32_e32 v22, v18, v7
	v_fma_f32 v23, -v6, v22, v18
	v_fmac_f32_e32 v22, v23, v7
	v_fma_f32 v6, -v6, v22, v18
	v_div_fmas_f32 v6, v6, v7, v22
	v_div_fixup_f32 v3, v6, v3, 1.0
	v_div_scale_f32 v6, s[2:3], v2, v2, 1.0
	v_rcp_f32_e32 v7, v6
	s_nop 0
	v_fma_f32 v18, -v6, v7, 1.0
	v_fmac_f32_e32 v7, v18, v7
	v_div_scale_f32 v18, vcc, 1.0, v2, 1.0
	v_mul_f32_e32 v22, v18, v7
	v_fma_f32 v23, -v6, v22, v18
	v_fmac_f32_e32 v22, v23, v7
	v_fma_f32 v6, -v6, v22, v18
	v_div_fmas_f32 v6, v6, v7, v22
	v_div_fixup_f32 v2, v6, v2, 1.0
	v_div_scale_f32 v6, s[2:3], v9, v9, 1.0
	v_rcp_f32_e32 v7, v6
	v_pk_fma_f32 v[2:3], v[2:3], v[14:15], v[38:39]
	v_fma_f32 v18, -v6, v7, 1.0
	v_fmac_f32_e32 v7, v18, v7
	v_div_scale_f32 v18, vcc, 1.0, v9, 1.0
	v_mul_f32_e32 v22, v18, v7
	v_fma_f32 v23, -v6, v22, v18
	v_fmac_f32_e32 v22, v23, v7
	v_fma_f32 v6, -v6, v22, v18
	v_div_fmas_f32 v6, v6, v7, v22
	v_div_fixup_f32 v7, v6, v9, 1.0
	v_div_scale_f32 v6, s[2:3], v8, v8, 1.0
	v_rcp_f32_e32 v9, v6
	s_nop 0
	v_fma_f32 v18, -v6, v9, 1.0
	v_fmac_f32_e32 v9, v18, v9
	v_div_scale_f32 v18, vcc, 1.0, v8, 1.0
	v_mul_f32_e32 v22, v18, v9
	v_fma_f32 v23, -v6, v22, v18
	v_fmac_f32_e32 v22, v23, v9
	v_fma_f32 v6, -v6, v22, v18
	v_div_fmas_f32 v6, v6, v9, v22
	v_div_fixup_f32 v6, v6, v8, 1.0
	v_pk_add_f32 v[8:9], v[20:21], 1.0 op_sel_hi:[1,0]
	s_nop 0
	v_div_scale_f32 v18, s[2:3], v9, v9, 1.0
	v_rcp_f32_e32 v20, v18
	s_nop 0
	v_fma_f32 v21, -v18, v20, 1.0
	v_fmac_f32_e32 v20, v21, v20
	v_div_scale_f32 v21, vcc, 1.0, v9, 1.0
	v_mul_f32_e32 v22, v21, v20
	v_fma_f32 v23, -v18, v22, v21
	v_fmac_f32_e32 v22, v23, v20
	v_fma_f32 v18, -v18, v22, v21
	v_div_fmas_f32 v18, v18, v20, v22
	v_div_fixup_f32 v21, v18, v9, 1.0
	v_div_scale_f32 v9, s[2:3], v8, v8, 1.0
	v_rcp_f32_e32 v18, v9
	s_nop 0
	v_fma_f32 v20, -v9, v18, 1.0
	v_fmac_f32_e32 v18, v20, v18
	v_div_scale_f32 v20, vcc, 1.0, v8, 1.0
	v_mul_f32_e32 v22, v20, v18
	v_fma_f32 v23, -v9, v22, v20
	v_fmac_f32_e32 v22, v23, v18
	v_fma_f32 v9, -v9, v22, v20
	v_div_fmas_f32 v9, v9, v18, v22
	v_div_fixup_f32 v20, v9, v8, 1.0
	v_div_scale_f32 v8, s[2:3], v5, v5, 1.0
	v_rcp_f32_e32 v9, v8
	s_nop 0
	v_fma_f32 v18, -v8, v9, 1.0
	v_fmac_f32_e32 v9, v18, v9
	v_div_scale_f32 v18, vcc, 1.0, v5, 1.0
	v_mul_f32_e32 v22, v18, v9
	v_fma_f32 v23, -v8, v22, v18
	v_fmac_f32_e32 v22, v23, v9
	v_fma_f32 v8, -v8, v22, v18
	v_div_fmas_f32 v8, v8, v9, v22
	v_div_fixup_f32 v9, v8, v5, 1.0
	v_div_scale_f32 v5, s[2:3], v4, v4, 1.0
	v_rcp_f32_e32 v8, v5
	s_nop 0
	v_fma_f32 v18, -v5, v8, 1.0
	v_fmac_f32_e32 v8, v18, v8
	v_div_scale_f32 v18, vcc, 1.0, v4, 1.0
	v_mul_f32_e32 v22, v18, v8
	v_fma_f32 v23, -v5, v22, v18
	v_fmac_f32_e32 v22, v23, v8
	v_fma_f32 v5, -v5, v22, v18
	v_div_fmas_f32 v5, v5, v8, v22
	v_div_fixup_f32 v8, v5, v4, 1.0
	v_pk_fma_f32 v[4:5], v[6:7], v[16:17], v[40:41]
	v_pk_fma_f32 v[6:7], v[20:21], v[10:11], v[34:35]
	v_pk_fma_f32 v[8:9], v[8:9], v[12:13], v[36:37]
	global_store_dwordx4 v[76:77], v[2:5], off offset:512 nt
	global_store_dwordx4 v[76:77], v[6:9], off offset:528 nt
	s_nop 1
	v_mul_f32_e32 v6, v6, v6
	v_fmac_f32_e32 v6, v2, v2
	v_add_f32_e32 v2, v19, v6
	v_mul_f32_e32 v6, v7, v7
	v_fmac_f32_e32 v6, v3, v3
	v_mul_f32_e32 v3, v8, v8
	v_add_f32_e32 v2, v6, v2
	v_fmac_f32_e32 v3, v4, v4
	v_add_f32_e32 v2, v3, v2
	v_mul_f32_e32 v3, v9, v9
	v_fmac_f32_e32 v3, v5, v5
	v_add_f32_e32 v2, v3, v2
	ds_bpermute_b32 v3, v225, v2
	s_waitcnt lgkmcnt(0)
	v_add_f32_e32 v2, v2, v3
	ds_bpermute_b32 v3, v226, v2
	s_and_saveexec_b64 s[2:3], s[42:43]
	s_cbranch_execz .LBB0_766
	v_lshl_add_u64 v[4:5], v[74:75], 2, s[36:37]
	s_waitcnt lgkmcnt(0)
	v_add_f32_e32 v2, v2, v3
	global_atomic_add_f32 v[4:5], v2, off
	s_branch .LBB0_766

; __device__ __forceinline__ float dppf_prev(float cur, float below) { return __uint_as_float(dpp_prev(__float_as_uint(cur), __float_as_uint(below))); }
; __device__ __forceinline__ float dppf_next(float cur, float above) { return __uint_as_float(dpp_next(__float_as_uint(cur), __float_as_uint(above))); }
;     __device__ __forceinline__ void operator()(AccT& acc, const Unit& u, int wr, int wc, int fr, int fq) const {
;     ...
;         for (int ai = 0; ai < 2; ++ai) { const int gidx = u.pm * 4 + ai * 2 + wr;
; #pragma unroll
;             for (int m = 0; m < 4; ++m) { const float rstd = rsqrtf(rss[half * HALF_TOK + gidx * 64 + m * 16 + fr] * (1.0f / DM) + 1e-6f);
; #pragma unroll
;                 for (int n = 0; n < 2; ++n) { acc[ai][0][m][n] = acc[ai][0][m][n] * rstd; acc[ai][1][m][n] = acc[ai][1][m][n] * rstd; } }
; #pragma unroll
;             for (int n = 0; n < 2; ++n) {
;                 const f32x4 w0 = *(const f32x4*)(cw + fcol + 4 * n), w1 = *(const f32x4*)(cw + DFF + fcol + 4 * n), w2 = *(const f32x4*)(cw + 2 * DFF + fcol + 4 * n), b = *(const f32x4*)(cb + fcol + 4 * n);
; #pragma unroll
;                 for (int m = 0; m < 4; ++m) { const int lr = m * 16 + fr;
;                     const f32x4 gc = acc[ai][0][m][n], up = acc[ai][1][m][n]; f32x4 uu;
; #pragma unroll
;                     for (int j = 0; j < 4; ++j) { const float gp = dppf_prev(gc[j], m > 0 ? acc[ai][0][m - 1][n][j] : 0.f), gn = dppf_next(gc[j], m < 3 ? acc[ai][0][m + 1][n][j] : 0.f);
;                         uu[j] = gp * w0[j] + gc[j] * w1[j] + gn * w2[j] + b[j]; }
.LBB0_889:
	s_lshl_b32 s89, s48, 2
	s_add_i32 s89, s89, s15
	v_mov_b32_e32 v164, v169
	v_mov_b32_e32 v130, v196
	s_lshl_b32 s36, s49, 7
	s_lshl_b32 s48, s89, 6
	s_or_b32 s36, s36, s81
	v_add_u32_e32 v165, s48, v164
	v_lshl_add_u32 v144, v130, 3, s36
	v_add_u32_e32 v130, s85, v165
	v_ashrrev_i32_e32 v131, 31, v130
	v_lshl_add_u64 v[132:133], v[130:131], 2, s[10:11]
	global_load_dword v131, v[132:133], off
	v_ashrrev_i32_e32 v145, 31, v144
	v_readlane_b32 s60, v255, 2
	v_readlane_b32 s36, v255, 29
	v_readlane_b32 s61, v255, 3
	v_readlane_b32 s37, v255, 30
	v_readlane_b32 s62, v255, 4
	v_readlane_b32 s63, v255, 5
	global_load_dword v188, v[132:133], off offset:64
	global_load_dword v189, v[132:133], off offset:128
	global_load_dword v190, v[132:133], off offset:192
	v_lshlrev_b64 v[146:147], 2, v[144:145]
	v_lshl_add_u64 v[148:149], s[60:61], 0, v[146:147]
	v_lshl_add_u64 v[150:151], s[36:37], 0, v[146:147]
	v_lshl_add_u64 v[152:153], s[16:17], 0, v[146:147]
	v_lshl_add_u64 v[146:147], s[62:63], 0, v[146:147]
	global_load_dwordx4 v[204:207], v[148:149], off
	global_load_dwordx4 v[222:225], v[150:151], off
	global_load_dwordx4 v[226:229], v[152:153], off
	global_load_dwordx4 v[230:233], v[146:147], off
	v_mov_b32_e32 v171, v1
	v_mov_b32_e32 v174, v1
	v_mov_b32_e32 v175, v1
	v_mov_b32_dpp v171, v171 row_ror:1 row_mask:0xf bank_mask:0xf
	v_mov_b32_e32 v172, v171
	v_mov_b32_e32 v173, v171
	v_mov_b32_e32 v170, v171
	s_mov_b32 s0, 0xbf3a00e3
	s_mov_b32 s42, 0xbe11a98e
	s_mov_b32 s12, 0x3e027906
	s_mov_b32 s14, 0xbf38aa3b
	v_readlane_b32 s64, v255, 6
	v_readlane_b32 s65, v255, 7
	v_readlane_b32 s66, v255, 8
	v_readlane_b32 s67, v255, 9
	v_readlane_b32 s68, v255, 10
	v_readlane_b32 s69, v255, 11
	v_readlane_b32 s70, v255, 12
	v_readlane_b32 s71, v255, 13
	v_readlane_b32 s72, v255, 14
	v_readlane_b32 s73, v255, 15
	v_readlane_b32 s74, v255, 16
	v_readlane_b32 s75, v255, 17
	s_waitcnt vmcnt(0)
	v_fmamk_f32 v131, v131, 0x3a800000, v210
	v_cmp_gt_f32_e32 vcc, s30, v131
	v_mul_f32_e32 v132, 0x4b800000, v131
	s_nop 0
	v_cndmask_b32_e32 v131, v131, v132, vcc
	v_rsq_f32_e32 v131, v131
	s_nop 0
	v_mul_f32_e32 v132, 0x45800000, v131
	v_cndmask_b32_e32 v158, v131, v132, vcc
	v_mov_b32_e32 v159, v158
	v_pk_mul_f32 v[182:183], v[122:123], v[158:159] op_sel_hi:[1,0]
	v_add_u32_e32 v122, 16, v130
	v_ashrrev_i32_e32 v123, 31, v122
	v_lshl_add_u64 v[122:123], v[122:123], 2, s[10:11]
	v_mov_b32_e32 v122, v188
	v_pk_mul_f32 v[186:187], v[126:127], v[158:159] op_sel_hi:[1,0]
	v_lshlrev_b64 v[126:127], 2, v[144:145]
	v_lshl_add_u64 v[148:149], s[60:61], 0, v[126:127]
	v_lshl_add_u64 v[150:151], s[36:37], 0, v[126:127]
	v_lshl_add_u64 v[152:153], s[16:17], 0, v[126:127]
	v_pk_mul_f32 v[180:181], v[124:125], v[158:159] op_sel_hi:[1,0]
	v_lshl_add_u64 v[146:147], s[62:63], 0, v[126:127]
	v_pk_mul_f32 v[184:185], v[128:129], v[158:159] op_sel_hi:[1,0]
	v_mov_b64_e32 v[126:127], v[230:231]
	v_mov_b64_e32 v[128:129], v[232:233]
	v_mov_b32_dpp v172, v182 row_shr:1 row_mask:0xf bank_mask:0xf
	v_mov_b32_dpp v173, v183 row_shr:1 row_mask:0xf bank_mask:0xf
	v_mov_b32_dpp v170, v180 row_shr:1 row_mask:0xf bank_mask:0xf
	v_mov_b32_dpp v171, v181 row_shr:1 row_mask:0xf bank_mask:0xf
	s_mov_b32 s36, 0x3f35f0e3
	v_mov_b32_e32 v160, v158
	v_mov_b32_e32 v161, v158
	s_waitcnt vmcnt(0)
	v_fmamk_f32 v122, v122, 0x3a800000, v210
	v_cmp_gt_f32_e32 vcc, s30, v122
	v_mul_f32_e32 v123, 0x4b800000, v122
	s_nop 0
	v_cndmask_b32_e32 v122, v122, v123, vcc
	v_rsq_f32_e32 v122, v122
	s_nop 0
	v_mul_f32_e32 v123, 0x45800000, v122
	v_cndmask_b32_e32 v154, v122, v123, vcc
	v_mov_b32_e32 v155, v154
	v_pk_mul_f32 v[178:179], v[118:119], v[154:155] op_sel_hi:[1,0]
	v_add_u32_e32 v118, 32, v130
	v_ashrrev_i32_e32 v119, 31, v118
	v_lshl_add_u64 v[118:119], v[118:119], 2, s[10:11]
	v_mov_b32_e32 v167, v189
	v_add_u32_e32 v118, 48, v130
	v_ashrrev_i32_e32 v119, 31, v118
	v_lshl_add_u64 v[118:119], v[118:119], 2, s[10:11]
	v_pk_mul_f32 v[176:177], v[120:121], v[154:155] op_sel_hi:[1,0]
	v_mov_b32_e32 v166, v190
	v_mov_b64_e32 v[130:131], v[222:223]
	v_mov_b64_e32 v[132:133], v[224:225]
	v_mov_b64_e32 v[122:123], v[226:227]
	v_mov_b64_e32 v[124:125], v[228:229]
	v_mov_b32_dpp v174, v178 row_ror:15 row_mask:0xf bank_mask:0xf
	v_mov_b64_e32 v[118:119], v[204:205]
	v_mov_b64_e32 v[120:121], v[206:207]
	global_load_dwordx4 v[204:207], v[148:149], off offset:16
	global_load_dwordx4 v[222:225], v[150:151], off offset:16
	global_load_dwordx4 v[226:229], v[152:153], off offset:16
	global_load_dwordx4 v[230:233], v[146:147], off offset:16
	v_mov_b32_dpp v175, v179 row_ror:15 row_mask:0xf bank_mask:0xf
	v_mov_b32_dpp v174, v182 row_shl:1 row_mask:0xf bank_mask:0xf
	v_mov_b32_e32 v156, v154
	v_mov_b32_dpp v175, v183 row_shl:1 row_mask:0xf bank_mask:0xf
	v_mov_b32_e32 v157, v154
	s_waitcnt vmcnt(4)
; __device__ __forceinline__ unsigned cvt_pk_bf16(float lo, float hi) { unsigned r; asm volatile("v_cvt_pk_bf16_f32 %0, %1, %2" : "=v"(r) : "v"(lo), "v"(hi)); return r; }
; __device__ __forceinline__ float dppf_prev(float cur, float below) { return __uint_as_float(dpp_prev(__float_as_uint(cur), __float_as_uint(below))); }
; __device__ __forceinline__ float dppf_next(float cur, float above) { return __uint_as_float(dpp_next(__float_as_uint(cur), __float_as_uint(above))); }
;     __device__ __forceinline__ void operator()(AccT& acc, const Unit& u, int wr, int wc, int fr, int fq) const {
;     ...
;                     for (int j = 0; j < 4; ++j) { const float gp = dppf_prev(gc[j], m > 0 ? acc[ai][0][m - 1][n][j] : 0.f), gn = dppf_next(gc[j], m < 3 ? acc[ai][0][m + 1][n][j] : 0.f);
;                         uu[j] = gp * w0[j] + gc[j] * w1[j] + gn * w2[j] + b[j]; }
;                     const f32x2 ga = gelu_pk((f32x2){uu[0], uu[1]}), gb = gelu_pk((f32x2){uu[2], uu[3]});
;                     u32x2 wa; wa.x = cvt_pk_bf16(ga.x * up[0], ga.y * up[1]); wa.y = cvt_pk_bf16(gb.x * up[2], gb.y * up[3]);
;                     *(u32x2*)(ACT + (size_t)(gidx * 64 + lr) * DFF + fcol + 4 * n) = wa;
;                     if (m == 0 || m == 3) {
;                         if (lr == 0 || lr == 63) { u32x2 wu; wu.x = cvt_pk_bf16(up[0], up[1]); wu.y = cvt_pk_bf16(up[2], up[3]); *(u32x2*)(UP + (size_t)(gidx * 2 + (lr == 63 ? 1 : 0)) * DFF + fcol + 4 * n) = wu; }
	v_pk_mul_f32 v[188:189], v[130:131], v[182:183]
	v_pk_mul_f32 v[190:191], v[132:133], v[180:181]
	v_pk_fma_f32 v[172:173], v[118:119], v[172:173], v[188:189]
	s_nop 0
	v_pk_fma_f32 v[172:173], v[122:123], v[174:175], v[172:173]
	v_pk_fma_f32 v[170:171], v[120:121], v[170:171], v[190:191]
	v_pk_add_f32 v[188:189], v[126:127], v[172:173]
	v_mov_b32_e32 v172, v1
	v_mov_b32_e32 v173, v1
	v_mov_b64_e32 v[190:191], s[0:1]
	v_mov_b32_dpp v172, v176 row_ror:15 row_mask:0xf bank_mask:0xf
	v_mov_b32_dpp v173, v177 row_ror:15 row_mask:0xf bank_mask:0xf
	s_mov_b32 s0, 0x3f07dc22
	v_mov_b32_dpp v172, v180 row_shl:1 row_mask:0xf bank_mask:0xf
	v_mov_b32_dpp v173, v181 row_shl:1 row_mask:0xf bank_mask:0xf
	v_pk_fma_f32 v[170:171], v[124:125], v[172:173], v[170:171]
	v_cmp_gt_f32_e32 vcc, 0, v188
	v_pk_add_f32 v[174:175], v[128:129], v[170:171]
	v_and_b32_e32 v171, 0x7fffffff, v189
	v_and_b32_e32 v170, 0x7fffffff, v188
	v_pk_fma_f32 v[170:171], v[170:171], s[54:55], 1.0 op_sel_hi:[1,0,0]
	s_nop 0
	v_rcp_f32_e32 v170, v170
	v_rcp_f32_e32 v171, v171
	s_nop 0
	v_pk_fma_f32 v[172:173], v[170:171], s[0:1], v[190:191] op_sel_hi:[1,0,0]
	s_nop 0
	v_pk_fma_f32 v[172:173], v[170:171], v[172:173], s[36:37] op_sel_hi:[1,1,0]
	s_nop 0
	v_pk_fma_f32 v[172:173], v[170:171], v[172:173], s[42:43] op_sel_hi:[1,1,0]
	s_nop 0
	v_pk_fma_f32 v[172:173], v[170:171], v[172:173], s[12:13] op_sel_hi:[1,1,0]
	s_nop 0
	v_pk_mul_f32 v[192:193], v[170:171], v[172:173]
	v_pk_mul_f32 v[170:171], v[188:189], v[188:189]
	s_nop 0
	v_pk_mul_f32 v[170:171], v[170:171], s[14:15] op_sel_hi:[1,0]
	s_nop 0
	v_exp_f32_e32 v170, v170
	v_exp_f32_e32 v171, v171
	s_nop 0
	v_pk_mul_f32 v[170:171], v[170:171], v[192:193]
	s_nop 0
	v_pk_mul_f32 v[172:173], v[188:189], v[170:171]
	v_pk_fma_f32 v[170:171], v[188:189], v[170:171], v[188:189] neg_lo:[1,0,0] neg_hi:[1,0,0]
	s_nop 0
	v_cndmask_b32_e32 v188, v170, v172, vcc
	v_cmp_gt_f32_e32 vcc, 0, v189
	v_and_b32_e32 v170, 0x7fffffff, v174
	s_nop 0
	v_cndmask_b32_e32 v189, v171, v173, vcc
	v_and_b32_e32 v171, 0x7fffffff, v175
	v_pk_fma_f32 v[170:171], v[170:171], s[54:55], 1.0 op_sel_hi:[1,0,0]
	v_cmp_gt_f32_e32 vcc, 0, v174
	v_rcp_f32_e32 v170, v170
	v_rcp_f32_e32 v171, v171
	s_nop 0
	v_pk_fma_f32 v[172:173], v[170:171], s[0:1], v[190:191] op_sel_hi:[1,0,0]
	s_nop 0
	v_pk_fma_f32 v[172:173], v[170:171], v[172:173], s[36:37] op_sel_hi:[1,1,0]
	s_movk_i32 s36, 0x1600
	v_pk_fma_f32 v[172:173], v[170:171], v[172:173], s[42:43] op_sel_hi:[1,1,0]
	v_cmp_lt_i32_e64 s[42:43], 62, v164
	v_pk_fma_f32 v[172:173], v[170:171], v[172:173], s[12:13] op_sel_hi:[1,1,0]
	s_nop 0
	v_pk_mul_f32 v[170:171], v[170:171], v[172:173]
	v_pk_mul_f32 v[172:173], v[174:175], v[174:175]
	s_nop 0
	v_pk_mul_f32 v[172:173], v[172:173], s[14:15] op_sel_hi:[1,0]
	s_nop 0
	v_exp_f32_e32 v172, v172
	v_exp_f32_e32 v173, v173
	s_nop 0
	v_pk_mul_f32 v[170:171], v[172:173], v[170:171]
	s_nop 0
	v_pk_mul_f32 v[172:173], v[174:175], v[170:171]
	v_pk_fma_f32 v[170:171], v[174:175], v[170:171], v[174:175] neg_lo:[1,0,0] neg_hi:[1,0,0]
	s_nop 0
	v_cndmask_b32_e32 v172, v170, v172, vcc
	v_cmp_gt_f32_e32 vcc, 0, v175
	v_mul_f32_e32 v170, v186, v188
	v_mul_f32_e32 v172, v184, v172
	v_cndmask_b32_e32 v171, v171, v173, vcc
	v_mul_f32_e32 v173, v187, v189
	v_mul_f32_e32 v171, v185, v171
	v_cvt_pk_bf16_f32 v170, v170, v173
	v_cvt_pk_bf16_f32 v171, v172, v171
	v_mov_b64_e32 v[172:173], s[20:21]
	v_mad_i64_i32 v[172:173], s[36:37], v165, s36, v[172:173]
	v_lshl_add_u64 v[174:175], v[144:145], 1, v[172:173]
	s_mov_b64 s[36:37], 0
	v_cmp_eq_u32_e32 vcc, 63, v164
	global_store_dwordx2 v[174:175], v[170:171], off
	s_and_saveexec_b64 s[44:45], s[42:43]
	s_xor_b64 s[42:43], exec, s[44:45]
	s_cbranch_execz .LBB0_907
	s_and_b64 s[36:37], vcc, exec
	s_or_saveexec_b64 s[44:45], s[42:43]
	v_cmp_eq_u32_e64 s[42:43], 0, v164
	s_xor_b64 exec, exec, s[44:45]
	s_cbranch_execnz .LBB0_908

; __device__ __forceinline__ unsigned cvt_pk_bf16(float lo, float hi) { unsigned r; asm volatile("v_cvt_pk_bf16_f32 %0, %1, %2" : "=v"(r) : "v"(lo), "v"(hi)); return r; }
; __device__ __forceinline__ float dppf_prev(float cur, float below) { return __uint_as_float(dpp_prev(__float_as_uint(cur), __float_as_uint(below))); }
; __device__ __forceinline__ float dppf_next(float cur, float above) { return __uint_as_float(dpp_next(__float_as_uint(cur), __float_as_uint(above))); }
;     __device__ __forceinline__ void operator()(AccT& acc, const Unit& u, int wr, int wc, int fr, int fq) const {
;     ...
;             for (int n = 0; n < 2; ++n) {
;                 const f32x4 w0 = *(const f32x4*)(cw + fcol + 4 * n), w1 = *(const f32x4*)(cw + DFF + fcol + 4 * n), w2 = *(const f32x4*)(cw + 2 * DFF + fcol + 4 * n), b = *(const f32x4*)(cb + fcol + 4 * n);
; #pragma unroll
;                 for (int m = 0; m < 4; ++m) { const int lr = m * 16 + fr;
;                     const f32x4 gc = acc[ai][0][m][n], up = acc[ai][1][m][n]; f32x4 uu;
; #pragma unroll
;                     for (int j = 0; j < 4; ++j) { const float gp = dppf_prev(gc[j], m > 0 ? acc[ai][0][m - 1][n][j] : 0.f), gn = dppf_next(gc[j], m < 3 ? acc[ai][0][m + 1][n][j] : 0.f);
;                         uu[j] = gp * w0[j] + gc[j] * w1[j] + gn * w2[j] + b[j]; }
;                     const f32x2 ga = gelu_pk((f32x2){uu[0], uu[1]}), gb = gelu_pk((f32x2){uu[2], uu[3]});
;                     u32x2 wa; wa.x = cvt_pk_bf16(ga.x * up[0], ga.y * up[1]); wa.y = cvt_pk_bf16(gb.x * up[2], gb.y * up[3]);
;                     *(u32x2*)(ACT + (size_t)(gidx * 64 + lr) * DFF + fcol + 4 * n) = wa;
.LBB0_903:
	s_or_b64 exec, exec, s[36:37]
	s_movk_i32 s12, 0x2000
	v_pk_mul_f32 v[130:131], v[90:91], v[158:159]
	v_add_co_u32_e64 v90, s[54:55], s12, v148
	v_pk_mul_f32 v[120:121], v[88:89], v[156:157]
	s_nop 0
	v_addc_co_u32_e64 v91, s[54:55], 0, v149, s[54:55]
	v_pk_mul_f32 v[122:123], v[86:87], v[154:155]
	s_waitcnt vmcnt(0)
	v_mov_b64_e32 v[86:87], v[204:205]
	v_mov_b64_e32 v[88:89], v[206:207]
	v_mov_b64_e32 v[98:99], v[222:223]
	v_mov_b64_e32 v[100:101], v[224:225]
	v_add_co_u32_e64 v90, s[54:55], s0, v148
	v_pk_mul_f32 v[124:125], v[96:97], v[160:161]
	s_nop 0
	v_addc_co_u32_e64 v91, s[54:55], 0, v149, s[54:55]
	v_pk_mul_f32 v[126:127], v[94:95], v[158:159]
	v_pk_mul_f32 v[128:129], v[92:93], v[160:161]
	v_mov_b64_e32 v[90:91], v[226:227]
	v_mov_b64_e32 v[92:93], v[228:229]
	s_nop 0
	v_mov_b64_e32 v[94:95], v[230:231]
	v_mov_b64_e32 v[96:97], v[232:233]
	global_load_dwordx4 v[204:207], v[148:149], off
	global_load_dwordx4 v[222:225], v[150:151], off
	global_load_dwordx4 v[226:229], v[152:153], off
	global_load_dwordx4 v[230:233], v[146:147], off
	v_mov_b32_e32 v133, v1
	v_mov_b32_e32 v160, v1
	v_mov_b32_e32 v161, v1
	v_mov_b32_dpp v133, v133 row_ror:1 row_mask:0xf bank_mask:0xf
	v_mov_b32_e32 v158, v133
	v_mov_b32_e32 v159, v133
	v_mov_b32_dpp v160, v122 row_ror:15 row_mask:0xf bank_mask:0xf
	v_mov_b32_dpp v158, v126 row_shr:1 row_mask:0xf bank_mask:0xf
	v_mov_b32_dpp v159, v127 row_shr:1 row_mask:0xf bank_mask:0xf
	v_mov_b32_dpp v161, v123 row_ror:15 row_mask:0xf bank_mask:0xf
	v_mov_b32_dpp v160, v126 row_shl:1 row_mask:0xf bank_mask:0xf
	v_mov_b32_e32 v132, v133
	v_mov_b32_dpp v161, v127 row_shl:1 row_mask:0xf bank_mask:0xf
	v_mov_b32_dpp v133, v125 row_shr:1 row_mask:0xf bank_mask:0xf
	v_mov_b32_dpp v132, v124 row_shr:1 row_mask:0xf bank_mask:0xf
	s_mov_b32 s0, 0x3e6d3388
	s_mov_b64 s[36:37], 0x2c10
	v_lshl_add_u64 v[104:105], v[148:149], 0, s[36:37]
	s_mov_b64 s[36:37], 0x5810
	v_lshl_add_u64 v[106:107], v[148:149], 0, s[36:37]
	s_mov_b32 s36, 0xbf3a00e3
	s_mov_b32 s52, 0x3f35f0e3
	s_mov_b32 s56, 0xbe11a98e
	s_mov_b32 s12, 0x3e027906
	s_waitcnt vmcnt(4)
	v_pk_mul_f32 v[178:179], v[126:127], v[98:99]
	s_nop 0
	v_pk_fma_f32 v[158:159], v[86:87], v[158:159], v[178:179]
	v_pk_mul_f32 v[172:173], v[124:125], v[100:101]
	v_pk_fma_f32 v[158:159], v[90:91], v[160:161], v[158:159]
	v_mov_b32_e32 v160, v1
	v_mov_b32_e32 v161, v1
	v_pk_add_f32 v[158:159], v[94:95], v[158:159]
	v_mov_b32_dpp v160, v120 row_ror:15 row_mask:0xf bank_mask:0xf
	v_mov_b32_dpp v161, v121 row_ror:15 row_mask:0xf bank_mask:0xf
	v_pk_fma_f32 v[132:133], v[88:89], v[132:133], v[172:173]
	v_mov_b32_dpp v160, v124 row_shl:1 row_mask:0xf bank_mask:0xf
	v_mov_b32_dpp v161, v125 row_shl:1 row_mask:0xf bank_mask:0xf
	v_pk_fma_f32 v[132:133], v[92:93], v[160:161], v[132:133]
	v_and_b32_e32 v161, 0x7fffffff, v159
	v_and_b32_e32 v160, 0x7fffffff, v158
	v_pk_fma_f32 v[160:161], v[160:161], s[0:1], 1.0 op_sel_hi:[1,0,0]
	v_mov_b64_e32 v[172:173], s[36:37]
	v_rcp_f32_e32 v160, v160
	v_rcp_f32_e32 v161, v161
	s_mov_b32 s36, 0x3f07dc22
	v_pk_add_f32 v[132:133], v[96:97], v[132:133]
	v_cmp_gt_f32_e64 s[54:55], 0, v158
	v_pk_fma_f32 v[178:179], v[160:161], s[36:37], v[172:173] op_sel_hi:[1,0,0]
	s_nop 0
	v_pk_fma_f32 v[178:179], v[160:161], v[178:179], s[52:53] op_sel_hi:[1,1,0]
	s_nop 0
	v_pk_fma_f32 v[178:179], v[160:161], v[178:179], s[56:57] op_sel_hi:[1,1,0]
	s_nop 0
	v_pk_fma_f32 v[178:179], v[160:161], v[178:179], s[12:13] op_sel_hi:[1,1,0]
	s_nop 0
	v_pk_mul_f32 v[160:161], v[160:161], v[178:179]
	v_pk_mul_f32 v[178:179], v[158:159], v[158:159]
	s_nop 0
	v_pk_mul_f32 v[178:179], v[178:179], s[14:15] op_sel_hi:[1,0]
	s_nop 0
	v_exp_f32_e32 v178, v178
	v_exp_f32_e32 v179, v179
	s_nop 0
	v_pk_mul_f32 v[160:161], v[178:179], v[160:161]
	s_nop 0
	v_pk_mul_f32 v[178:179], v[158:159], v[160:161]
	v_pk_fma_f32 v[160:161], v[158:159], v[160:161], v[158:159] neg_lo:[1,0,0] neg_hi:[1,0,0]
	v_and_b32_e32 v158, 0x7fffffff, v132
	v_cndmask_b32_e64 v178, v160, v178, s[54:55]
	v_cmp_gt_f32_e64 s[54:55], 0, v159
	v_and_b32_e32 v159, 0x7fffffff, v133
	v_pk_fma_f32 v[158:159], v[158:159], s[0:1], 1.0 op_sel_hi:[1,0,0]
	v_cndmask_b32_e64 v179, v161, v179, s[54:55]
	v_rcp_f32_e32 v158, v158
	v_rcp_f32_e32 v159, v159
	v_cmp_gt_f32_e64 s[54:55], 0, v132
	v_pk_fma_f32 v[160:161], v[158:159], s[36:37], v[172:173] op_sel_hi:[1,0,0]
	s_nop 0
	v_pk_fma_f32 v[160:161], v[158:159], v[160:161], s[52:53] op_sel_hi:[1,1,0]
	s_mov_b64 s[36:37], 0
	v_pk_fma_f32 v[160:161], v[158:159], v[160:161], s[56:57] op_sel_hi:[1,1,0]
	s_nop 0
	v_pk_fma_f32 v[160:161], v[158:159], v[160:161], s[12:13] op_sel_hi:[1,1,0]
	s_nop 0
	v_pk_mul_f32 v[158:159], v[158:159], v[160:161]
	v_pk_mul_f32 v[160:161], v[132:133], v[132:133]
	s_nop 0
	v_pk_mul_f32 v[160:161], v[160:161], s[14:15] op_sel_hi:[1,0]
	s_nop 0
	v_exp_f32_e32 v160, v160
	v_exp_f32_e32 v161, v161
	s_nop 0
	v_pk_mul_f32 v[158:159], v[160:161], v[158:159]
	s_nop 0
	v_pk_mul_f32 v[160:161], v[132:133], v[158:159]
	v_pk_fma_f32 v[158:159], v[132:133], v[158:159], v[132:133] neg_lo:[1,0,0] neg_hi:[1,0,0]
	v_mul_f32_e32 v132, v130, v178
	v_cndmask_b32_e64 v158, v158, v160, s[54:55]
	v_cmp_gt_f32_e64 s[54:55], 0, v133
	v_mul_f32_e32 v158, v128, v158
	s_nop 0
	v_cndmask_b32_e64 v133, v159, v161, s[54:55]
	v_mul_f32_e32 v133, v129, v133
	v_cmp_lt_i32_e64 s[54:55], 62, v164
	v_mul_f32_e32 v159, v131, v179
	v_cvt_pk_bf16_f32 v132, v132, v159
	v_cvt_pk_bf16_f32 v133, v158, v133
	global_store_dwordx2 v[174:175], v[132:133], off offset:8
	s_and_saveexec_b64 s[52:53], s[54:55]
	s_xor_b64 s[52:53], exec, s[52:53]
	s_cbranch_execz .LBB0_909
	s_and_b64 s[36:37], vcc, exec
	s_andn2_saveexec_b64 s[52:53], s[52:53]
	s_cbranch_execnz .LBB0_910

; __device__ __forceinline__ unsigned cvt_pk_bf16(float lo, float hi) { unsigned r; asm volatile("v_cvt_pk_bf16_f32 %0, %1, %2" : "=v"(r) : "v"(lo), "v"(hi)); return r; }
; __device__ __forceinline__ float dppf_prev(float cur, float below) { return __uint_as_float(dpp_prev(__float_as_uint(cur), __float_as_uint(below))); }
; __device__ __forceinline__ float dppf_next(float cur, float above) { return __uint_as_float(dpp_next(__float_as_uint(cur), __float_as_uint(above))); }
;     __device__ __forceinline__ void operator()(AccT& acc, const Unit& u, int wr, int wc, int fr, int fq) const {
;     ...
;         for (int ai = 0; ai < 2; ++ai) { const int gidx = u.pm * 4 + ai * 2 + wr;
; #pragma unroll
;             for (int m = 0; m < 4; ++m) { const float rstd = rsqrtf(rss[half * HALF_TOK + gidx * 64 + m * 16 + fr] * (1.0f / DM) + 1e-6f);
; #pragma unroll
;                 for (int n = 0; n < 2; ++n) { acc[ai][0][m][n] = acc[ai][0][m][n] * rstd; acc[ai][1][m][n] = acc[ai][1][m][n] * rstd; } }
; #pragma unroll
;             for (int n = 0; n < 2; ++n) {
;                 const f32x4 w0 = *(const f32x4*)(cw + fcol + 4 * n), w1 = *(const f32x4*)(cw + DFF + fcol + 4 * n), w2 = *(const f32x4*)(cw + 2 * DFF + fcol + 4 * n), b = *(const f32x4*)(cb + fcol + 4 * n);
; #pragma unroll
;                 for (int m = 0; m < 4; ++m) { const int lr = m * 16 + fr;
;                     const f32x4 gc = acc[ai][0][m][n], up = acc[ai][1][m][n]; f32x4 uu;
; #pragma unroll
;                     for (int j = 0; j < 4; ++j) { const float gp = dppf_prev(gc[j], m > 0 ? acc[ai][0][m - 1][n][j] : 0.f), gn = dppf_next(gc[j], m < 3 ? acc[ai][0][m + 1][n][j] : 0.f);
;                         uu[j] = gp * w0[j] + gc[j] * w1[j] + gn * w2[j] + b[j]; }
;                     const f32x2 ga = gelu_pk((f32x2){uu[0], uu[1]}), gb = gelu_pk((f32x2){uu[2], uu[3]});
;                     u32x2 wa; wa.x = cvt_pk_bf16(ga.x * up[0], ga.y * up[1]); wa.y = cvt_pk_bf16(gb.x * up[2], gb.y * up[3]);
;                     *(u32x2*)(ACT + (size_t)(gidx * 64 + lr) * DFF + fcol + 4 * n) = wa;
.LBB0_921:
	s_or_b64 exec, exec, s[36:37]
	s_add_i32 s89, s89, 2
	s_lshl_b32 s91, s89, 6
	v_add_u32_e32 v98, s91, v164
	v_add_u32_e32 v66, s85, v98
	v_ashrrev_i32_e32 v67, 31, v66
	v_lshl_add_u64 v[68:69], v[66:67], 2, s[10:11]
	global_load_dword v67, v[68:69], off
	global_load_dword v200, v[68:69], off offset:64
	global_load_dword v201, v[68:69], off offset:128
	global_load_dword v194, v[68:69], off offset:192
	v_mov_b32_e32 v79, v1
	v_mov_b32_e32 v94, v1
	v_mov_b32_e32 v95, v1
	v_mov_b32_dpp v79, v79 row_ror:1 row_mask:0xf bank_mask:0xf
	v_mov_b32_e32 v92, v79
	v_mov_b32_e32 v93, v79
	v_mov_b32_e32 v78, v79
	s_mov_b32 s36, 0xbf3a00e3
	s_mov_b32 s52, 0x3f35f0e3
	s_waitcnt vmcnt(0)
	v_fmamk_f32 v67, v67, 0x3a800000, v210
	v_cmp_gt_f32_e64 s[54:55], s30, v67
	v_mul_f32_e32 v68, 0x4b800000, v67
	s_nop 0
	v_cndmask_b32_e64 v67, v67, v68, s[54:55]
	v_rsq_f32_e32 v67, v67
	s_nop 0
	v_mul_f32_e32 v68, 0x45800000, v67
	v_cndmask_b32_e64 v74, v67, v68, s[54:55]
	v_mov_b32_e32 v75, v74
	v_pk_mul_f32 v[90:91], v[58:59], v[74:75] op_sel_hi:[1,0]
	v_add_u32_e32 v58, 16, v66
	v_ashrrev_i32_e32 v59, 31, v58
	v_lshl_add_u64 v[58:59], v[58:59], 2, s[10:11]
	v_mov_b32_e32 v58, v200
	v_pk_mul_f32 v[84:85], v[64:65], v[74:75] op_sel_hi:[1,0]
	v_pk_mul_f32 v[86:87], v[62:63], v[74:75] op_sel_hi:[1,0]
	v_pk_mul_f32 v[88:89], v[60:61], v[74:75] op_sel_hi:[1,0]
	v_mov_b32_dpp v78, v84 row_shr:1 row_mask:0xf bank_mask:0xf
	v_mov_b32_dpp v92, v86 row_shr:1 row_mask:0xf bank_mask:0xf
	v_mov_b32_dpp v93, v87 row_shr:1 row_mask:0xf bank_mask:0xf
	v_mov_b32_dpp v79, v85 row_shr:1 row_mask:0xf bank_mask:0xf
	v_mov_b32_e32 v76, v74
	v_mov_b32_e32 v77, v74
	s_waitcnt vmcnt(0)
	v_fmamk_f32 v58, v58, 0x3a800000, v210
	v_cmp_gt_f32_e64 s[54:55], s30, v58
	v_mul_f32_e32 v59, 0x4b800000, v58
	s_nop 0
	v_cndmask_b32_e64 v58, v58, v59, s[54:55]
	v_rsq_f32_e32 v58, v58
	s_nop 0
	v_mul_f32_e32 v59, 0x45800000, v58
	v_cndmask_b32_e64 v70, v58, v59, s[54:55]
	v_mov_b32_e32 v71, v70
	v_pk_mul_f32 v[82:83], v[54:55], v[70:71] op_sel_hi:[1,0]
	v_add_u32_e32 v54, 32, v66
	v_ashrrev_i32_e32 v55, 31, v54
	v_lshl_add_u64 v[54:55], v[54:55], 2, s[10:11]
	v_mov_b32_e32 v109, v201
	v_add_u32_e32 v54, 48, v66
	v_ashrrev_i32_e32 v55, 31, v54
	v_lshl_add_u64 v[54:55], v[54:55], 2, s[10:11]
	v_pk_mul_f32 v[80:81], v[56:57], v[70:71] op_sel_hi:[1,0]
	v_mov_b32_e32 v108, v194
	s_nop 0
	s_waitcnt vmcnt(0)
	v_mov_b64_e32 v[54:55], v[204:205]
	v_mov_b64_e32 v[56:57], v[206:207]
	v_mov_b64_e32 v[66:67], v[222:223]
	v_mov_b64_e32 v[68:69], v[224:225]
	v_mov_b64_e32 v[58:59], v[226:227]
	v_mov_b64_e32 v[60:61], v[228:229]
	v_mov_b64_e32 v[62:63], v[230:231]
	v_mov_b64_e32 v[64:65], v[232:233]
	global_load_dwordx4 v[204:207], v[148:149], off offset:16
	global_load_dwordx4 v[222:225], v[150:151], off offset:16
	global_load_dwordx4 v[226:229], v[152:153], off offset:16
	global_load_dwordx4 v[230:233], v[146:147], off offset:16
	v_mov_b32_dpp v94, v82 row_ror:15 row_mask:0xf bank_mask:0xf
	v_mov_b32_dpp v95, v83 row_ror:15 row_mask:0xf bank_mask:0xf
	v_mov_b32_e32 v72, v70
	v_mov_b32_dpp v94, v86 row_shl:1 row_mask:0xf bank_mask:0xf
	v_mov_b32_dpp v95, v87 row_shl:1 row_mask:0xf bank_mask:0xf
	v_mov_b32_e32 v73, v70
	s_waitcnt vmcnt(4)
	v_pk_mul_f32 v[100:101], v[66:67], v[86:87]
	s_nop 0
	v_pk_fma_f32 v[92:93], v[54:55], v[92:93], v[100:101]
	v_pk_mul_f32 v[96:97], v[68:69], v[84:85]
	v_pk_fma_f32 v[92:93], v[58:59], v[94:95], v[92:93]
	v_mov_b32_e32 v94, v1
	v_mov_b32_e32 v95, v1
	v_pk_add_f32 v[92:93], v[62:63], v[92:93]
	v_mov_b32_dpp v94, v80 row_ror:15 row_mask:0xf bank_mask:0xf
	v_mov_b32_dpp v95, v81 row_ror:15 row_mask:0xf bank_mask:0xf
	v_pk_fma_f32 v[78:79], v[56:57], v[78:79], v[96:97]
	v_mov_b32_dpp v94, v84 row_shl:1 row_mask:0xf bank_mask:0xf
	v_mov_b32_dpp v95, v85 row_shl:1 row_mask:0xf bank_mask:0xf
	v_pk_fma_f32 v[78:79], v[60:61], v[94:95], v[78:79]
	v_and_b32_e32 v95, 0x7fffffff, v93
	v_and_b32_e32 v94, 0x7fffffff, v92
	v_pk_fma_f32 v[94:95], v[94:95], s[0:1], 1.0 op_sel_hi:[1,0,0]
	v_pk_add_f32 v[78:79], v[64:65], v[78:79]
	v_rcp_f32_e32 v96, v94
	v_rcp_f32_e32 v97, v95
	v_mov_b64_e32 v[94:95], s[36:37]
	s_mov_b32 s36, 0x3f07dc22
	v_cmp_gt_f32_e64 s[54:55], 0, v92
	v_pk_fma_f32 v[100:101], v[96:97], s[36:37], v[94:95] op_sel_hi:[1,0,0]
	s_nop 0
	v_pk_fma_f32 v[100:101], v[96:97], v[100:101], s[52:53] op_sel_hi:[1,1,0]
	s_nop 0
	v_pk_fma_f32 v[100:101], v[96:97], v[100:101], s[56:57] op_sel_hi:[1,1,0]
	s_nop 0
	v_pk_fma_f32 v[100:101], v[96:97], v[100:101], s[12:13] op_sel_hi:[1,1,0]
	s_nop 0
	v_pk_mul_f32 v[96:97], v[96:97], v[100:101]
	v_pk_mul_f32 v[100:101], v[92:93], v[92:93]
	s_nop 0
	v_pk_mul_f32 v[100:101], v[100:101], s[14:15] op_sel_hi:[1,0]
	s_nop 0
	v_exp_f32_e32 v100, v100
	v_exp_f32_e32 v101, v101
	s_nop 0
	v_pk_mul_f32 v[96:97], v[100:101], v[96:97]
	s_nop 0
	v_pk_mul_f32 v[100:101], v[92:93], v[96:97]
	v_pk_fma_f32 v[96:97], v[92:93], v[96:97], v[92:93] neg_lo:[1,0,0] neg_hi:[1,0,0]
	v_and_b32_e32 v92, 0x7fffffff, v78
	v_cndmask_b32_e64 v96, v96, v100, s[54:55]
	v_cmp_gt_f32_e64 s[54:55], 0, v93
	v_and_b32_e32 v93, 0x7fffffff, v79
	v_pk_fma_f32 v[92:93], v[92:93], s[0:1], 1.0 op_sel_hi:[1,0,0]
	v_cndmask_b32_e64 v97, v97, v101, s[54:55]
	v_rcp_f32_e32 v92, v92
	v_rcp_f32_e32 v93, v93
	v_cmp_gt_f32_e64 s[54:55], 0, v78
	v_pk_fma_f32 v[94:95], v[92:93], s[36:37], v[94:95] op_sel_hi:[1,0,0]
	s_nop 0
	v_pk_fma_f32 v[94:95], v[92:93], v[94:95], s[52:53] op_sel_hi:[1,1,0]
	s_nop 0
	v_pk_fma_f32 v[94:95], v[92:93], v[94:95], s[56:57] op_sel_hi:[1,1,0]
	s_nop 0
	v_pk_fma_f32 v[94:95], v[92:93], v[94:95], s[12:13] op_sel_hi:[1,1,0]
	s_nop 0
	v_pk_mul_f32 v[92:93], v[92:93], v[94:95]
	v_pk_mul_f32 v[94:95], v[78:79], v[78:79]
	s_nop 0
	v_pk_mul_f32 v[94:95], v[94:95], s[14:15] op_sel_hi:[1,0]
	s_nop 0
	v_exp_f32_e32 v94, v94
	v_exp_f32_e32 v95, v95
	s_nop 0
	v_pk_mul_f32 v[92:93], v[94:95], v[92:93]
	s_nop 0
	v_pk_mul_f32 v[94:95], v[78:79], v[92:93]
	v_pk_fma_f32 v[92:93], v[78:79], v[92:93], v[78:79] neg_lo:[1,0,0] neg_hi:[1,0,0]
	s_nop 0
	v_cndmask_b32_e64 v78, v92, v94, s[54:55]
	v_cmp_gt_f32_e64 s[54:55], 0, v79
	v_mul_f32_e32 v92, v90, v96
	v_mul_f32_e32 v78, v88, v78
	v_cndmask_b32_e64 v79, v93, v95, s[54:55]
	v_mul_f32_e32 v93, v91, v97
	v_mul_f32_e32 v79, v89, v79
	v_cvt_pk_bf16_f32 v92, v92, v93
	v_cvt_pk_bf16_f32 v93, v78, v79
	v_mov_b64_e32 v[78:79], s[20:21]
	v_mad_i64_i32 v[78:79], s[36:37], v98, s94, v[78:79]
	v_lshl_add_u64 v[78:79], v[144:145], 1, v[78:79]
	v_cmp_lt_i32_e64 s[54:55], 62, v164
	s_mov_b64 s[36:37], 0
	global_store_dwordx2 v[78:79], v[92:93], off
	s_and_saveexec_b64 s[52:53], s[54:55]
	s_xor_b64 s[52:53], exec, s[52:53]
	s_cbranch_execz .LBB0_925
	s_and_b64 s[36:37], vcc, exec
	s_andn2_saveexec_b64 s[52:53], s[52:53]
	s_cbranch_execnz .LBB0_926

; __device__ __forceinline__ unsigned cvt_pk_bf16(float lo, float hi) { unsigned r; asm volatile("v_cvt_pk_bf16_f32 %0, %1, %2" : "=v"(r) : "v"(lo), "v"(hi)); return r; }
; __device__ __forceinline__ float dppf_prev(float cur, float below) { return __uint_as_float(dpp_prev(__float_as_uint(cur), __float_as_uint(below))); }
; __device__ __forceinline__ float dppf_next(float cur, float above) { return __uint_as_float(dpp_next(__float_as_uint(cur), __float_as_uint(above))); }
;     __device__ __forceinline__ void operator()(AccT& acc, const Unit& u, int wr, int wc, int fr, int fq) const {
;     ...
;             for (int n = 0; n < 2; ++n) {
;                 const f32x4 w0 = *(const f32x4*)(cw + fcol + 4 * n), w1 = *(const f32x4*)(cw + DFF + fcol + 4 * n), w2 = *(const f32x4*)(cw + 2 * DFF + fcol + 4 * n), b = *(const f32x4*)(cb + fcol + 4 * n);
; #pragma unroll
;                 for (int m = 0; m < 4; ++m) { const int lr = m * 16 + fr;
;                     const f32x4 gc = acc[ai][0][m][n], up = acc[ai][1][m][n]; f32x4 uu;
; #pragma unroll
;                     for (int j = 0; j < 4; ++j) { const float gp = dppf_prev(gc[j], m > 0 ? acc[ai][0][m - 1][n][j] : 0.f), gn = dppf_next(gc[j], m < 3 ? acc[ai][0][m + 1][n][j] : 0.f);
;                         uu[j] = gp * w0[j] + gc[j] * w1[j] + gn * w2[j] + b[j]; }
;                     const f32x2 ga = gelu_pk((f32x2){uu[0], uu[1]}), gb = gelu_pk((f32x2){uu[2], uu[3]});
;                     u32x2 wa; wa.x = cvt_pk_bf16(ga.x * up[0], ga.y * up[1]); wa.y = cvt_pk_bf16(gb.x * up[2], gb.y * up[3]);
;                     *(u32x2*)(ACT + (size_t)(gidx * 64 + lr) * DFF + fcol + 4 * n) = wa;
.LBB0_937:
	s_or_b64 exec, exec, s[36:37]
	v_pk_mul_f32 v[56:57], v[32:33], v[76:77]
	v_pk_mul_f32 v[58:59], v[30:31], v[74:75]
	v_pk_mul_f32 v[60:61], v[24:25], v[76:77]
	v_pk_mul_f32 v[62:63], v[22:23], v[74:75]
	v_pk_mul_f32 v[48:49], v[28:29], v[72:73]
	v_pk_mul_f32 v[54:55], v[26:27], v[70:71]
	s_waitcnt vmcnt(0)
	v_mov_b64_e32 v[22:23], v[204:205]
	v_mov_b64_e32 v[24:25], v[206:207]
	v_mov_b64_e32 v[34:35], v[222:223]
	v_mov_b64_e32 v[36:37], v[224:225]
	v_mov_b64_e32 v[26:27], v[226:227]
	v_mov_b64_e32 v[28:29], v[228:229]
	v_mov_b64_e32 v[30:31], v[230:231]
	v_mov_b64_e32 v[32:33], v[232:233]
	v_mov_b32_e32 v65, v1
	v_mov_b32_e32 v68, v1
	v_mov_b32_e32 v69, v1
	v_mov_b32_dpp v65, v65 row_ror:1 row_mask:0xf bank_mask:0xf
	v_mov_b32_e32 v66, v65
	v_mov_b32_e32 v67, v65
	v_mov_b32_dpp v68, v54 row_ror:15 row_mask:0xf bank_mask:0xf
	v_mov_b32_dpp v66, v58 row_shr:1 row_mask:0xf bank_mask:0xf
	v_mov_b32_dpp v67, v59 row_shr:1 row_mask:0xf bank_mask:0xf
	v_mov_b32_dpp v69, v55 row_ror:15 row_mask:0xf bank_mask:0xf
	v_mov_b32_dpp v68, v58 row_shl:1 row_mask:0xf bank_mask:0xf
	v_mov_b32_e32 v64, v65
	v_mov_b32_dpp v69, v59 row_shl:1 row_mask:0xf bank_mask:0xf
	v_mov_b32_dpp v65, v57 row_shr:1 row_mask:0xf bank_mask:0xf
	v_mov_b32_dpp v64, v56 row_shr:1 row_mask:0xf bank_mask:0xf
	s_mov_b32 s36, 0xbf3a00e3
	s_mov_b32 s52, 0x3f35f0e3
	s_waitcnt vmcnt(0)
	v_pk_mul_f32 v[76:77], v[58:59], v[34:35]
	s_nop 0
	v_pk_fma_f32 v[66:67], v[22:23], v[66:67], v[76:77]
	v_pk_mul_f32 v[74:75], v[56:57], v[36:37]
	v_pk_fma_f32 v[66:67], v[26:27], v[68:69], v[66:67]
	v_mov_b32_e32 v68, v1
	v_mov_b32_e32 v69, v1
	v_pk_add_f32 v[66:67], v[30:31], v[66:67]
	v_mov_b32_dpp v68, v48 row_ror:15 row_mask:0xf bank_mask:0xf
	v_mov_b32_dpp v69, v49 row_ror:15 row_mask:0xf bank_mask:0xf
	v_pk_fma_f32 v[64:65], v[24:25], v[64:65], v[74:75]
	v_mov_b32_dpp v68, v56 row_shl:1 row_mask:0xf bank_mask:0xf
	v_mov_b32_dpp v69, v57 row_shl:1 row_mask:0xf bank_mask:0xf
	v_pk_fma_f32 v[64:65], v[28:29], v[68:69], v[64:65]
	v_and_b32_e32 v69, 0x7fffffff, v67
	v_and_b32_e32 v68, 0x7fffffff, v66
	v_pk_fma_f32 v[68:69], v[68:69], s[0:1], 1.0 op_sel_hi:[1,0,0]
	v_mov_b64_e32 v[74:75], s[36:37]
	v_rcp_f32_e32 v68, v68
	v_rcp_f32_e32 v69, v69
	s_mov_b32 s36, 0x3f07dc22
	v_pk_add_f32 v[64:65], v[32:33], v[64:65]
	v_cmp_gt_f32_e64 s[54:55], 0, v66
	v_pk_fma_f32 v[76:77], v[68:69], s[36:37], v[74:75] op_sel_hi:[1,0,0]
	s_nop 0
	v_pk_fma_f32 v[76:77], v[68:69], v[76:77], s[52:53] op_sel_hi:[1,1,0]
	s_nop 0
	v_pk_fma_f32 v[76:77], v[68:69], v[76:77], s[56:57] op_sel_hi:[1,1,0]
	s_nop 0
	v_pk_fma_f32 v[76:77], v[68:69], v[76:77], s[12:13] op_sel_hi:[1,1,0]
	s_nop 0
	v_pk_mul_f32 v[68:69], v[68:69], v[76:77]
	v_pk_mul_f32 v[76:77], v[66:67], v[66:67]
	s_nop 0
	v_pk_mul_f32 v[76:77], v[76:77], s[14:15] op_sel_hi:[1,0]
	s_nop 0
	v_exp_f32_e32 v76, v76
	v_exp_f32_e32 v77, v77
	s_nop 0
	v_pk_mul_f32 v[68:69], v[76:77], v[68:69]
	s_nop 0
	v_pk_mul_f32 v[76:77], v[66:67], v[68:69]
	v_pk_fma_f32 v[68:69], v[66:67], v[68:69], v[66:67] neg_lo:[1,0,0] neg_hi:[1,0,0]
	v_and_b32_e32 v66, 0x7fffffff, v64
	v_cndmask_b32_e64 v76, v68, v76, s[54:55]
	v_cmp_gt_f32_e64 s[54:55], 0, v67
	v_and_b32_e32 v67, 0x7fffffff, v65
	v_pk_fma_f32 v[66:67], v[66:67], s[0:1], 1.0 op_sel_hi:[1,0,0]
	v_cndmask_b32_e64 v77, v69, v77, s[54:55]
	v_rcp_f32_e32 v66, v66
	v_rcp_f32_e32 v67, v67
	v_cmp_gt_f32_e64 s[54:55], 0, v64
	v_pk_fma_f32 v[68:69], v[66:67], s[36:37], v[74:75] op_sel_hi:[1,0,0]
	s_nop 0
	v_pk_fma_f32 v[68:69], v[66:67], v[68:69], s[52:53] op_sel_hi:[1,1,0]
	s_mov_b64 s[36:37], 0
	v_pk_fma_f32 v[68:69], v[66:67], v[68:69], s[56:57] op_sel_hi:[1,1,0]
	s_nop 0
	v_pk_fma_f32 v[68:69], v[66:67], v[68:69], s[12:13] op_sel_hi:[1,1,0]
	s_nop 0
	v_pk_mul_f32 v[66:67], v[66:67], v[68:69]
	v_pk_mul_f32 v[68:69], v[64:65], v[64:65]
	s_nop 0
	v_pk_mul_f32 v[68:69], v[68:69], s[14:15] op_sel_hi:[1,0]
	s_nop 0
	v_exp_f32_e32 v68, v68
	v_exp_f32_e32 v69, v69
	s_nop 0
	v_pk_mul_f32 v[66:67], v[68:69], v[66:67]
	s_nop 0
	v_pk_mul_f32 v[68:69], v[64:65], v[66:67]
	v_pk_fma_f32 v[66:67], v[64:65], v[66:67], v[64:65] neg_lo:[1,0,0] neg_hi:[1,0,0]
	v_mul_f32_e32 v64, v62, v76
	v_cndmask_b32_e64 v66, v66, v68, s[54:55]
	v_cmp_gt_f32_e64 s[54:55], 0, v65
	v_mul_f32_e32 v66, v60, v66
	s_nop 0
	v_cndmask_b32_e64 v65, v67, v69, s[54:55]
	v_mul_f32_e32 v65, v61, v65
	v_cmp_lt_i32_e64 s[54:55], 62, v164
	v_mul_f32_e32 v67, v63, v77
	v_cvt_pk_bf16_f32 v64, v64, v67
	v_cvt_pk_bf16_f32 v65, v66, v65
	global_store_dwordx2 v[78:79], v[64:65], off offset:8
	s_and_saveexec_b64 s[52:53], s[54:55]
	s_xor_b64 s[52:53], exec, s[52:53]
	s_cbranch_execz .LBB0_941
	s_and_b64 s[36:37], vcc, exec
	s_andn2_saveexec_b64 s[52:53], s[52:53]
	s_cbranch_execnz .LBB0_942
